# E40: lever 4 variant: all per-phase s_setprio toggles deleted from the GEMM K-loops (G1, MLA-up, Wo, MLP-up, MLP-down), on top of E38
# speedup vs baseline: 1.0121x; 1.0070x over previous
; #define PG8_STAGE(bufoff, gbase, voff) do { _Pragma("unroll") for (int _i = 0; _i < 2; ++_i) \
;     __builtin_amdgcn_global_load_lds((const unsigned*)((const char*)(gbase) + (voff)[_i]), (LAS unsigned*)(lds + (bufoff) + ldsw + _i * 8192), 16, 0, 0); } while (0)
; #define PG8_LDA(dst, b, h) do { _Pragma("unroll") for (int m = 0; m < 4; ++m) _Pragma("unroll") for (int k = 0; k < 2; ++k) dst[m][k] = *(const LAS bf16x8*)(lds + PG8_SA(b, h) + aoff + m * 2048 + k * 1024); } while (0)
; #define PG8_LDB(dst, b, h) do { _Pragma("unroll") for (int n = 0; n < 2; ++n) _Pragma("unroll") for (int k = 0; k < 2; ++k) dst[n][k] = *(const LAS bf16x8*)(lds + PG8_SB(b, h) + boff + n * 2048 + k * 1024); } while (0)
; #define PG8_MMA(ai, bj, At, Bt) do { __builtin_amdgcn_s_setprio(1); _Pragma("unroll") for (int m = 0; m < 4; ++m) _Pragma("unroll") for (int n = 0; n < 2; ++n) _Pragma("unroll") for (int k = 0; k < 2; ++k) \
;     acc[ai][bj][m][n] = __builtin_amdgcn_mfma_f32_16x16x32_bf16(Bt[n][k], At[m][k], acc[ai][bj][m][n], 0, 0, 0); __builtin_amdgcn_s_setprio(0); } while (0)
; #define PG8_WAIT_L(n) asm volatile("s_waitcnt lgkmcnt(" #n ")" ::: "memory")
; #define PG8_BAR __builtin_amdgcn_s_barrier()
; #define PG8_SCHED __builtin_amdgcn_sched_barrier(0)
; template <class Epi, class Sched>
; __device__ __forceinline__ void gemm_phase(LAS unsigned char* lds, const Gemm g, const Sched& S, const Epi& E) {
;     ...
;       PG8_LDB(B0, 0, 0); PG8_SCHED; PG8_LDA(At, 0, 0); PG8_STAGE(PG8_SA(1, 1), a1 + hstepA, voffA);
;       PG8_WAIT_L(8); PG8_BAR; PG8_WAIT_L(0); PG8_MMA(0, 0, At, B0); PG8_BAR; PG8_SCHED;
;       PG8_LDB(B1, 0, 1); PG8_STAGE(PG8_SB(0, 0), b2, voffB);
;       PG8_BAR; PG8_WAIT_L(0); PG8_MMA(0, 1, At, B1); PG8_BAR;
;       PG8_LDA(At, 0, 1); PG8_STAGE(PG8_SA(0, 0), a2, voffA);
;       PG8_BAR; PG8_WAIT_L(0); PG8_MMA(1, 0, At, B0); PG8_BAR; PG8_SCHED;
.LBB0_621:
	s_add_u32 s4, s10, 0xfffc0080
	s_addc_u32 s5, s11, -1
	s_add_i32 s76, 16, 0x10000
	v_add_u32_e32 v136, s76, v160
	ds_read_b128 v[128:131], v136
	ds_read_b128 v[132:135], v136 offset:1024
	ds_read_b128 v[152:155], v136 offset:2048
	ds_read_b128 v[156:159], v136 offset:3072
	s_cmp_eq_u32 s84, 12
	s_cselect_b32 s79, s18, s5
	s_cselect_b32 s78, s19, s4
	s_cselect_b32 s13, s17, s23
	s_cselect_b32 s12, s20, s21
	v_lshl_add_u64 v[136:137], s[10:11], 0, v[148:149]
	s_add_i32 m0, s39, 0xc000
	ds_read_b128 v[166:169], v164
	ds_read_b128 v[170:173], v164 offset:1024
	ds_read_b128 v[174:177], v164 offset:2048
	ds_read_b128 v[178:181], v164 offset:3072
	ds_read_b128 v[182:185], v164 offset:4096
	ds_read_b128 v[198:201], v164 offset:5120
	ds_read_b128 v[214:217], v164 offset:6144
	ds_read_b128 v[218:221], v164 offset:7168
	global_load_lds_dwordx4 v[136:137], off
	v_lshl_add_u64 v[136:137], s[10:11], 0, v[150:151]
	s_add_i32 m0, s39, 0xe000
	s_nop 0
	global_load_lds_dwordx4 v[136:137], off
	s_waitcnt lgkmcnt(8)
	s_barrier
	s_waitcnt lgkmcnt(0)
	s_waitcnt lgkmcnt(0)
	v_mfma_f32_16x16x32_bf16 v[124:127], v[128:131], v[166:169], v[124:127]
	v_mfma_f32_16x16x32_bf16 v[120:123], v[152:155], v[166:169], v[120:123]
	v_mfma_f32_16x16x32_bf16 v[108:111], v[128:131], v[174:177], v[108:111]
	v_mfma_f32_16x16x32_bf16 v[104:107], v[152:155], v[174:177], v[104:107]
	v_mfma_f32_16x16x32_bf16 v[92:95], v[128:131], v[182:185], v[92:95]
	v_mfma_f32_16x16x32_bf16 v[88:91], v[152:155], v[182:185], v[88:91]
	v_mfma_f32_16x16x32_bf16 v[76:79], v[128:131], v[214:217], v[76:79]
	v_mfma_f32_16x16x32_bf16 v[72:75], v[152:155], v[214:217], v[72:75]
	v_mfma_f32_16x16x32_bf16 v[124:127], v[132:135], v[170:173], v[124:127]
	v_mfma_f32_16x16x32_bf16 v[120:123], v[156:159], v[170:173], v[120:123]
	v_mfma_f32_16x16x32_bf16 v[108:111], v[132:135], v[178:181], v[108:111]
	v_mfma_f32_16x16x32_bf16 v[104:107], v[156:159], v[178:181], v[104:107]
	v_mfma_f32_16x16x32_bf16 v[92:95], v[132:135], v[198:201], v[92:95]
	v_mfma_f32_16x16x32_bf16 v[88:91], v[156:159], v[198:201], v[88:91]
	v_mfma_f32_16x16x32_bf16 v[76:79], v[132:135], v[218:221], v[76:79]
	v_mfma_f32_16x16x32_bf16 v[72:75], v[156:159], v[218:221], v[72:75]
	s_barrier
	s_add_i32 s77, 16, 0x14000
	v_add_u32_e32 v136, s77, v160
	s_add_i32 s4, s76, s58
	ds_read_b128 v[222:225], v136
	ds_read_b128 v[226:229], v136 offset:1024
	ds_read_b128 v[230:233], v136 offset:2048
	ds_read_b128 v[234:237], v136 offset:3072
	v_lshl_add_u64 v[136:137], s[12:13], 0, v[138:139]
	s_mov_b32 m0, s4
	v_lshl_add_u64 v[238:239], s[12:13], 0, v[140:141]
	global_load_lds_dwordx4 v[136:137], off
	s_add_i32 m0, s4, 0x2000
	s_nop 0
	global_load_lds_dwordx4 v[238:239], off
	s_barrier
	s_waitcnt lgkmcnt(0)
	s_waitcnt lgkmcnt(0)
	v_mfma_f32_16x16x32_bf16 v[116:119], v[222:225], v[166:169], v[116:119]
	v_mfma_f32_16x16x32_bf16 v[112:115], v[230:233], v[166:169], v[112:115]
	v_mfma_f32_16x16x32_bf16 v[100:103], v[222:225], v[174:177], v[100:103]
	v_mfma_f32_16x16x32_bf16 v[96:99], v[230:233], v[174:177], v[96:99]
	v_mfma_f32_16x16x32_bf16 v[84:87], v[222:225], v[182:185], v[84:87]
	v_mfma_f32_16x16x32_bf16 v[80:83], v[230:233], v[182:185], v[80:83]
	v_mfma_f32_16x16x32_bf16 v[68:71], v[222:225], v[214:217], v[68:71]
	v_mfma_f32_16x16x32_bf16 v[64:67], v[230:233], v[214:217], v[64:67]
	v_mfma_f32_16x16x32_bf16 v[116:119], v[226:229], v[170:173], v[116:119]
	v_mfma_f32_16x16x32_bf16 v[112:115], v[234:237], v[170:173], v[112:115]
	v_mfma_f32_16x16x32_bf16 v[100:103], v[226:229], v[178:181], v[100:103]
	v_mfma_f32_16x16x32_bf16 v[96:99], v[234:237], v[178:181], v[96:99]
	v_mfma_f32_16x16x32_bf16 v[84:87], v[226:229], v[198:201], v[84:87]
	v_mfma_f32_16x16x32_bf16 v[80:83], v[234:237], v[198:201], v[80:83]
	v_mfma_f32_16x16x32_bf16 v[68:71], v[226:229], v[218:221], v[68:71]
	v_mfma_f32_16x16x32_bf16 v[64:67], v[234:237], v[218:221], v[64:67]
	s_mov_b32 m0, s39
	v_lshl_add_u64 v[240:241], s[78:79], 0, v[138:139]
	s_barrier
	ds_read_b128 v[166:169], v164 offset:16384
	ds_read_b128 v[170:173], v164 offset:17408
	ds_read_b128 v[174:177], v164 offset:18432
	ds_read_b128 v[178:181], v164 offset:19456
	ds_read_b128 v[182:185], v164 offset:20480
	ds_read_b128 v[198:201], v164 offset:21504
	ds_read_b128 v[214:217], v164 offset:22528
	ds_read_b128 v[218:221], v164 offset:23552
	global_load_lds_dwordx4 v[240:241], off
	v_lshl_add_u64 v[242:243], s[78:79], 0, v[140:141]
	s_mov_b32 m0, s59
	s_nop 0
	global_load_lds_dwordx4 v[242:243], off
	s_barrier
	s_waitcnt lgkmcnt(0)
	s_waitcnt lgkmcnt(0)
	v_mfma_f32_16x16x32_bf16 v[60:63], v[128:131], v[166:169], v[60:63]
	v_mfma_f32_16x16x32_bf16 v[56:59], v[152:155], v[166:169], v[56:59]
	v_mfma_f32_16x16x32_bf16 v[44:47], v[128:131], v[174:177], v[44:47]
	v_mfma_f32_16x16x32_bf16 v[40:43], v[152:155], v[174:177], v[40:43]
	v_mfma_f32_16x16x32_bf16 v[28:31], v[128:131], v[182:185], v[28:31]
	v_mfma_f32_16x16x32_bf16 v[24:27], v[152:155], v[182:185], v[24:27]
	v_mfma_f32_16x16x32_bf16 v[12:15], v[128:131], v[214:217], v[12:15]
	v_mfma_f32_16x16x32_bf16 v[8:11], v[152:155], v[214:217], v[8:11]
	v_mfma_f32_16x16x32_bf16 v[60:63], v[132:135], v[170:173], v[60:63]
	v_mfma_f32_16x16x32_bf16 v[56:59], v[156:159], v[170:173], v[56:59]
	v_mfma_f32_16x16x32_bf16 v[44:47], v[132:135], v[178:181], v[44:47]
	v_mfma_f32_16x16x32_bf16 v[40:43], v[156:159], v[178:181], v[40:43]
	v_mfma_f32_16x16x32_bf16 v[28:31], v[132:135], v[198:201], v[28:31]
	v_mfma_f32_16x16x32_bf16 v[24:27], v[156:159], v[198:201], v[24:27]
	v_mfma_f32_16x16x32_bf16 v[12:15], v[132:135], v[218:221], v[12:15]
	v_mfma_f32_16x16x32_bf16 v[8:11], v[156:159], v[218:221], v[8:11]
	s_barrier
; #define PG8_STAGE(bufoff, gbase, voff) do { _Pragma("unroll") for (int _i = 0; _i < 2; ++_i) \
;     __builtin_amdgcn_global_load_lds((const unsigned*)((const char*)(gbase) + (voff)[_i]), (LAS unsigned*)(lds + (bufoff) + ldsw + _i * 8192), 16, 0, 0); } while (0)
; #define PG8_LDA(dst, b, h) do { _Pragma("unroll") for (int m = 0; m < 4; ++m) _Pragma("unroll") for (int k = 0; k < 2; ++k) dst[m][k] = *(const LAS bf16x8*)(lds + PG8_SA(b, h) + aoff + m * 2048 + k * 1024); } while (0)
; #define PG8_LDB(dst, b, h) do { _Pragma("unroll") for (int n = 0; n < 2; ++n) _Pragma("unroll") for (int k = 0; k < 2; ++k) dst[n][k] = *(const LAS bf16x8*)(lds + PG8_SB(b, h) + boff + n * 2048 + k * 1024); } while (0)
; #define PG8_MMA(ai, bj, At, Bt) do { __builtin_amdgcn_s_setprio(1); _Pragma("unroll") for (int m = 0; m < 4; ++m) _Pragma("unroll") for (int n = 0; n < 2; ++n) _Pragma("unroll") for (int k = 0; k < 2; ++k) \
;     acc[ai][bj][m][n] = __builtin_amdgcn_mfma_f32_16x16x32_bf16(Bt[n][k], At[m][k], acc[ai][bj][m][n], 0, 0, 0); __builtin_amdgcn_s_setprio(0); } while (0)
; #define PG8_WAIT_V(n) asm volatile("s_waitcnt vmcnt(" #n ")" ::: "memory")
; #define PG8_WAIT_L(n) asm volatile("s_waitcnt lgkmcnt(" #n ")" ::: "memory")
; #define PG8_BAR __builtin_amdgcn_s_barrier()
; #define PG8_SCHED __builtin_amdgcn_sched_barrier(0)
; template <class Epi, class Sched>
; __device__ __forceinline__ void gemm_phase(LAS unsigned char* lds, const Gemm g, const Sched& S, const Epi& E) {
;     ...
;       PG8_STAGE(PG8_SB(0, 1), b2 + hstepB, voffB);
;       PG8_WAIT_V(6); PG8_BAR; PG8_MMA(1, 1, At, B1); PG8_BAR;
;       PG8_LDB(B0, 1, 0); PG8_SCHED; PG8_LDA(At, 1, 0); PG8_STAGE(PG8_SA(0, 1), a2 + hstepA, voffA);
;       PG8_WAIT_L(8); PG8_BAR; PG8_WAIT_L(0); PG8_MMA(0, 0, At, B0); PG8_BAR; PG8_SCHED;
;       PG8_LDB(B1, 1, 1); PG8_STAGE(PG8_SB(1, 0), b3, voffB);
;       PG8_BAR; PG8_WAIT_L(0); PG8_MMA(0, 1, At, B1); PG8_BAR;
;       PG8_LDA(At, 1, 1); PG8_STAGE(PG8_SA(1, 0), a3, voffA);
;       PG8_BAR; PG8_WAIT_L(0); PG8_MMA(1, 0, At, B0); PG8_BAR; PG8_SCHED;
	s_add_u32 s4, s12, 0x40000
	s_addc_u32 s5, s13, 0
	s_add_i32 s76, s77, s58
	v_lshl_add_u64 v[128:129], s[4:5], 0, v[138:139]
	s_mov_b32 m0, s76
	s_nop 0
	global_load_lds_dwordx4 v[128:129], off
	v_lshl_add_u64 v[128:129], s[4:5], 0, v[140:141]
	s_add_i32 m0, s76, 0x2000
	s_nop 0
	global_load_lds_dwordx4 v[128:129], off
	s_waitcnt vmcnt(6)
	s_barrier
	v_mfma_f32_16x16x32_bf16 v[52:55], v[222:225], v[166:169], v[52:55]
	v_mfma_f32_16x16x32_bf16 v[48:51], v[230:233], v[166:169], v[48:51]
	v_mfma_f32_16x16x32_bf16 v[36:39], v[222:225], v[174:177], v[36:39]
	v_mfma_f32_16x16x32_bf16 v[32:35], v[230:233], v[174:177], v[32:35]
	v_mfma_f32_16x16x32_bf16 v[20:23], v[222:225], v[182:185], v[20:23]
	v_mfma_f32_16x16x32_bf16 v[16:19], v[230:233], v[182:185], v[16:19]
	v_mfma_f32_16x16x32_bf16 v[4:7], v[222:225], v[214:217], v[4:7]
	v_mfma_f32_16x16x32_bf16 v[0:3], v[230:233], v[214:217], v[0:3]
	v_mfma_f32_16x16x32_bf16 v[52:55], v[226:229], v[170:173], v[52:55]
	v_mfma_f32_16x16x32_bf16 v[48:51], v[234:237], v[170:173], v[48:51]
	v_mfma_f32_16x16x32_bf16 v[36:39], v[226:229], v[178:181], v[36:39]
	v_mfma_f32_16x16x32_bf16 v[32:35], v[234:237], v[178:181], v[32:35]
	v_mfma_f32_16x16x32_bf16 v[20:23], v[226:229], v[198:201], v[20:23]
	v_mfma_f32_16x16x32_bf16 v[16:19], v[234:237], v[198:201], v[16:19]
	v_mfma_f32_16x16x32_bf16 v[4:7], v[226:229], v[218:221], v[4:7]
	v_mfma_f32_16x16x32_bf16 v[0:3], v[234:237], v[218:221], v[0:3]
	s_add_i32 s76, 16, 0x18000
	v_add_u32_e32 v156, s76, v160
	s_barrier
	ds_read_b128 v[128:131], v156
	ds_read_b128 v[132:135], v156 offset:1024
	ds_read_b128 v[152:155], v156 offset:2048
	ds_read_b128 v[156:159], v156 offset:3072
	s_add_u32 s4, s78, 0x40000
	s_addc_u32 s5, s79, 0
	s_mov_b32 m0, s67
	v_lshl_add_u64 v[222:223], s[4:5], 0, v[138:139]
	ds_read_b128 v[166:169], v164 offset:32768
	ds_read_b128 v[170:173], v164 offset:33792
	ds_read_b128 v[174:177], v164 offset:34816
	ds_read_b128 v[178:181], v164 offset:35840
	ds_read_b128 v[182:185], v164 offset:36864
	ds_read_b128 v[198:201], v164 offset:37888
	ds_read_b128 v[214:217], v164 offset:38912
	ds_read_b128 v[218:221], v164 offset:39936
	global_load_lds_dwordx4 v[222:223], off
	v_lshl_add_u64 v[222:223], s[4:5], 0, v[140:141]
	s_mov_b32 m0, s68
	s_nop 0
	global_load_lds_dwordx4 v[222:223], off
	s_waitcnt lgkmcnt(8)
	s_barrier
	s_waitcnt lgkmcnt(0)
	s_waitcnt lgkmcnt(0)
	v_mfma_f32_16x16x32_bf16 v[124:127], v[128:131], v[166:169], v[124:127]
	v_mfma_f32_16x16x32_bf16 v[120:123], v[152:155], v[166:169], v[120:123]
	v_mfma_f32_16x16x32_bf16 v[108:111], v[128:131], v[174:177], v[108:111]
	v_mfma_f32_16x16x32_bf16 v[104:107], v[152:155], v[174:177], v[104:107]
	v_mfma_f32_16x16x32_bf16 v[92:95], v[128:131], v[182:185], v[92:95]
	v_mfma_f32_16x16x32_bf16 v[88:91], v[152:155], v[182:185], v[88:91]
	v_mfma_f32_16x16x32_bf16 v[76:79], v[128:131], v[214:217], v[76:79]
	v_mfma_f32_16x16x32_bf16 v[72:75], v[152:155], v[214:217], v[72:75]
	v_mfma_f32_16x16x32_bf16 v[124:127], v[132:135], v[170:173], v[124:127]
	v_mfma_f32_16x16x32_bf16 v[120:123], v[156:159], v[170:173], v[120:123]
	v_mfma_f32_16x16x32_bf16 v[108:111], v[132:135], v[178:181], v[108:111]
	v_mfma_f32_16x16x32_bf16 v[104:107], v[156:159], v[178:181], v[104:107]
	v_mfma_f32_16x16x32_bf16 v[92:95], v[132:135], v[198:201], v[92:95]
	v_mfma_f32_16x16x32_bf16 v[88:91], v[156:159], v[198:201], v[88:91]
	v_mfma_f32_16x16x32_bf16 v[76:79], v[132:135], v[218:221], v[76:79]
	v_mfma_f32_16x16x32_bf16 v[72:75], v[156:159], v[218:221], v[72:75]
	s_barrier
	s_add_i32 s77, 16, 0x1c000
	s_add_i32 s4, s76, s58
	v_add_u32_e32 v165, s77, v160
	v_lshl_add_u64 v[136:137], v[136:137], 0, s[62:63]
	s_mov_b32 m0, s4
	ds_read_b128 v[222:225], v165
	ds_read_b128 v[226:229], v165 offset:1024
	ds_read_b128 v[230:233], v165 offset:2048
	ds_read_b128 v[234:237], v165 offset:3072
	global_load_lds_dwordx4 v[136:137], off
	v_lshl_add_u64 v[136:137], v[238:239], 0, s[62:63]
	s_add_i32 m0, s4, 0x2000
	s_nop 0
	global_load_lds_dwordx4 v[136:137], off
	s_barrier
	s_waitcnt lgkmcnt(0)
	s_waitcnt lgkmcnt(0)
	v_mfma_f32_16x16x32_bf16 v[116:119], v[222:225], v[166:169], v[116:119]
	v_mfma_f32_16x16x32_bf16 v[112:115], v[230:233], v[166:169], v[112:115]
	v_mfma_f32_16x16x32_bf16 v[100:103], v[222:225], v[174:177], v[100:103]
	v_mfma_f32_16x16x32_bf16 v[96:99], v[230:233], v[174:177], v[96:99]
	v_mfma_f32_16x16x32_bf16 v[84:87], v[222:225], v[182:185], v[84:87]
	v_mfma_f32_16x16x32_bf16 v[80:83], v[230:233], v[182:185], v[80:83]
	v_mfma_f32_16x16x32_bf16 v[68:71], v[222:225], v[214:217], v[68:71]
	v_mfma_f32_16x16x32_bf16 v[64:67], v[230:233], v[214:217], v[64:67]
	v_mfma_f32_16x16x32_bf16 v[116:119], v[226:229], v[170:173], v[116:119]
	v_mfma_f32_16x16x32_bf16 v[112:115], v[234:237], v[170:173], v[112:115]
	v_mfma_f32_16x16x32_bf16 v[100:103], v[226:229], v[178:181], v[100:103]
	v_mfma_f32_16x16x32_bf16 v[96:99], v[234:237], v[178:181], v[96:99]
	v_mfma_f32_16x16x32_bf16 v[84:87], v[226:229], v[198:201], v[84:87]
	v_mfma_f32_16x16x32_bf16 v[80:83], v[234:237], v[198:201], v[80:83]
	v_mfma_f32_16x16x32_bf16 v[68:71], v[226:229], v[218:221], v[68:71]
	v_mfma_f32_16x16x32_bf16 v[64:67], v[234:237], v[218:221], v[64:67]
	s_mov_b32 m0, s74
	v_lshl_add_u64 v[136:137], v[240:241], 0, s[62:63]
	s_barrier
; __device__ __forceinline__ float siluf_(float v) { return v * sigmoidf_(v); }
; __device__ __forceinline__ void store_bf16x4(bf16_t* p, f32x4 v) { u32x2 w; w.x = cvt_pk_bf16(v[0], v[1]); w.y = cvt_pk_bf16(v[2], v[3]); *(u32x2*)p = w; }
; #define PG8_STAGE(bufoff, gbase, voff) do { _Pragma("unroll") for (int _i = 0; _i < 2; ++_i) \
;     __builtin_amdgcn_global_load_lds((const unsigned*)((const char*)(gbase) + (voff)[_i]), (LAS unsigned*)(lds + (bufoff) + ldsw + _i * 8192), 16, 0, 0); } while (0)
; #define PG8_MMA(ai, bj, At, Bt) do { __builtin_amdgcn_s_setprio(1); _Pragma("unroll") for (int m = 0; m < 4; ++m) _Pragma("unroll") for (int n = 0; n < 2; ++n) _Pragma("unroll") for (int k = 0; k < 2; ++k) \
;     acc[ai][bj][m][n] = __builtin_amdgcn_mfma_f32_16x16x32_bf16(Bt[n][k], At[m][k], acc[ai][bj][m][n], 0, 0, 0); __builtin_amdgcn_s_setprio(0); } while (0)
; #define PG8_WAIT_V(n) asm volatile("s_waitcnt vmcnt(" #n ")" ::: "memory")
; #define PG8_WAIT_L(n) asm volatile("s_waitcnt lgkmcnt(" #n ")" ::: "memory")
; #define PG8_BAR __builtin_amdgcn_s_barrier()
; #define PG8_SCHED __builtin_amdgcn_sched_barrier(0)
; template <class Epi, class Sched>
; __device__ __forceinline__ void gemm_phase(LAS unsigned char* lds, const Gemm g, const Sched& S, const Epi& E) {
;     ...
;       PG8_BAR; PG8_WAIT_L(0); PG8_MMA(1, 0, At, B0); PG8_BAR; PG8_SCHED;
;       PG8_STAGE(PG8_SB(1, 1), b3 + hstepB, voffB);
;       PG8_WAIT_V(6); PG8_BAR; PG8_MMA(1, 1, At, B1); PG8_BAR;
;     }
;     E(acc, cur, wr, wc, fr, fq);
;   __device__ __forceinline__ void operator()(const f32x4 (&acc)[2][2][4][2], const pg8::Unit& u, int wr, int wc, int fr, int fq) const {
;     ...
;     EPI_LOOP(
;       if (pn < 4) { store_bf16x4(DQK + (size_t)row * 1024 + col, v); }
;       else if (pn < 6) { store_bf16x4(DV + (size_t)row * 512 + (col - 1024), v); }
;       else if (pn < 10) { store_bf16x4(RV + (size_t)row * 512 + (col - 2048), v); }
;       else { f32x4 o; for (int j = 0; j < 4; ++j) o[j] = siluf_(v[j]); store_bf16x4(RG + (size_t)row * 512 + (col - 2560), o); }
	ds_read_b128 v[166:169], v164 offset:49152
	ds_read_b128 v[170:173], v164 offset:50176
	ds_read_b128 v[174:177], v164 offset:51200
	ds_read_b128 v[178:181], v164 offset:52224
	ds_read_b128 v[182:185], v164 offset:53248
	ds_read_b128 v[198:201], v164 offset:54272
	ds_read_b128 v[214:217], v164 offset:55296
	ds_read_b128 v[218:221], v164 offset:56320
	global_load_lds_dwordx4 v[136:137], off
	v_lshl_add_u64 v[136:137], v[242:243], 0, s[62:63]
	s_mov_b32 m0, s75
	s_nop 0
	global_load_lds_dwordx4 v[136:137], off
	s_barrier
	s_waitcnt lgkmcnt(0)
	s_waitcnt lgkmcnt(0)
	v_mfma_f32_16x16x32_bf16 v[60:63], v[128:131], v[166:169], v[60:63]
	v_mfma_f32_16x16x32_bf16 v[56:59], v[152:155], v[166:169], v[56:59]
	v_mfma_f32_16x16x32_bf16 v[44:47], v[128:131], v[174:177], v[44:47]
	v_mfma_f32_16x16x32_bf16 v[40:43], v[152:155], v[174:177], v[40:43]
	v_mfma_f32_16x16x32_bf16 v[28:31], v[128:131], v[182:185], v[28:31]
	v_mfma_f32_16x16x32_bf16 v[24:27], v[152:155], v[182:185], v[24:27]
	v_mfma_f32_16x16x32_bf16 v[12:15], v[128:131], v[214:217], v[12:15]
	v_mfma_f32_16x16x32_bf16 v[8:11], v[152:155], v[214:217], v[8:11]
	v_mfma_f32_16x16x32_bf16 v[60:63], v[132:135], v[170:173], v[60:63]
	v_mfma_f32_16x16x32_bf16 v[56:59], v[156:159], v[170:173], v[56:59]
	v_mfma_f32_16x16x32_bf16 v[44:47], v[132:135], v[178:181], v[44:47]
	v_mfma_f32_16x16x32_bf16 v[40:43], v[156:159], v[178:181], v[40:43]
	v_mfma_f32_16x16x32_bf16 v[28:31], v[132:135], v[198:201], v[28:31]
	v_mfma_f32_16x16x32_bf16 v[24:27], v[156:159], v[198:201], v[24:27]
	v_mfma_f32_16x16x32_bf16 v[12:15], v[132:135], v[218:221], v[12:15]
	v_mfma_f32_16x16x32_bf16 v[8:11], v[156:159], v[218:221], v[8:11]
	s_barrier
	s_add_u32 s4, s12, 0x40080
	s_addc_u32 s5, s13, 0
	s_add_i32 s12, s77, s58
	v_lshl_add_u64 v[128:129], s[4:5], 0, v[138:139]
	s_mov_b32 m0, s12
	s_nop 0
	global_load_lds_dwordx4 v[128:129], off
	v_lshl_add_u64 v[128:129], s[4:5], 0, v[140:141]
	s_add_i32 m0, s12, 0x2000
	s_nop 0
	global_load_lds_dwordx4 v[128:129], off
	s_waitcnt vmcnt(6)
	s_barrier
	v_mfma_f32_16x16x32_bf16 v[52:55], v[222:225], v[166:169], v[52:55]
	v_mfma_f32_16x16x32_bf16 v[48:51], v[230:233], v[166:169], v[48:51]
	v_mfma_f32_16x16x32_bf16 v[36:39], v[222:225], v[174:177], v[36:39]
	v_mfma_f32_16x16x32_bf16 v[32:35], v[230:233], v[174:177], v[32:35]
	v_mfma_f32_16x16x32_bf16 v[20:23], v[222:225], v[182:185], v[20:23]
	v_mfma_f32_16x16x32_bf16 v[16:19], v[230:233], v[182:185], v[16:19]
	v_mfma_f32_16x16x32_bf16 v[4:7], v[222:225], v[214:217], v[4:7]
	v_mfma_f32_16x16x32_bf16 v[0:3], v[230:233], v[214:217], v[0:3]
	v_mfma_f32_16x16x32_bf16 v[52:55], v[226:229], v[170:173], v[52:55]
	v_mfma_f32_16x16x32_bf16 v[48:51], v[234:237], v[170:173], v[48:51]
	v_mfma_f32_16x16x32_bf16 v[36:39], v[226:229], v[178:181], v[36:39]
	v_mfma_f32_16x16x32_bf16 v[32:35], v[234:237], v[178:181], v[32:35]
	v_mfma_f32_16x16x32_bf16 v[20:23], v[226:229], v[198:201], v[20:23]
	v_mfma_f32_16x16x32_bf16 v[16:19], v[234:237], v[198:201], v[16:19]
	v_mfma_f32_16x16x32_bf16 v[4:7], v[226:229], v[218:221], v[4:7]
	v_mfma_f32_16x16x32_bf16 v[0:3], v[234:237], v[218:221], v[0:3]
	s_add_i32 s84, s84, 2
	s_add_u32 s10, s10, 0x100
	s_addc_u32 s11, s11, 0
	s_add_u32 s21, s21, 0x100
	s_addc_u32 s23, s23, 0
	s_cmp_gt_u32 s84, 13
	s_barrier
	s_cbranch_scc0 .LBB0_621
	s_and_b32 s4, s38, -2
	s_cmp_lg_u32 s4, 6
	s_mov_b64 s[10:11], -1
	s_cbranch_scc0 .LBB0_1008
	s_cmp_gt_i32 s38, 3
	v_lshl_add_u32 v130, s66, 8, v145
	s_cselect_b64 s[10:11], -1, 0
	s_cmp_gt_u32 s38, 5
	s_cselect_b64 s[84:85], -1, 0
	s_cmp_gt_u32 s38, 9
	v_ashrrev_i32_e32 v131, 31, v130
	v_lshl_or_b32 v128, s38, 8, v142
	v_and_b32_e32 v252, 16, v187
	v_lshrrev_b32_e32 v253, 1, v252
	v_add_u32_e32 v252, v252, v253
	v_mov_b32_e32 v253, v144
	s_cselect_b64 s[78:79], -1, 0
	v_lshlrev_b64 v[132:133], 10, v[130:131]
	s_mov_b64 s[12:13], -1
	s_and_b64 vcc, exec, s[10:11]
	s_cbranch_vccz .LBB0_633
	s_and_b64 vcc, exec, s[84:85]
	s_cbranch_vccz .LBB0_630
	s_andn2_b64 vcc, exec, s[78:79]
	s_cbranch_vccnz .LBB0_627
	v_mul_f32_e32 v129, 0xbfb8aa3b, v124
	v_mul_f32_e32 v134, 0xbfb8aa3b, v125
	v_mul_f32_e32 v135, 0xbfb8aa3b, v126
	v_exp_f32_e32 v129, v129
	v_exp_f32_e32 v134, v134
	v_exp_f32_e32 v135, v135
	v_mul_f32_e32 v136, 0xbfb8aa3b, v127
	v_add_f32_e32 v129, 1.0, v129
	v_add_f32_e32 v134, 1.0, v134
	v_exp_f32_e32 v136, v136
	v_add_f32_e32 v135, 1.0, v135
	v_rcp_f32_e32 v129, v129
	v_rcp_f32_e32 v134, v134
	v_rcp_f32_e32 v135, v135
	v_add_f32_e32 v136, 1.0, v136
	v_rcp_f32_e32 v136, v136
	v_mul_f32_e32 v137, v124, v129
	v_mul_f32_e32 v152, v125, v134
	v_mul_f32_e32 v153, v126, v135
	v_lshl_add_u64 v[134:135], s[46:47], 0, v[132:133]
	v_mov_b32_e32 v129, v144
	v_lshl_add_u64 v[134:135], v[128:129], 1, v[134:135]
	v_add_co_u32_e32 v134, vcc, 0xfffff000, v134
	s_mov_b64 s[12:13], 0
	s_nop 0
	v_addc_co_u32_e32 v135, vcc, -1, v135, vcc
	v_mul_f32_e32 v154, v127, v136
	v_cvt_pk_bf16_f32 v244, v137, v152
	v_cvt_pk_bf16_f32 v245, v153, v154

; #define PG8_STAGE(bufoff, gbase, voff) do { _Pragma("unroll") for (int _i = 0; _i < 2; ++_i) \
;     __builtin_amdgcn_global_load_lds((const unsigned*)((const char*)(gbase) + (voff)[_i]), (LAS unsigned*)(lds + (bufoff) + ldsw + _i * 8192), 16, 0, 0); } while (0)
; #define PG8_LDA(dst, b, h) do { _Pragma("unroll") for (int m = 0; m < 4; ++m) _Pragma("unroll") for (int k = 0; k < 2; ++k) dst[m][k] = *(const LAS bf16x8*)(lds + PG8_SA(b, h) + aoff + m * 2048 + k * 1024); } while (0)
; #define PG8_LDB(dst, b, h) do { _Pragma("unroll") for (int n = 0; n < 2; ++n) _Pragma("unroll") for (int k = 0; k < 2; ++k) dst[n][k] = *(const LAS bf16x8*)(lds + PG8_SB(b, h) + boff + n * 2048 + k * 1024); } while (0)
; #define PG8_MMA(ai, bj, At, Bt) do { __builtin_amdgcn_s_setprio(1); _Pragma("unroll") for (int m = 0; m < 4; ++m) _Pragma("unroll") for (int n = 0; n < 2; ++n) _Pragma("unroll") for (int k = 0; k < 2; ++k) \
;     acc[ai][bj][m][n] = __builtin_amdgcn_mfma_f32_16x16x32_bf16(Bt[n][k], At[m][k], acc[ai][bj][m][n], 0, 0, 0); __builtin_amdgcn_s_setprio(0); } while (0)
; #define PG8_WAIT_L(n) asm volatile("s_waitcnt lgkmcnt(" #n ")" ::: "memory")
; #define PG8_BAR __builtin_amdgcn_s_barrier()
; #define PG8_SCHED __builtin_amdgcn_sched_barrier(0)
; template <class Epi, class Sched>
; __device__ __forceinline__ void gemm_phase(LAS unsigned char* lds, const Gemm g, const Sched& S, const Epi& E) {
;     ...
;       PG8_LDB(B0, 0, 0); PG8_SCHED; PG8_LDA(At, 0, 0); PG8_STAGE(PG8_SA(1, 1), a1 + hstepA, voffA);
;       PG8_WAIT_L(8); PG8_BAR; PG8_WAIT_L(0); PG8_MMA(0, 0, At, B0); PG8_BAR; PG8_SCHED;
;       PG8_LDB(B1, 0, 1); PG8_STAGE(PG8_SB(0, 0), b2, voffB);
;       PG8_BAR; PG8_WAIT_L(0); PG8_MMA(0, 1, At, B1); PG8_BAR;
;       PG8_LDA(At, 0, 1); PG8_STAGE(PG8_SA(0, 0), a2, voffA);
;       PG8_BAR; PG8_WAIT_L(0); PG8_MMA(1, 0, At, B0); PG8_BAR; PG8_SCHED;
.LBB0_1541:
	s_add_u32 s36, s78, 0xfffc0080
	s_addc_u32 s37, s79, -1
	s_add_i32 s76, 16, 0x10000
	v_add_u32_e32 v153, s76, v150
	ds_read_b128 v[136:139], v153
	ds_read_b128 v[140:143], v153 offset:1024
	ds_read_b128 v[146:149], v153 offset:2048
	ds_read_b128 v[154:157], v153 offset:3072
	s_cmp_eq_u32 s84, 12
	s_cselect_b32 s83, s9, s37
	s_cselect_b32 s82, s11, s36
	s_cselect_b32 s39, s23, s27
	s_cselect_b32 s38, s24, s25
	v_lshl_add_u64 v[214:215], s[78:79], 0, v[132:133]
	s_add_i32 m0, s69, 0xc000
	ds_read_b128 v[158:161], v152
	ds_read_b128 v[162:165], v152 offset:1024
	ds_read_b128 v[166:169], v152 offset:2048
	ds_read_b128 v[170:173], v152 offset:3072
	ds_read_b128 v[174:177], v152 offset:4096
	ds_read_b128 v[178:181], v152 offset:5120
	ds_read_b128 v[182:185], v152 offset:6144
	ds_read_b128 v[198:201], v152 offset:7168
	global_load_lds_dwordx4 v[214:215], off
	v_lshl_add_u64 v[214:215], s[78:79], 0, v[134:135]
	s_add_i32 m0, s69, 0xe000
	s_nop 0
	global_load_lds_dwordx4 v[214:215], off
	s_waitcnt lgkmcnt(8)
	s_barrier
	s_waitcnt lgkmcnt(0)
	s_waitcnt lgkmcnt(0)
	v_mfma_f32_16x16x32_bf16 v[124:127], v[136:139], v[158:161], v[124:127]
	v_mfma_f32_16x16x32_bf16 v[120:123], v[146:149], v[158:161], v[120:123]
	v_mfma_f32_16x16x32_bf16 v[108:111], v[136:139], v[166:169], v[108:111]
	v_mfma_f32_16x16x32_bf16 v[104:107], v[146:149], v[166:169], v[104:107]
	v_mfma_f32_16x16x32_bf16 v[92:95], v[136:139], v[174:177], v[92:95]
	v_mfma_f32_16x16x32_bf16 v[88:91], v[146:149], v[174:177], v[88:91]
	v_mfma_f32_16x16x32_bf16 v[76:79], v[136:139], v[182:185], v[76:79]
	v_mfma_f32_16x16x32_bf16 v[72:75], v[146:149], v[182:185], v[72:75]
	v_mfma_f32_16x16x32_bf16 v[124:127], v[140:143], v[162:165], v[124:127]
	v_mfma_f32_16x16x32_bf16 v[120:123], v[154:157], v[162:165], v[120:123]
	v_mfma_f32_16x16x32_bf16 v[108:111], v[140:143], v[170:173], v[108:111]
	v_mfma_f32_16x16x32_bf16 v[104:107], v[154:157], v[170:173], v[104:107]
	v_mfma_f32_16x16x32_bf16 v[92:95], v[140:143], v[178:181], v[92:95]
	v_mfma_f32_16x16x32_bf16 v[88:91], v[154:157], v[178:181], v[88:91]
	v_mfma_f32_16x16x32_bf16 v[76:79], v[140:143], v[198:201], v[76:79]
	v_mfma_f32_16x16x32_bf16 v[72:75], v[154:157], v[198:201], v[72:75]
	s_barrier
	s_add_i32 s77, 16, 0x14000
	s_add_i32 s36, s76, s68
	v_add_u32_e32 v153, s77, v150
	v_lshl_add_u64 v[230:231], s[38:39], 0, v[128:129]
	s_mov_b32 m0, s36
	ds_read_b128 v[214:217], v153
	ds_read_b128 v[218:221], v153 offset:1024
	ds_read_b128 v[222:225], v153 offset:2048
	ds_read_b128 v[226:229], v153 offset:3072
	global_load_lds_dwordx4 v[230:231], off
	v_lshl_add_u64 v[232:233], s[38:39], 0, v[130:131]
	s_add_i32 m0, s36, 0x2000
	s_nop 0
	global_load_lds_dwordx4 v[232:233], off
	s_barrier
	s_waitcnt lgkmcnt(0)
	s_waitcnt lgkmcnt(0)
	v_mfma_f32_16x16x32_bf16 v[116:119], v[214:217], v[158:161], v[116:119]
	v_mfma_f32_16x16x32_bf16 v[112:115], v[222:225], v[158:161], v[112:115]
	v_mfma_f32_16x16x32_bf16 v[100:103], v[214:217], v[166:169], v[100:103]
	v_mfma_f32_16x16x32_bf16 v[96:99], v[222:225], v[166:169], v[96:99]
	v_mfma_f32_16x16x32_bf16 v[84:87], v[214:217], v[174:177], v[84:87]
	v_mfma_f32_16x16x32_bf16 v[80:83], v[222:225], v[174:177], v[80:83]
	v_mfma_f32_16x16x32_bf16 v[68:71], v[214:217], v[182:185], v[68:71]
	v_mfma_f32_16x16x32_bf16 v[64:67], v[222:225], v[182:185], v[64:67]
	v_mfma_f32_16x16x32_bf16 v[116:119], v[218:221], v[162:165], v[116:119]
	v_mfma_f32_16x16x32_bf16 v[112:115], v[226:229], v[162:165], v[112:115]
	v_mfma_f32_16x16x32_bf16 v[100:103], v[218:221], v[170:173], v[100:103]
	v_mfma_f32_16x16x32_bf16 v[96:99], v[226:229], v[170:173], v[96:99]
	v_mfma_f32_16x16x32_bf16 v[84:87], v[218:221], v[178:181], v[84:87]
	v_mfma_f32_16x16x32_bf16 v[80:83], v[226:229], v[178:181], v[80:83]
	v_mfma_f32_16x16x32_bf16 v[68:71], v[218:221], v[198:201], v[68:71]
	v_mfma_f32_16x16x32_bf16 v[64:67], v[226:229], v[198:201], v[64:67]
	s_mov_b32 m0, s69
	v_lshl_add_u64 v[234:235], s[82:83], 0, v[128:129]
	s_barrier
	ds_read_b128 v[158:161], v152 offset:16384
	ds_read_b128 v[162:165], v152 offset:17408
	ds_read_b128 v[166:169], v152 offset:18432
	ds_read_b128 v[170:173], v152 offset:19456
	ds_read_b128 v[174:177], v152 offset:20480
	ds_read_b128 v[178:181], v152 offset:21504
	ds_read_b128 v[182:185], v152 offset:22528
	ds_read_b128 v[198:201], v152 offset:23552
	global_load_lds_dwordx4 v[234:235], off
	v_lshl_add_u64 v[236:237], s[82:83], 0, v[130:131]
	s_mov_b32 m0, s74
	s_nop 0
	global_load_lds_dwordx4 v[236:237], off
	s_barrier
	s_waitcnt lgkmcnt(0)
	s_waitcnt lgkmcnt(0)
	v_mfma_f32_16x16x32_bf16 v[60:63], v[136:139], v[158:161], v[60:63]
	v_mfma_f32_16x16x32_bf16 v[56:59], v[146:149], v[158:161], v[56:59]
	v_mfma_f32_16x16x32_bf16 v[44:47], v[136:139], v[166:169], v[44:47]
	v_mfma_f32_16x16x32_bf16 v[40:43], v[146:149], v[166:169], v[40:43]
	v_mfma_f32_16x16x32_bf16 v[28:31], v[136:139], v[174:177], v[28:31]
	v_mfma_f32_16x16x32_bf16 v[24:27], v[146:149], v[174:177], v[24:27]
	v_mfma_f32_16x16x32_bf16 v[12:15], v[136:139], v[182:185], v[12:15]
	v_mfma_f32_16x16x32_bf16 v[8:11], v[146:149], v[182:185], v[8:11]
	v_mfma_f32_16x16x32_bf16 v[60:63], v[140:143], v[162:165], v[60:63]
	v_mfma_f32_16x16x32_bf16 v[56:59], v[154:157], v[162:165], v[56:59]
	v_mfma_f32_16x16x32_bf16 v[44:47], v[140:143], v[170:173], v[44:47]
	v_mfma_f32_16x16x32_bf16 v[40:43], v[154:157], v[170:173], v[40:43]
	v_mfma_f32_16x16x32_bf16 v[28:31], v[140:143], v[178:181], v[28:31]
	v_mfma_f32_16x16x32_bf16 v[24:27], v[154:157], v[178:181], v[24:27]
	v_mfma_f32_16x16x32_bf16 v[12:15], v[140:143], v[198:201], v[12:15]
	v_mfma_f32_16x16x32_bf16 v[8:11], v[154:157], v[198:201], v[8:11]
	s_barrier
; #define PG8_STAGE(bufoff, gbase, voff) do { _Pragma("unroll") for (int _i = 0; _i < 2; ++_i) \
;     __builtin_amdgcn_global_load_lds((const unsigned*)((const char*)(gbase) + (voff)[_i]), (LAS unsigned*)(lds + (bufoff) + ldsw + _i * 8192), 16, 0, 0); } while (0)
; #define PG8_LDA(dst, b, h) do { _Pragma("unroll") for (int m = 0; m < 4; ++m) _Pragma("unroll") for (int k = 0; k < 2; ++k) dst[m][k] = *(const LAS bf16x8*)(lds + PG8_SA(b, h) + aoff + m * 2048 + k * 1024); } while (0)
; #define PG8_LDB(dst, b, h) do { _Pragma("unroll") for (int n = 0; n < 2; ++n) _Pragma("unroll") for (int k = 0; k < 2; ++k) dst[n][k] = *(const LAS bf16x8*)(lds + PG8_SB(b, h) + boff + n * 2048 + k * 1024); } while (0)
; #define PG8_MMA(ai, bj, At, Bt) do { __builtin_amdgcn_s_setprio(1); _Pragma("unroll") for (int m = 0; m < 4; ++m) _Pragma("unroll") for (int n = 0; n < 2; ++n) _Pragma("unroll") for (int k = 0; k < 2; ++k) \
;     acc[ai][bj][m][n] = __builtin_amdgcn_mfma_f32_16x16x32_bf16(Bt[n][k], At[m][k], acc[ai][bj][m][n], 0, 0, 0); __builtin_amdgcn_s_setprio(0); } while (0)
; #define PG8_WAIT_V(n) asm volatile("s_waitcnt vmcnt(" #n ")" ::: "memory")
; #define PG8_WAIT_L(n) asm volatile("s_waitcnt lgkmcnt(" #n ")" ::: "memory")
; #define PG8_BAR __builtin_amdgcn_s_barrier()
; #define PG8_SCHED __builtin_amdgcn_sched_barrier(0)
; template <class Epi, class Sched>
; __device__ __forceinline__ void gemm_phase(LAS unsigned char* lds, const Gemm g, const Sched& S, const Epi& E) {
;     ...
;       PG8_STAGE(PG8_SB(0, 1), b2 + hstepB, voffB);
;       PG8_WAIT_V(6); PG8_BAR; PG8_MMA(1, 1, At, B1); PG8_BAR;
;       PG8_LDB(B0, 1, 0); PG8_SCHED; PG8_LDA(At, 1, 0); PG8_STAGE(PG8_SA(0, 1), a2 + hstepA, voffA);
;       PG8_WAIT_L(8); PG8_BAR; PG8_WAIT_L(0); PG8_MMA(0, 0, At, B0); PG8_BAR; PG8_SCHED;
;       PG8_LDB(B1, 1, 1); PG8_STAGE(PG8_SB(1, 0), b3, voffB);
;       PG8_BAR; PG8_WAIT_L(0); PG8_MMA(0, 1, At, B1); PG8_BAR;
	s_add_u32 s36, s38, 0x40000
	s_addc_u32 s37, s39, 0
	s_add_i32 s76, s77, s68
	v_lshl_add_u64 v[136:137], s[36:37], 0, v[128:129]
	s_mov_b32 m0, s76
	s_nop 0
	global_load_lds_dwordx4 v[136:137], off
	v_lshl_add_u64 v[136:137], s[36:37], 0, v[130:131]
	s_add_i32 m0, s76, 0x2000
	s_nop 0
	global_load_lds_dwordx4 v[136:137], off
	s_waitcnt vmcnt(6)
	s_barrier
	v_mfma_f32_16x16x32_bf16 v[52:55], v[214:217], v[158:161], v[52:55]
	v_mfma_f32_16x16x32_bf16 v[48:51], v[222:225], v[158:161], v[48:51]
	v_mfma_f32_16x16x32_bf16 v[36:39], v[214:217], v[166:169], v[36:39]
	v_mfma_f32_16x16x32_bf16 v[32:35], v[222:225], v[166:169], v[32:35]
	v_mfma_f32_16x16x32_bf16 v[20:23], v[214:217], v[174:177], v[20:23]
	v_mfma_f32_16x16x32_bf16 v[16:19], v[222:225], v[174:177], v[16:19]
	v_mfma_f32_16x16x32_bf16 v[4:7], v[214:217], v[182:185], v[4:7]
	v_mfma_f32_16x16x32_bf16 v[0:3], v[222:225], v[182:185], v[0:3]
	v_mfma_f32_16x16x32_bf16 v[52:55], v[218:221], v[162:165], v[52:55]
	v_mfma_f32_16x16x32_bf16 v[48:51], v[226:229], v[162:165], v[48:51]
	v_mfma_f32_16x16x32_bf16 v[36:39], v[218:221], v[170:173], v[36:39]
	v_mfma_f32_16x16x32_bf16 v[32:35], v[226:229], v[170:173], v[32:35]
	v_mfma_f32_16x16x32_bf16 v[20:23], v[218:221], v[178:181], v[20:23]
	v_mfma_f32_16x16x32_bf16 v[16:19], v[226:229], v[178:181], v[16:19]
	v_mfma_f32_16x16x32_bf16 v[4:7], v[218:221], v[198:201], v[4:7]
	v_mfma_f32_16x16x32_bf16 v[0:3], v[226:229], v[198:201], v[0:3]
	s_add_i32 s76, 16, 0x18000
	v_add_u32_e32 v153, s76, v150
	s_barrier
	ds_read_b128 v[136:139], v153
	ds_read_b128 v[140:143], v153 offset:1024
	ds_read_b128 v[146:149], v153 offset:2048
	ds_read_b128 v[154:157], v153 offset:3072
	s_add_u32 s36, s82, 0x40000
	s_addc_u32 s37, s83, 0
	s_mov_b32 m0, s75
	v_lshl_add_u64 v[214:215], s[36:37], 0, v[128:129]
	ds_read_b128 v[158:161], v152 offset:32768
	ds_read_b128 v[162:165], v152 offset:33792
	ds_read_b128 v[166:169], v152 offset:34816
	ds_read_b128 v[170:173], v152 offset:35840
	ds_read_b128 v[174:177], v152 offset:36864
	ds_read_b128 v[178:181], v152 offset:37888
	ds_read_b128 v[182:185], v152 offset:38912
	ds_read_b128 v[198:201], v152 offset:39936
	global_load_lds_dwordx4 v[214:215], off
	v_lshl_add_u64 v[214:215], s[36:37], 0, v[130:131]
	s_mov_b32 m0, s86
	s_nop 0
	global_load_lds_dwordx4 v[214:215], off
	s_waitcnt lgkmcnt(8)
	s_barrier
	s_waitcnt lgkmcnt(0)
	s_waitcnt lgkmcnt(0)
	v_mfma_f32_16x16x32_bf16 v[124:127], v[136:139], v[158:161], v[124:127]
	v_mfma_f32_16x16x32_bf16 v[120:123], v[146:149], v[158:161], v[120:123]
	v_mfma_f32_16x16x32_bf16 v[108:111], v[136:139], v[166:169], v[108:111]
	v_mfma_f32_16x16x32_bf16 v[104:107], v[146:149], v[166:169], v[104:107]
	v_mfma_f32_16x16x32_bf16 v[92:95], v[136:139], v[174:177], v[92:95]
	v_mfma_f32_16x16x32_bf16 v[88:91], v[146:149], v[174:177], v[88:91]
	v_mfma_f32_16x16x32_bf16 v[76:79], v[136:139], v[182:185], v[76:79]
	v_mfma_f32_16x16x32_bf16 v[72:75], v[146:149], v[182:185], v[72:75]
	v_mfma_f32_16x16x32_bf16 v[124:127], v[140:143], v[162:165], v[124:127]
	v_mfma_f32_16x16x32_bf16 v[120:123], v[154:157], v[162:165], v[120:123]
	v_mfma_f32_16x16x32_bf16 v[108:111], v[140:143], v[170:173], v[108:111]
	v_mfma_f32_16x16x32_bf16 v[104:107], v[154:157], v[170:173], v[104:107]
	v_mfma_f32_16x16x32_bf16 v[92:95], v[140:143], v[178:181], v[92:95]
	v_mfma_f32_16x16x32_bf16 v[88:91], v[154:157], v[178:181], v[88:91]
	v_mfma_f32_16x16x32_bf16 v[76:79], v[140:143], v[198:201], v[76:79]
	v_mfma_f32_16x16x32_bf16 v[72:75], v[154:157], v[198:201], v[72:75]
	s_barrier
	s_add_i32 s77, 16, 0x1c000
	s_add_i32 s36, s76, s68
	v_add_u32_e32 v153, s77, v150
	v_lshl_add_u64 v[230:231], v[230:231], 0, s[62:63]
	s_mov_b32 m0, s36
	ds_read_b128 v[214:217], v153
	ds_read_b128 v[218:221], v153 offset:1024
	ds_read_b128 v[222:225], v153 offset:2048
	ds_read_b128 v[226:229], v153 offset:3072
	global_load_lds_dwordx4 v[230:231], off
	v_lshl_add_u64 v[230:231], v[232:233], 0, s[62:63]
	s_add_i32 m0, s36, 0x2000
	s_nop 0
	global_load_lds_dwordx4 v[230:231], off
	s_barrier
	s_waitcnt lgkmcnt(0)
	s_waitcnt lgkmcnt(0)
	v_mfma_f32_16x16x32_bf16 v[116:119], v[214:217], v[158:161], v[116:119]
	v_mfma_f32_16x16x32_bf16 v[112:115], v[222:225], v[158:161], v[112:115]
	v_mfma_f32_16x16x32_bf16 v[100:103], v[214:217], v[166:169], v[100:103]
	v_mfma_f32_16x16x32_bf16 v[96:99], v[222:225], v[166:169], v[96:99]
	v_mfma_f32_16x16x32_bf16 v[84:87], v[214:217], v[174:177], v[84:87]
	v_mfma_f32_16x16x32_bf16 v[80:83], v[222:225], v[174:177], v[80:83]
	v_mfma_f32_16x16x32_bf16 v[68:71], v[214:217], v[182:185], v[68:71]
	v_mfma_f32_16x16x32_bf16 v[64:67], v[222:225], v[182:185], v[64:67]
	v_mfma_f32_16x16x32_bf16 v[116:119], v[218:221], v[162:165], v[116:119]
	v_mfma_f32_16x16x32_bf16 v[112:115], v[226:229], v[162:165], v[112:115]
	v_mfma_f32_16x16x32_bf16 v[100:103], v[218:221], v[170:173], v[100:103]
	v_mfma_f32_16x16x32_bf16 v[96:99], v[226:229], v[170:173], v[96:99]
	v_mfma_f32_16x16x32_bf16 v[84:87], v[218:221], v[178:181], v[84:87]
	v_mfma_f32_16x16x32_bf16 v[80:83], v[226:229], v[178:181], v[80:83]
	v_mfma_f32_16x16x32_bf16 v[68:71], v[218:221], v[198:201], v[68:71]
	v_mfma_f32_16x16x32_bf16 v[64:67], v[226:229], v[198:201], v[64:67]
	s_mov_b32 m0, s87
	v_lshl_add_u64 v[230:231], v[234:235], 0, s[62:63]
	s_barrier
; __device__ __forceinline__ float sigmoidf_(float v) { return __builtin_amdgcn_rcpf(1.0f + __expf(-v)); }
; __device__ __forceinline__ float siluf_(float v) { return v * sigmoidf_(v); }
; __device__ __forceinline__ void store_bf16x4(bf16_t* p, f32x4 v) { u32x2 w; w.x = cvt_pk_bf16(v[0], v[1]); w.y = cvt_pk_bf16(v[2], v[3]); *(u32x2*)p = w; }
; #define PG8_STAGE(bufoff, gbase, voff) do { _Pragma("unroll") for (int _i = 0; _i < 2; ++_i) \
;     __builtin_amdgcn_global_load_lds((const unsigned*)((const char*)(gbase) + (voff)[_i]), (LAS unsigned*)(lds + (bufoff) + ldsw + _i * 8192), 16, 0, 0); } while (0)
; #define PG8_MMA(ai, bj, At, Bt) do { __builtin_amdgcn_s_setprio(1); _Pragma("unroll") for (int m = 0; m < 4; ++m) _Pragma("unroll") for (int n = 0; n < 2; ++n) _Pragma("unroll") for (int k = 0; k < 2; ++k) \
;     acc[ai][bj][m][n] = __builtin_amdgcn_mfma_f32_16x16x32_bf16(Bt[n][k], At[m][k], acc[ai][bj][m][n], 0, 0, 0); __builtin_amdgcn_s_setprio(0); } while (0)
; #define PG8_WAIT_V(n) asm volatile("s_waitcnt vmcnt(" #n ")" ::: "memory")
; #define PG8_WAIT_L(n) asm volatile("s_waitcnt lgkmcnt(" #n ")" ::: "memory")
; #define PG8_BAR __builtin_amdgcn_s_barrier()
; #define PG8_SCHED __builtin_amdgcn_sched_barrier(0)
; template <class Epi, class Sched>
; __device__ __forceinline__ void gemm_phase(LAS unsigned char* lds, const Gemm g, const Sched& S, const Epi& E) {
;     ...
;       PG8_BAR; PG8_WAIT_L(0); PG8_MMA(1, 0, At, B0); PG8_BAR; PG8_SCHED;
;       PG8_STAGE(PG8_SB(1, 1), b3 + hstepB, voffB);
;       PG8_WAIT_V(6); PG8_BAR; PG8_MMA(1, 1, At, B1); PG8_BAR;
;     }
;     E(acc, cur, wr, wc, fr, fq);
;   __device__ __forceinline__ void operator()(const f32x4 (&acc)[2][2][4][2], const pg8::Unit& u, int wr, int wc, int fr, int fq) const {
;     ...
;     EPI_LOOP(
;       if (pn < 2) { f32x4 o; for (int j = 0; j < 4; ++j) o[j] = siluf_(v[j]); store_bf16x4(QH + (size_t)row * 512 + col, o); }
;       else if (pn < 6) { const int c = col - 512; const f32x4 lb = *(const f32x4*)(LBj + c); f32x4 o; for (int j = 0; j < 4; ++j) o[j] = lb[j] + (1.f - lb[j]) * sigmoidf_(v[j]); *(f32x4*)(F + (size_t)row * 1024 + c) = o; }
	ds_read_b128 v[158:161], v152 offset:49152
	ds_read_b128 v[162:165], v152 offset:50176
	ds_read_b128 v[166:169], v152 offset:51200
	ds_read_b128 v[170:173], v152 offset:52224
	ds_read_b128 v[174:177], v152 offset:53248
	ds_read_b128 v[178:181], v152 offset:54272
	ds_read_b128 v[182:185], v152 offset:55296
	ds_read_b128 v[198:201], v152 offset:56320
	global_load_lds_dwordx4 v[230:231], off
	v_lshl_add_u64 v[230:231], v[236:237], 0, s[62:63]
	s_mov_b32 m0, s88
	s_nop 0
	global_load_lds_dwordx4 v[230:231], off
	s_barrier
	s_waitcnt lgkmcnt(0)
	s_waitcnt lgkmcnt(0)
	v_mfma_f32_16x16x32_bf16 v[60:63], v[136:139], v[158:161], v[60:63]
	v_mfma_f32_16x16x32_bf16 v[56:59], v[146:149], v[158:161], v[56:59]
	v_mfma_f32_16x16x32_bf16 v[44:47], v[136:139], v[166:169], v[44:47]
	v_mfma_f32_16x16x32_bf16 v[40:43], v[146:149], v[166:169], v[40:43]
	v_mfma_f32_16x16x32_bf16 v[28:31], v[136:139], v[174:177], v[28:31]
	v_mfma_f32_16x16x32_bf16 v[24:27], v[146:149], v[174:177], v[24:27]
	v_mfma_f32_16x16x32_bf16 v[12:15], v[136:139], v[182:185], v[12:15]
	v_mfma_f32_16x16x32_bf16 v[8:11], v[146:149], v[182:185], v[8:11]
	v_mfma_f32_16x16x32_bf16 v[60:63], v[140:143], v[162:165], v[60:63]
	v_mfma_f32_16x16x32_bf16 v[56:59], v[154:157], v[162:165], v[56:59]
	v_mfma_f32_16x16x32_bf16 v[44:47], v[140:143], v[170:173], v[44:47]
	v_mfma_f32_16x16x32_bf16 v[40:43], v[154:157], v[170:173], v[40:43]
	v_mfma_f32_16x16x32_bf16 v[28:31], v[140:143], v[178:181], v[28:31]
	v_mfma_f32_16x16x32_bf16 v[24:27], v[154:157], v[178:181], v[24:27]
	v_mfma_f32_16x16x32_bf16 v[12:15], v[140:143], v[198:201], v[12:15]
	v_mfma_f32_16x16x32_bf16 v[8:11], v[154:157], v[198:201], v[8:11]
	s_barrier
	s_add_u32 s36, s38, 0x40080
	s_addc_u32 s37, s39, 0
	s_add_i32 s38, s77, s68
	v_lshl_add_u64 v[136:137], s[36:37], 0, v[128:129]
	s_mov_b32 m0, s38
	s_nop 0
	global_load_lds_dwordx4 v[136:137], off
	v_lshl_add_u64 v[136:137], s[36:37], 0, v[130:131]
	s_add_i32 m0, s38, 0x2000
	s_nop 0
	global_load_lds_dwordx4 v[136:137], off
	s_waitcnt vmcnt(6)
	s_barrier
	v_mfma_f32_16x16x32_bf16 v[52:55], v[214:217], v[158:161], v[52:55]
	v_mfma_f32_16x16x32_bf16 v[48:51], v[222:225], v[158:161], v[48:51]
	v_mfma_f32_16x16x32_bf16 v[36:39], v[214:217], v[166:169], v[36:39]
	v_mfma_f32_16x16x32_bf16 v[32:35], v[222:225], v[166:169], v[32:35]
	v_mfma_f32_16x16x32_bf16 v[20:23], v[214:217], v[174:177], v[20:23]
	v_mfma_f32_16x16x32_bf16 v[16:19], v[222:225], v[174:177], v[16:19]
	v_mfma_f32_16x16x32_bf16 v[4:7], v[214:217], v[182:185], v[4:7]
	v_mfma_f32_16x16x32_bf16 v[0:3], v[222:225], v[182:185], v[0:3]
	v_mfma_f32_16x16x32_bf16 v[52:55], v[218:221], v[162:165], v[52:55]
	v_mfma_f32_16x16x32_bf16 v[48:51], v[226:229], v[162:165], v[48:51]
	v_mfma_f32_16x16x32_bf16 v[36:39], v[218:221], v[170:173], v[36:39]
	v_mfma_f32_16x16x32_bf16 v[32:35], v[226:229], v[170:173], v[32:35]
	v_mfma_f32_16x16x32_bf16 v[20:23], v[218:221], v[178:181], v[20:23]
	v_mfma_f32_16x16x32_bf16 v[16:19], v[226:229], v[178:181], v[16:19]
	v_mfma_f32_16x16x32_bf16 v[4:7], v[218:221], v[198:201], v[4:7]
	v_mfma_f32_16x16x32_bf16 v[0:3], v[226:229], v[198:201], v[0:3]
	s_add_i32 s84, s84, 2
	s_add_u32 s78, s78, 0x100
	s_addc_u32 s79, s79, 0
	s_add_u32 s25, s25, 0x100
	s_addc_u32 s27, s27, 0
	s_cmp_gt_u32 s84, 13
	s_barrier
	s_cbranch_scc0 .LBB0_1541
	s_cmp_gt_i32 s8, 1
	s_cselect_b64 s[82:83], -1, 0
	s_cmp_gt_u32 s8, 5
	v_lshl_add_u32 v138, s10, 8, v145
	s_cselect_b64 s[38:39], -1, 0
	s_cmp_gt_u32 s8, 7
	v_lshl_or_b32 v136, s8, 8, v151
	s_cselect_b64 s[84:85], -1, 0
	s_cmp_gt_u32 s8, 9
	v_ashrrev_i32_e32 v139, 31, v138
	v_mad_i64_i32 v[146:147], s[8:9], v138, s64, 0
	s_cselect_b64 s[78:79], -1, 0
	v_lshlrev_b64 v[142:143], 10, v[138:139]
	v_lshlrev_b64 v[140:141], 12, v[138:139]
	v_and_b32_e32 v244, 16, v187
	v_lshrrev_b32_e32 v245, 1, v244
	v_add_u32_e32 v244, v244, v245
	v_mov_b32_e32 v245, v144
	s_andn2_b64 vcc, s[82:83], s[38:39]
	s_cbranch_vccz .Llbv_skip
	v_mov_b32_e32 v148, v136
	v_ashrrev_i32_e32 v149, 31, v136
	v_lshlrev_b64 v[148:149], 2, v[148:149]
	v_lshl_add_u64 v[148:149], s[18:19], 0, v[148:149]
	global_load_dwordx4 v[238:241], v[148:149], off offset:-2048
	global_load_dwordx4 v[242:245], v[148:149], off offset:-1984
	global_load_dwordx4 v[246:249], v[148:149], off offset:-1536
	global_load_dwordx4 v[250:253], v[148:149], off offset:-1472
	s_waitcnt vmcnt(0)

; #define PG8_STAGE(bufoff, gbase, voff) do { _Pragma("unroll") for (int _i = 0; _i < 2; ++_i) \
;     __builtin_amdgcn_global_load_lds((const unsigned*)((const char*)(gbase) + (voff)[_i]), (LAS unsigned*)(lds + (bufoff) + ldsw + _i * 8192), 16, 0, 0); } while (0)
; #define PG8_LDA(dst, b, h) do { _Pragma("unroll") for (int m = 0; m < 4; ++m) _Pragma("unroll") for (int k = 0; k < 2; ++k) dst[m][k] = *(const LAS bf16x8*)(lds + PG8_SA(b, h) + aoff + m * 2048 + k * 1024); } while (0)
; #define PG8_LDB(dst, b, h) do { _Pragma("unroll") for (int n = 0; n < 2; ++n) _Pragma("unroll") for (int k = 0; k < 2; ++k) dst[n][k] = *(const LAS bf16x8*)(lds + PG8_SB(b, h) + boff + n * 2048 + k * 1024); } while (0)
; #define PG8_MMA(ai, bj, At, Bt) do { __builtin_amdgcn_s_setprio(1); _Pragma("unroll") for (int m = 0; m < 4; ++m) _Pragma("unroll") for (int n = 0; n < 2; ++n) _Pragma("unroll") for (int k = 0; k < 2; ++k) \
;     acc[ai][bj][m][n] = __builtin_amdgcn_mfma_f32_16x16x32_bf16(Bt[n][k], At[m][k], acc[ai][bj][m][n], 0, 0, 0); __builtin_amdgcn_s_setprio(0); } while (0)
; #define PG8_WAIT_L(n) asm volatile("s_waitcnt lgkmcnt(" #n ")" ::: "memory")
; #define PG8_BAR __builtin_amdgcn_s_barrier()
; #define PG8_SCHED __builtin_amdgcn_sched_barrier(0)
; template <class Epi, class Sched>
; __device__ __forceinline__ void gemm_phase(LAS unsigned char* lds, const Gemm g, const Sched& S, const Epi& E) {
;     ...
;       const bool last = (t == nt - 2);
;       const char* a1 = cA + (size_t)(t + 1) * kstep;
;       const char* a2 = last ? nA : cA + (size_t)(t + 2) * kstep; const char* b2 = last ? nB : cB + (size_t)(t + 2) * kstep;
;       const char* a3 = a2 + kstep; const char* b3 = b2 + kstep;
;       PG8_LDB(B0, 0, 0); PG8_SCHED; PG8_LDA(At, 0, 0); PG8_STAGE(PG8_SA(1, 1), a1 + hstepA, voffA);
;       PG8_WAIT_L(8); PG8_BAR; PG8_WAIT_L(0); PG8_MMA(0, 0, At, B0); PG8_BAR; PG8_SCHED;
;       PG8_LDB(B1, 0, 1); PG8_STAGE(PG8_SB(0, 0), b2, voffB);
;       PG8_BAR; PG8_WAIT_L(0); PG8_MMA(0, 1, At, B1); PG8_BAR;
;       PG8_LDA(At, 0, 1); PG8_STAGE(PG8_SA(0, 0), a2, voffA);
;       PG8_BAR; PG8_WAIT_L(0); PG8_MMA(1, 0, At, B0); PG8_BAR; PG8_SCHED;
.LBB0_2347:
	s_add_u32 s10, s14, 0x100
	s_addc_u32 s11, s15, 0
	s_add_i32 s36, 16, 0x10000
	v_add_u32_e32 v149, s36, v146
	ds_read_b128 v[140:143], v149
	ds_read_b128 v[150:153], v149 offset:1024
	ds_read_b128 v[154:157], v149 offset:2048
	ds_read_b128 v[158:161], v149 offset:3072
	s_cmp_eq_u32 s58, 2
	s_cselect_b32 s19, s5, s11
	s_cselect_b32 s18, s4, s10
	s_cselect_b32 s17, s9, s51
	s_cselect_b32 s16, s8, s49
	v_lshl_add_u64 v[218:219], s[14:15], 0, v[136:137]
	s_add_i32 m0, s24, 0xc000
	ds_read_b128 v[162:165], v148
	ds_read_b128 v[166:169], v148 offset:1024
	ds_read_b128 v[170:173], v148 offset:2048
	ds_read_b128 v[174:177], v148 offset:3072
	ds_read_b128 v[178:181], v148 offset:4096
	ds_read_b128 v[182:185], v148 offset:5120
	ds_read_b128 v[198:201], v148 offset:6144
	ds_read_b128 v[214:217], v148 offset:7168
	global_load_lds_dwordx4 v[218:219], off
	v_lshl_add_u64 v[218:219], s[14:15], 0, v[138:139]
	s_add_i32 m0, s24, 0xe000
	s_nop 0
	global_load_lds_dwordx4 v[218:219], off
	s_waitcnt lgkmcnt(8)
	s_barrier
	s_waitcnt lgkmcnt(0)
	s_waitcnt lgkmcnt(0)
	v_mfma_f32_16x16x32_bf16 v[124:127], v[140:143], v[162:165], v[124:127]
	v_mfma_f32_16x16x32_bf16 v[120:123], v[154:157], v[162:165], v[120:123]
	v_mfma_f32_16x16x32_bf16 v[116:119], v[140:143], v[170:173], v[116:119]
	v_mfma_f32_16x16x32_bf16 v[108:111], v[154:157], v[170:173], v[108:111]
	v_mfma_f32_16x16x32_bf16 v[100:103], v[140:143], v[178:181], v[100:103]
	v_mfma_f32_16x16x32_bf16 v[92:95], v[154:157], v[178:181], v[92:95]
	v_mfma_f32_16x16x32_bf16 v[84:87], v[140:143], v[198:201], v[84:87]
	v_mfma_f32_16x16x32_bf16 v[76:79], v[154:157], v[198:201], v[76:79]
	v_mfma_f32_16x16x32_bf16 v[124:127], v[150:153], v[166:169], v[124:127]
	v_mfma_f32_16x16x32_bf16 v[120:123], v[158:161], v[166:169], v[120:123]
	v_mfma_f32_16x16x32_bf16 v[116:119], v[150:153], v[174:177], v[116:119]
	v_mfma_f32_16x16x32_bf16 v[108:111], v[158:161], v[174:177], v[108:111]
	v_mfma_f32_16x16x32_bf16 v[100:103], v[150:153], v[182:185], v[100:103]
	v_mfma_f32_16x16x32_bf16 v[92:95], v[158:161], v[182:185], v[92:95]
	v_mfma_f32_16x16x32_bf16 v[84:87], v[150:153], v[214:217], v[84:87]
	v_mfma_f32_16x16x32_bf16 v[76:79], v[158:161], v[214:217], v[76:79]
	s_barrier
	s_add_i32 s37, 16, 0x14000
	s_add_i32 s14, s36, s23
	v_add_u32_e32 v149, s37, v146
	v_lshl_add_u64 v[234:235], s[16:17], 0, v[132:133]
	s_mov_b32 m0, s14
	ds_read_b128 v[218:221], v149
	ds_read_b128 v[222:225], v149 offset:1024
	ds_read_b128 v[226:229], v149 offset:2048
	ds_read_b128 v[230:233], v149 offset:3072
	global_load_lds_dwordx4 v[234:235], off
	v_lshl_add_u64 v[236:237], s[16:17], 0, v[128:129]
	s_add_i32 m0, s14, 0x2000
	s_nop 0
	global_load_lds_dwordx4 v[236:237], off
	s_barrier
	s_waitcnt lgkmcnt(0)
	s_waitcnt lgkmcnt(0)
	v_mfma_f32_16x16x32_bf16 v[112:115], v[218:221], v[162:165], v[112:115]
	v_mfma_f32_16x16x32_bf16 v[104:107], v[226:229], v[162:165], v[104:107]
	v_mfma_f32_16x16x32_bf16 v[96:99], v[218:221], v[170:173], v[96:99]
	v_mfma_f32_16x16x32_bf16 v[88:91], v[226:229], v[170:173], v[88:91]
	v_mfma_f32_16x16x32_bf16 v[80:83], v[218:221], v[178:181], v[80:83]
	v_mfma_f32_16x16x32_bf16 v[72:75], v[226:229], v[178:181], v[72:75]
	v_mfma_f32_16x16x32_bf16 v[68:71], v[218:221], v[198:201], v[68:71]
	v_mfma_f32_16x16x32_bf16 v[64:67], v[226:229], v[198:201], v[64:67]
	v_mfma_f32_16x16x32_bf16 v[112:115], v[222:225], v[166:169], v[112:115]
	v_mfma_f32_16x16x32_bf16 v[104:107], v[230:233], v[166:169], v[104:107]
	v_mfma_f32_16x16x32_bf16 v[96:99], v[222:225], v[174:177], v[96:99]
	v_mfma_f32_16x16x32_bf16 v[88:91], v[230:233], v[174:177], v[88:91]
	v_mfma_f32_16x16x32_bf16 v[80:83], v[222:225], v[182:185], v[80:83]
	v_mfma_f32_16x16x32_bf16 v[72:75], v[230:233], v[182:185], v[72:75]
	v_mfma_f32_16x16x32_bf16 v[68:71], v[222:225], v[214:217], v[68:71]
	v_mfma_f32_16x16x32_bf16 v[64:67], v[230:233], v[214:217], v[64:67]
	s_mov_b32 m0, s24
	v_lshl_add_u64 v[238:239], s[18:19], 0, v[134:135]
	s_barrier
	ds_read_b128 v[162:165], v148 offset:16384
	ds_read_b128 v[166:169], v148 offset:17408
	ds_read_b128 v[170:173], v148 offset:18432
	ds_read_b128 v[174:177], v148 offset:19456
	ds_read_b128 v[178:181], v148 offset:20480
	ds_read_b128 v[182:185], v148 offset:21504
	ds_read_b128 v[198:201], v148 offset:22528
	ds_read_b128 v[214:217], v148 offset:23552
	global_load_lds_dwordx4 v[238:239], off
	v_lshl_add_u64 v[240:241], s[18:19], 0, v[130:131]
	s_mov_b32 m0, s25
	s_nop 0
	global_load_lds_dwordx4 v[240:241], off
	s_barrier
	s_waitcnt lgkmcnt(0)
	s_waitcnt lgkmcnt(0)
	v_mfma_f32_16x16x32_bf16 v[60:63], v[140:143], v[162:165], v[60:63]
	v_mfma_f32_16x16x32_bf16 v[56:59], v[154:157], v[162:165], v[56:59]
	v_mfma_f32_16x16x32_bf16 v[52:55], v[140:143], v[170:173], v[52:55]
	v_mfma_f32_16x16x32_bf16 v[44:47], v[154:157], v[170:173], v[44:47]
	v_mfma_f32_16x16x32_bf16 v[36:39], v[140:143], v[178:181], v[36:39]
	v_mfma_f32_16x16x32_bf16 v[28:31], v[154:157], v[178:181], v[28:31]
	v_mfma_f32_16x16x32_bf16 v[20:23], v[140:143], v[198:201], v[20:23]
	v_mfma_f32_16x16x32_bf16 v[12:15], v[154:157], v[198:201], v[12:15]
	v_mfma_f32_16x16x32_bf16 v[60:63], v[150:153], v[166:169], v[60:63]
	v_mfma_f32_16x16x32_bf16 v[56:59], v[158:161], v[166:169], v[56:59]
	v_mfma_f32_16x16x32_bf16 v[52:55], v[150:153], v[174:177], v[52:55]
	v_mfma_f32_16x16x32_bf16 v[44:47], v[158:161], v[174:177], v[44:47]
	v_mfma_f32_16x16x32_bf16 v[36:39], v[150:153], v[182:185], v[36:39]
	v_mfma_f32_16x16x32_bf16 v[28:31], v[158:161], v[182:185], v[28:31]
	v_mfma_f32_16x16x32_bf16 v[20:23], v[150:153], v[214:217], v[20:23]
	v_mfma_f32_16x16x32_bf16 v[12:15], v[158:161], v[214:217], v[12:15]
	s_barrier
; #define PG8_STAGE(bufoff, gbase, voff) do { _Pragma("unroll") for (int _i = 0; _i < 2; ++_i) \
;     __builtin_amdgcn_global_load_lds((const unsigned*)((const char*)(gbase) + (voff)[_i]), (LAS unsigned*)(lds + (bufoff) + ldsw + _i * 8192), 16, 0, 0); } while (0)
; #define PG8_LDA(dst, b, h) do { _Pragma("unroll") for (int m = 0; m < 4; ++m) _Pragma("unroll") for (int k = 0; k < 2; ++k) dst[m][k] = *(const LAS bf16x8*)(lds + PG8_SA(b, h) + aoff + m * 2048 + k * 1024); } while (0)
; #define PG8_LDB(dst, b, h) do { _Pragma("unroll") for (int n = 0; n < 2; ++n) _Pragma("unroll") for (int k = 0; k < 2; ++k) dst[n][k] = *(const LAS bf16x8*)(lds + PG8_SB(b, h) + boff + n * 2048 + k * 1024); } while (0)
; #define PG8_MMA(ai, bj, At, Bt) do { __builtin_amdgcn_s_setprio(1); _Pragma("unroll") for (int m = 0; m < 4; ++m) _Pragma("unroll") for (int n = 0; n < 2; ++n) _Pragma("unroll") for (int k = 0; k < 2; ++k) \
;     acc[ai][bj][m][n] = __builtin_amdgcn_mfma_f32_16x16x32_bf16(Bt[n][k], At[m][k], acc[ai][bj][m][n], 0, 0, 0); __builtin_amdgcn_s_setprio(0); } while (0)
; #define PG8_WAIT_V(n) asm volatile("s_waitcnt vmcnt(" #n ")" ::: "memory")
; #define PG8_WAIT_L(n) asm volatile("s_waitcnt lgkmcnt(" #n ")" ::: "memory")
; #define PG8_BAR __builtin_amdgcn_s_barrier()
; #define PG8_SCHED __builtin_amdgcn_sched_barrier(0)
; template <class Epi, class Sched>
; __device__ __forceinline__ void gemm_phase(LAS unsigned char* lds, const Gemm g, const Sched& S, const Epi& E) {
;     ...
;       PG8_STAGE(PG8_SB(0, 1), b2 + hstepB, voffB);
;       PG8_WAIT_V(6); PG8_BAR; PG8_MMA(1, 1, At, B1); PG8_BAR;
;       PG8_LDB(B0, 1, 0); PG8_SCHED; PG8_LDA(At, 1, 0); PG8_STAGE(PG8_SA(0, 1), a2 + hstepA, voffA);
;       PG8_WAIT_L(8); PG8_BAR; PG8_WAIT_L(0); PG8_MMA(0, 0, At, B0); PG8_BAR; PG8_SCHED;
;       PG8_LDB(B1, 1, 1); PG8_STAGE(PG8_SB(1, 0), b3, voffB);
;       PG8_BAR; PG8_WAIT_L(0); PG8_MMA(0, 1, At, B1); PG8_BAR;
;       PG8_LDA(At, 1, 1); PG8_STAGE(PG8_SA(1, 0), a3, voffA);
;       PG8_BAR; PG8_WAIT_L(0); PG8_MMA(1, 0, At, B0); PG8_BAR; PG8_SCHED;
	s_add_u32 s14, s16, 0x18000
	s_addc_u32 s15, s17, 0
	s_add_i32 s36, s37, s23
	v_lshl_add_u64 v[140:141], s[14:15], 0, v[132:133]
	s_mov_b32 m0, s36
	s_nop 0
	global_load_lds_dwordx4 v[140:141], off
	v_lshl_add_u64 v[140:141], s[14:15], 0, v[128:129]
	s_add_i32 m0, s36, 0x2000
	s_nop 0
	global_load_lds_dwordx4 v[140:141], off
	s_waitcnt vmcnt(6)
	s_barrier
	v_mfma_f32_16x16x32_bf16 v[48:51], v[218:221], v[162:165], v[48:51]
	v_mfma_f32_16x16x32_bf16 v[40:43], v[226:229], v[162:165], v[40:43]
	v_mfma_f32_16x16x32_bf16 v[32:35], v[218:221], v[170:173], v[32:35]
	v_mfma_f32_16x16x32_bf16 v[24:27], v[226:229], v[170:173], v[24:27]
	v_mfma_f32_16x16x32_bf16 v[16:19], v[218:221], v[178:181], v[16:19]
	v_mfma_f32_16x16x32_bf16 v[8:11], v[226:229], v[178:181], v[8:11]
	v_mfma_f32_16x16x32_bf16 v[4:7], v[218:221], v[198:201], v[4:7]
	v_mfma_f32_16x16x32_bf16 v[0:3], v[226:229], v[198:201], v[0:3]
	v_mfma_f32_16x16x32_bf16 v[48:51], v[222:225], v[166:169], v[48:51]
	v_mfma_f32_16x16x32_bf16 v[40:43], v[230:233], v[166:169], v[40:43]
	v_mfma_f32_16x16x32_bf16 v[32:35], v[222:225], v[174:177], v[32:35]
	v_mfma_f32_16x16x32_bf16 v[24:27], v[230:233], v[174:177], v[24:27]
	v_mfma_f32_16x16x32_bf16 v[16:19], v[222:225], v[182:185], v[16:19]
	v_mfma_f32_16x16x32_bf16 v[8:11], v[230:233], v[182:185], v[8:11]
	v_mfma_f32_16x16x32_bf16 v[4:7], v[222:225], v[214:217], v[4:7]
	v_mfma_f32_16x16x32_bf16 v[0:3], v[230:233], v[214:217], v[0:3]
	s_add_i32 s36, 16, 0x18000
	v_add_u32_e32 v149, s36, v146
	s_barrier
	ds_read_b128 v[140:143], v149
	ds_read_b128 v[150:153], v149 offset:1024
	ds_read_b128 v[154:157], v149 offset:2048
	ds_read_b128 v[158:161], v149 offset:3072
	s_add_u32 s14, s18, 0x30000
	s_addc_u32 s15, s19, 0
	s_mov_b32 m0, s26
	v_lshl_add_u64 v[218:219], s[14:15], 0, v[134:135]
	ds_read_b128 v[162:165], v148 offset:32768
	ds_read_b128 v[166:169], v148 offset:33792
	ds_read_b128 v[170:173], v148 offset:34816
	ds_read_b128 v[174:177], v148 offset:35840
	ds_read_b128 v[178:181], v148 offset:36864
	ds_read_b128 v[182:185], v148 offset:37888
	ds_read_b128 v[198:201], v148 offset:38912
	ds_read_b128 v[214:217], v148 offset:39936
	global_load_lds_dwordx4 v[218:219], off
	v_lshl_add_u64 v[218:219], s[14:15], 0, v[130:131]
	s_mov_b32 m0, s27
	s_nop 0
	global_load_lds_dwordx4 v[218:219], off
	s_waitcnt lgkmcnt(8)
	s_barrier
	s_waitcnt lgkmcnt(0)
	s_waitcnt lgkmcnt(0)
	v_mfma_f32_16x16x32_bf16 v[124:127], v[140:143], v[162:165], v[124:127]
	v_mfma_f32_16x16x32_bf16 v[120:123], v[154:157], v[162:165], v[120:123]
	v_mfma_f32_16x16x32_bf16 v[116:119], v[140:143], v[170:173], v[116:119]
	v_mfma_f32_16x16x32_bf16 v[108:111], v[154:157], v[170:173], v[108:111]
	v_mfma_f32_16x16x32_bf16 v[100:103], v[140:143], v[178:181], v[100:103]
	v_mfma_f32_16x16x32_bf16 v[92:95], v[154:157], v[178:181], v[92:95]
	v_mfma_f32_16x16x32_bf16 v[84:87], v[140:143], v[198:201], v[84:87]
	v_mfma_f32_16x16x32_bf16 v[76:79], v[154:157], v[198:201], v[76:79]
	v_mfma_f32_16x16x32_bf16 v[124:127], v[150:153], v[166:169], v[124:127]
	v_mfma_f32_16x16x32_bf16 v[120:123], v[158:161], v[166:169], v[120:123]
	v_mfma_f32_16x16x32_bf16 v[116:119], v[150:153], v[174:177], v[116:119]
	v_mfma_f32_16x16x32_bf16 v[108:111], v[158:161], v[174:177], v[108:111]
	v_mfma_f32_16x16x32_bf16 v[100:103], v[150:153], v[182:185], v[100:103]
	v_mfma_f32_16x16x32_bf16 v[92:95], v[158:161], v[182:185], v[92:95]
	v_mfma_f32_16x16x32_bf16 v[84:87], v[150:153], v[214:217], v[84:87]
	v_mfma_f32_16x16x32_bf16 v[76:79], v[158:161], v[214:217], v[76:79]
	s_barrier
	s_add_i32 s18, 16, 0x1c000
	s_add_i32 s14, s36, s23
	v_add_u32_e32 v149, s18, v146
	v_lshl_add_u64 v[234:235], v[234:235], 0, s[62:63]
	s_mov_b32 m0, s14
	ds_read_b128 v[218:221], v149
	ds_read_b128 v[222:225], v149 offset:1024
	ds_read_b128 v[226:229], v149 offset:2048
	ds_read_b128 v[230:233], v149 offset:3072
	global_load_lds_dwordx4 v[234:235], off
	v_lshl_add_u64 v[234:235], v[236:237], 0, s[62:63]
	s_add_i32 m0, s14, 0x2000
	s_nop 0
	global_load_lds_dwordx4 v[234:235], off
	s_barrier
	s_waitcnt lgkmcnt(0)
	s_waitcnt lgkmcnt(0)
	v_mfma_f32_16x16x32_bf16 v[112:115], v[218:221], v[162:165], v[112:115]
	v_mfma_f32_16x16x32_bf16 v[104:107], v[226:229], v[162:165], v[104:107]
	v_mfma_f32_16x16x32_bf16 v[96:99], v[218:221], v[170:173], v[96:99]
	v_mfma_f32_16x16x32_bf16 v[88:91], v[226:229], v[170:173], v[88:91]
	v_mfma_f32_16x16x32_bf16 v[80:83], v[218:221], v[178:181], v[80:83]
	v_mfma_f32_16x16x32_bf16 v[72:75], v[226:229], v[178:181], v[72:75]
	v_mfma_f32_16x16x32_bf16 v[68:71], v[218:221], v[198:201], v[68:71]
	v_mfma_f32_16x16x32_bf16 v[64:67], v[226:229], v[198:201], v[64:67]
	v_mfma_f32_16x16x32_bf16 v[112:115], v[222:225], v[166:169], v[112:115]
	v_mfma_f32_16x16x32_bf16 v[104:107], v[230:233], v[166:169], v[104:107]
	v_mfma_f32_16x16x32_bf16 v[96:99], v[222:225], v[174:177], v[96:99]
	v_mfma_f32_16x16x32_bf16 v[88:91], v[230:233], v[174:177], v[88:91]
	v_mfma_f32_16x16x32_bf16 v[80:83], v[222:225], v[182:185], v[80:83]
	v_mfma_f32_16x16x32_bf16 v[72:75], v[230:233], v[182:185], v[72:75]
	v_mfma_f32_16x16x32_bf16 v[68:71], v[222:225], v[214:217], v[68:71]
	v_mfma_f32_16x16x32_bf16 v[64:67], v[230:233], v[214:217], v[64:67]
	s_mov_b32 m0, s28
	v_lshl_add_u64 v[234:235], v[238:239], 0, s[62:63]
	s_barrier
	ds_read_b128 v[162:165], v148 offset:49152
	ds_read_b128 v[166:169], v148 offset:50176
	ds_read_b128 v[170:173], v148 offset:51200
	ds_read_b128 v[174:177], v148 offset:52224
	ds_read_b128 v[178:181], v148 offset:53248
	ds_read_b128 v[182:185], v148 offset:54272
	ds_read_b128 v[198:201], v148 offset:55296
	ds_read_b128 v[214:217], v148 offset:56320
	global_load_lds_dwordx4 v[234:235], off
	v_lshl_add_u64 v[234:235], v[240:241], 0, s[62:63]
	s_mov_b32 m0, s29
	s_nop 0
	global_load_lds_dwordx4 v[234:235], off
	s_barrier
; #define PG8_STAGE(bufoff, gbase, voff) do { _Pragma("unroll") for (int _i = 0; _i < 2; ++_i) \
;     __builtin_amdgcn_global_load_lds((const unsigned*)((const char*)(gbase) + (voff)[_i]), (LAS unsigned*)(lds + (bufoff) + ldsw + _i * 8192), 16, 0, 0); } while (0)
; #define PG8_MMA(ai, bj, At, Bt) do { __builtin_amdgcn_s_setprio(1); _Pragma("unroll") for (int m = 0; m < 4; ++m) _Pragma("unroll") for (int n = 0; n < 2; ++n) _Pragma("unroll") for (int k = 0; k < 2; ++k) \
;     acc[ai][bj][m][n] = __builtin_amdgcn_mfma_f32_16x16x32_bf16(Bt[n][k], At[m][k], acc[ai][bj][m][n], 0, 0, 0); __builtin_amdgcn_s_setprio(0); } while (0)
; #define PG8_WAIT_V(n) asm volatile("s_waitcnt vmcnt(" #n ")" ::: "memory")
; #define PG8_WAIT_L(n) asm volatile("s_waitcnt lgkmcnt(" #n ")" ::: "memory")
; #define PG8_BAR __builtin_amdgcn_s_barrier()
; #define PG8_SCHED __builtin_amdgcn_sched_barrier(0)
; template <class Epi, class Sched>
; __device__ __forceinline__ void gemm_phase(LAS unsigned char* lds, const Gemm g, const Sched& S, const Epi& E) {
;     ...
;       PG8_BAR; PG8_WAIT_L(0); PG8_MMA(1, 0, At, B0); PG8_BAR; PG8_SCHED;
;       PG8_STAGE(PG8_SB(1, 1), b3 + hstepB, voffB);
;       PG8_WAIT_V(6); PG8_BAR; PG8_MMA(1, 1, At, B1); PG8_BAR;
	s_waitcnt lgkmcnt(0)
	s_waitcnt lgkmcnt(0)
	v_mfma_f32_16x16x32_bf16 v[60:63], v[140:143], v[162:165], v[60:63]
	v_mfma_f32_16x16x32_bf16 v[56:59], v[154:157], v[162:165], v[56:59]
	v_mfma_f32_16x16x32_bf16 v[52:55], v[140:143], v[170:173], v[52:55]
	v_mfma_f32_16x16x32_bf16 v[44:47], v[154:157], v[170:173], v[44:47]
	v_mfma_f32_16x16x32_bf16 v[36:39], v[140:143], v[178:181], v[36:39]
	v_mfma_f32_16x16x32_bf16 v[28:31], v[154:157], v[178:181], v[28:31]
	v_mfma_f32_16x16x32_bf16 v[20:23], v[140:143], v[198:201], v[20:23]
	v_mfma_f32_16x16x32_bf16 v[12:15], v[154:157], v[198:201], v[12:15]
	v_mfma_f32_16x16x32_bf16 v[60:63], v[150:153], v[166:169], v[60:63]
	v_mfma_f32_16x16x32_bf16 v[56:59], v[158:161], v[166:169], v[56:59]
	v_mfma_f32_16x16x32_bf16 v[52:55], v[150:153], v[174:177], v[52:55]
	v_mfma_f32_16x16x32_bf16 v[44:47], v[158:161], v[174:177], v[44:47]
	v_mfma_f32_16x16x32_bf16 v[36:39], v[150:153], v[182:185], v[36:39]
	v_mfma_f32_16x16x32_bf16 v[28:31], v[158:161], v[182:185], v[28:31]
	v_mfma_f32_16x16x32_bf16 v[20:23], v[150:153], v[214:217], v[20:23]
	v_mfma_f32_16x16x32_bf16 v[12:15], v[158:161], v[214:217], v[12:15]
	s_barrier
	s_add_u32 s14, s16, 0x18080
	s_addc_u32 s15, s17, 0
	s_add_i32 s16, s18, s23
	v_lshl_add_u64 v[140:141], s[14:15], 0, v[132:133]
	s_mov_b32 m0, s16
	s_nop 0
	global_load_lds_dwordx4 v[140:141], off
	v_lshl_add_u64 v[140:141], s[14:15], 0, v[128:129]
	s_add_i32 m0, s16, 0x2000
	s_nop 0
	global_load_lds_dwordx4 v[140:141], off
	s_waitcnt vmcnt(6)
	s_barrier
	v_mfma_f32_16x16x32_bf16 v[48:51], v[218:221], v[162:165], v[48:51]
	v_mfma_f32_16x16x32_bf16 v[40:43], v[226:229], v[162:165], v[40:43]
	v_mfma_f32_16x16x32_bf16 v[32:35], v[218:221], v[170:173], v[32:35]
	v_mfma_f32_16x16x32_bf16 v[24:27], v[226:229], v[170:173], v[24:27]
	v_mfma_f32_16x16x32_bf16 v[16:19], v[218:221], v[178:181], v[16:19]
	v_mfma_f32_16x16x32_bf16 v[8:11], v[226:229], v[178:181], v[8:11]
	v_mfma_f32_16x16x32_bf16 v[4:7], v[218:221], v[198:201], v[4:7]
	v_mfma_f32_16x16x32_bf16 v[0:3], v[226:229], v[198:201], v[0:3]
	v_mfma_f32_16x16x32_bf16 v[48:51], v[222:225], v[166:169], v[48:51]
	v_mfma_f32_16x16x32_bf16 v[40:43], v[230:233], v[166:169], v[40:43]
	v_mfma_f32_16x16x32_bf16 v[32:35], v[222:225], v[174:177], v[32:35]
	v_mfma_f32_16x16x32_bf16 v[24:27], v[230:233], v[174:177], v[24:27]
	v_mfma_f32_16x16x32_bf16 v[16:19], v[222:225], v[182:185], v[16:19]
	v_mfma_f32_16x16x32_bf16 v[8:11], v[230:233], v[182:185], v[8:11]
	v_mfma_f32_16x16x32_bf16 v[4:7], v[222:225], v[214:217], v[4:7]
	v_mfma_f32_16x16x32_bf16 v[0:3], v[230:233], v[214:217], v[0:3]
	s_add_i32 s58, s58, 2
	s_add_u32 s49, s49, 0x100
	s_addc_u32 s51, s51, 0
	s_cmp_gt_u32 s58, 3
	s_mov_b64 s[14:15], s[10:11]
	s_barrier
	s_cbranch_scc0 .LBB0_2347
; #define PG8_WAIT_V(n) asm volatile("s_waitcnt vmcnt(" #n ")" ::: "memory")
; #define PG8_BAR __builtin_amdgcn_s_barrier()
; template <class Epi, class Sched>
; __device__ __forceinline__ void gemm_phase(LAS unsigned char* lds, const Gemm g, const Sched& S, const Epi& E) {
;     ...
;     E(acc, cur, wr, wc, fr, fq);
;     if (!has_next) break;
; #pragma unroll
;     for (int a = 0; a < 2; ++a)
; #pragma unroll
;       for (int b = 0; b < 2; ++b)
; #pragma unroll
;         for (int m = 0; m < 4; ++m)
; #pragma unroll
;           for (int n = 0; n < 2; ++n) acc[a][b][m][n] = (f32x4){0.f, 0.f, 0.f, 0.f};
;     cur = nxt; cA = nA; cB = nB; ++ui;
;   }
;   PG8_WAIT_V(0);
;   if (wr == 0) PG8_BAR;
;   PG8_BAR;
	v_lshl_or_b32 v142, s45, 8, v147
	v_and_b32_e32 v250, 16, v187
	v_lshrrev_b32_e32 v251, 2, v250
	v_sub_u32_e32 v250, v250, v251
	v_add_u32_e32 v142, v142, v250
	v_lshl_add_u32 v149, s48, 8, v145
	v_mov_b64_e32 v[140:141], s[12:13]
	v_ashrrev_i32_e32 v143, 31, v142
	v_mad_i64_i32 v[150:151], s[10:11], v149, s40, v[140:141]
	v_lshlrev_b64 v[142:143], 1, v[142:143]
	v_lshl_add_u64 v[150:151], v[150:151], 0, v[142:143]
	v_cvt_pk_bf16_f32 v242, v124, v125
	v_cvt_pk_bf16_f32 v243, v126, v127
	v_cvt_pk_bf16_f32 v244, v120, v121
	v_cvt_pk_bf16_f32 v245, v122, v123
	s_nop 1
	v_permlane16_swap_b32_e32 v242, v244
	v_permlane16_swap_b32_e32 v243, v245
	global_store_dwordx4 v[150:151], v[242:245], off
	v_cvt_pk_bf16_f32 v246, v112, v113
	v_cvt_pk_bf16_f32 v247, v114, v115
	v_cvt_pk_bf16_f32 v248, v104, v105
	v_cvt_pk_bf16_f32 v249, v106, v107
	s_nop 1
	v_permlane16_swap_b32_e32 v246, v248
	v_permlane16_swap_b32_e32 v247, v249
	global_store_dwordx4 v[150:151], v[246:249], off offset:256
	v_or_b32_e32 v104, 16, v149
	v_mad_i64_i32 v[104:105], s[10:11], v104, s40, v[140:141]
	v_lshl_add_u64 v[104:105], v[104:105], 0, v[142:143]
	v_cvt_pk_bf16_f32 v242, v116, v117
	v_cvt_pk_bf16_f32 v243, v118, v119
	v_cvt_pk_bf16_f32 v244, v108, v109
	v_cvt_pk_bf16_f32 v245, v110, v111
	s_nop 1
	v_permlane16_swap_b32_e32 v242, v244
	v_permlane16_swap_b32_e32 v243, v245
	global_store_dwordx4 v[104:105], v[242:245], off
	v_cvt_pk_bf16_f32 v246, v96, v97
	v_cvt_pk_bf16_f32 v247, v98, v99
	v_cvt_pk_bf16_f32 v248, v88, v89
	v_cvt_pk_bf16_f32 v249, v90, v91
	s_nop 1
	v_permlane16_swap_b32_e32 v246, v248
	v_permlane16_swap_b32_e32 v247, v249
	global_store_dwordx4 v[104:105], v[246:249], off offset:256
	v_or_b32_e32 v88, 32, v149
	v_mad_i64_i32 v[88:89], s[10:11], v88, s40, v[140:141]
	v_lshl_add_u64 v[88:89], v[88:89], 0, v[142:143]
	v_cvt_pk_bf16_f32 v242, v100, v101
	v_cvt_pk_bf16_f32 v243, v102, v103
	v_cvt_pk_bf16_f32 v244, v92, v93
	v_cvt_pk_bf16_f32 v245, v94, v95
	s_nop 1
	v_permlane16_swap_b32_e32 v242, v244
	v_permlane16_swap_b32_e32 v243, v245
	global_store_dwordx4 v[88:89], v[242:245], off
	v_cvt_pk_bf16_f32 v246, v80, v81
	v_cvt_pk_bf16_f32 v247, v82, v83
	v_cvt_pk_bf16_f32 v248, v72, v73
	v_cvt_pk_bf16_f32 v249, v74, v75
	s_nop 1
	v_permlane16_swap_b32_e32 v246, v248
	v_permlane16_swap_b32_e32 v247, v249
	global_store_dwordx4 v[88:89], v[246:249], off offset:256
	v_or_b32_e32 v72, 48, v149
	v_mad_i64_i32 v[72:73], s[10:11], v72, s40, v[140:141]
	v_lshl_add_u64 v[72:73], v[72:73], 0, v[142:143]
	v_cvt_pk_bf16_f32 v242, v84, v85
	v_cvt_pk_bf16_f32 v243, v86, v87
	v_cvt_pk_bf16_f32 v244, v76, v77
	v_cvt_pk_bf16_f32 v245, v78, v79
	s_nop 1
	v_permlane16_swap_b32_e32 v242, v244
	v_permlane16_swap_b32_e32 v243, v245
	global_store_dwordx4 v[72:73], v[242:245], off
	v_cvt_pk_bf16_f32 v246, v68, v69
	v_cvt_pk_bf16_f32 v247, v70, v71
	v_cvt_pk_bf16_f32 v248, v64, v65
	v_cvt_pk_bf16_f32 v249, v66, v67
	s_nop 1
	v_permlane16_swap_b32_e32 v246, v248
	v_permlane16_swap_b32_e32 v247, v249
	global_store_dwordx4 v[72:73], v[246:249], off offset:256
	v_add_u32_e32 v64, 0x80, v149
	v_mad_i64_i32 v[64:65], s[10:11], v64, s40, v[140:141]
	v_lshl_add_u64 v[64:65], v[64:65], 0, v[142:143]
	v_cvt_pk_bf16_f32 v242, v60, v61
	v_cvt_pk_bf16_f32 v243, v62, v63
	v_cvt_pk_bf16_f32 v244, v56, v57
	v_cvt_pk_bf16_f32 v245, v58, v59
	s_nop 1
	v_permlane16_swap_b32_e32 v242, v244
	v_permlane16_swap_b32_e32 v243, v245
	global_store_dwordx4 v[64:65], v[242:245], off
	v_cvt_pk_bf16_f32 v246, v48, v49
	v_cvt_pk_bf16_f32 v247, v50, v51
	v_cvt_pk_bf16_f32 v248, v40, v41
	v_cvt_pk_bf16_f32 v249, v42, v43
	s_nop 1
	v_permlane16_swap_b32_e32 v246, v248
	v_permlane16_swap_b32_e32 v247, v249
	global_store_dwordx4 v[64:65], v[246:249], off offset:256
	v_add_u32_e32 v40, 0x90, v149
	v_mad_i64_i32 v[40:41], s[10:11], v40, s40, v[140:141]
	v_lshl_add_u64 v[40:41], v[40:41], 0, v[142:143]
	v_cvt_pk_bf16_f32 v242, v52, v53
	v_cvt_pk_bf16_f32 v243, v54, v55
	v_cvt_pk_bf16_f32 v244, v44, v45
	v_cvt_pk_bf16_f32 v245, v46, v47
	s_nop 1
	v_permlane16_swap_b32_e32 v242, v244
	v_permlane16_swap_b32_e32 v243, v245
	global_store_dwordx4 v[40:41], v[242:245], off
	v_cvt_pk_bf16_f32 v246, v32, v33
	v_cvt_pk_bf16_f32 v247, v34, v35
	v_cvt_pk_bf16_f32 v248, v24, v25
	v_cvt_pk_bf16_f32 v249, v26, v27
	s_nop 1
	v_permlane16_swap_b32_e32 v246, v248
	v_permlane16_swap_b32_e32 v247, v249
	global_store_dwordx4 v[40:41], v[246:249], off offset:256
	v_add_u32_e32 v24, 0xa0, v149
	v_mad_i64_i32 v[24:25], s[10:11], v24, s40, v[140:141]
	v_lshl_add_u64 v[24:25], v[24:25], 0, v[142:143]
	v_cvt_pk_bf16_f32 v242, v36, v37
	v_cvt_pk_bf16_f32 v243, v38, v39
	v_cvt_pk_bf16_f32 v244, v28, v29
	v_cvt_pk_bf16_f32 v245, v30, v31
	s_nop 1
	v_permlane16_swap_b32_e32 v242, v244
	v_permlane16_swap_b32_e32 v243, v245
	global_store_dwordx4 v[24:25], v[242:245], off
	v_cvt_pk_bf16_f32 v246, v16, v17
	v_cvt_pk_bf16_f32 v247, v18, v19
	v_cvt_pk_bf16_f32 v248, v8, v9
	v_cvt_pk_bf16_f32 v249, v10, v11
	s_nop 1
	v_permlane16_swap_b32_e32 v246, v248
	v_permlane16_swap_b32_e32 v247, v249
	global_store_dwordx4 v[24:25], v[246:249], off offset:256
	v_add_u32_e32 v8, 0xb0, v149
	v_mad_i64_i32 v[8:9], s[10:11], v8, s40, v[140:141]
	v_lshl_add_u64 v[8:9], v[8:9], 0, v[142:143]
	v_cvt_pk_bf16_f32 v242, v20, v21
	v_cvt_pk_bf16_f32 v243, v22, v23
	s_and_b64 vcc, exec, s[6:7]
	s_mov_b32 s45, s39
	s_mov_b32 s48, s44
	s_mov_b64 s[16:17], s[8:9]
	s_mov_b64 s[14:15], s[4:5]
	s_movk_i32 s58, 0x6000
	s_movk_i32 s51, 0x4000
	v_cvt_pk_bf16_f32 v244, v12, v13
	v_cvt_pk_bf16_f32 v245, v14, v15
	s_nop 1
	v_permlane16_swap_b32_e32 v242, v244
	v_permlane16_swap_b32_e32 v243, v245
	global_store_dwordx4 v[8:9], v[242:245], off
	v_cvt_pk_bf16_f32 v246, v4, v5
	v_cvt_pk_bf16_f32 v247, v6, v7
	v_cvt_pk_bf16_f32 v248, v0, v1
	v_cvt_pk_bf16_f32 v249, v2, v3
	s_nop 1
	v_permlane16_swap_b32_e32 v246, v248
	v_permlane16_swap_b32_e32 v247, v249
	global_store_dwordx4 v[8:9], v[246:249], off offset:256
	s_cbranch_vccz .LBB0_2336
	s_waitcnt vmcnt(0)
	s_cmpk_gt_u32 s20, 0xff
	v_readlane_b32 s44, v255, 32
	v_readlane_b32 s45, v255, 33
	s_cbranch_scc1 .LBB0_2351
	s_barrier

; #define PG8_STAGE(bufoff, gbase, voff) do { _Pragma("unroll") for (int _i = 0; _i < 2; ++_i) \
;     __builtin_amdgcn_global_load_lds((const unsigned*)((const char*)(gbase) + (voff)[_i]), (LAS unsigned*)(lds + (bufoff) + ldsw + _i * 8192), 16, 0, 0); } while (0)
; #define PG8_LDA(dst, b, h) do { _Pragma("unroll") for (int m = 0; m < 4; ++m) _Pragma("unroll") for (int k = 0; k < 2; ++k) dst[m][k] = *(const LAS bf16x8*)(lds + PG8_SA(b, h) + aoff + m * 2048 + k * 1024); } while (0)
; #define PG8_LDB(dst, b, h) do { _Pragma("unroll") for (int n = 0; n < 2; ++n) _Pragma("unroll") for (int k = 0; k < 2; ++k) dst[n][k] = *(const LAS bf16x8*)(lds + PG8_SB(b, h) + boff + n * 2048 + k * 1024); } while (0)
; #define PG8_MMA(ai, bj, At, Bt) do { __builtin_amdgcn_s_setprio(1); _Pragma("unroll") for (int m = 0; m < 4; ++m) _Pragma("unroll") for (int n = 0; n < 2; ++n) _Pragma("unroll") for (int k = 0; k < 2; ++k) \
;     acc[ai][bj][m][n] = __builtin_amdgcn_mfma_f32_16x16x32_bf16(Bt[n][k], At[m][k], acc[ai][bj][m][n], 0, 0, 0); __builtin_amdgcn_s_setprio(0); } while (0)
; #define PG8_WAIT_L(n) asm volatile("s_waitcnt lgkmcnt(" #n ")" ::: "memory")
; #define PG8_BAR __builtin_amdgcn_s_barrier()
; #define PG8_SCHED __builtin_amdgcn_sched_barrier(0)
; template <class Epi, class Sched>
; __device__ __forceinline__ void gemm_phase(LAS unsigned char* lds, const Gemm g, const Sched& S, const Epi& E) {
;     ...
;     const char* nA = has_next ? (const char*)g.A + (size_t)nxt.pm * tstepA + (size_t)nxt.ko * 2 : cA; const char* nB = has_next ? (const char*)g.Bt + (size_t)nxt.pn * tstepB + (size_t)nxt.ko * 2 : cB;
;     for (int t = 0; t < nt; t += 2) {
;       const bool last = (t == nt - 2);
;       const char* a1 = cA + (size_t)(t + 1) * kstep;
;       const char* a2 = last ? nA : cA + (size_t)(t + 2) * kstep; const char* b2 = last ? nB : cB + (size_t)(t + 2) * kstep;
;       const char* a3 = a2 + kstep; const char* b3 = b2 + kstep;
;       PG8_LDB(B0, 0, 0); PG8_SCHED; PG8_LDA(At, 0, 0); PG8_STAGE(PG8_SA(1, 1), a1 + hstepA, voffA);
;       PG8_WAIT_L(8); PG8_BAR; PG8_WAIT_L(0); PG8_MMA(0, 0, At, B0); PG8_BAR; PG8_SCHED;
;       PG8_LDB(B1, 0, 1); PG8_STAGE(PG8_SB(0, 0), b2, voffB);
;       PG8_BAR; PG8_WAIT_L(0); PG8_MMA(0, 1, At, B1); PG8_BAR;
;       PG8_LDA(At, 0, 1); PG8_STAGE(PG8_SA(0, 0), a2, voffA);
;       PG8_BAR; PG8_WAIT_L(0); PG8_MMA(1, 0, At, B0); PG8_BAR; PG8_SCHED;
.LBB0_2365:
	s_add_u32 s23, s18, s22
	s_addc_u32 s36, s19, 0
	s_add_u32 s28, s23, 0x100
	s_addc_u32 s29, s36, 0
	s_and_b64 s[26:27], s[20:21], exec
	s_cselect_b32 s29, s11, s29
	s_cselect_b32 s28, s10, s28
	s_add_u32 s22, s14, s22
	s_addc_u32 s26, s15, 0
	s_add_u32 s22, s22, 0x100
	s_addc_u32 s26, s26, 0
	s_add_i32 s37, 16, 0x10000
	s_and_b64 s[20:21], s[20:21], exec
	s_cselect_b32 s39, s5, s26
	s_cselect_b32 s38, s83, s22
	s_add_u32 s48, s23, 0x30080
	s_addc_u32 s49, s36, 0
	s_add_i32 vcc_lo, s37, s58
	s_add_i32 m0, s59, 0xc000
	s_add_i32 s36, s59, 0xe000
	s_add_i32 s95, 16, 0x14000
	s_add_i32 s94, vcc_lo, 0x2000
	s_add_u32 s26, s38, 0x10000
	v_add_u32_e32 v145, s37, v141
	s_addc_u32 s27, s39, 0
	s_add_i32 s89, s95, s58
	ds_read_b128 v[136:139], v145
	ds_read_b128 v[146:149], v145 offset:1024
	ds_read_b128 v[150:153], v145 offset:2048
	ds_read_b128 v[154:157], v145 offset:3072
	s_add_i32 s88, s89, 0x2000
	s_add_i32 s87, 16, 0x18000
	s_add_u32 s22, s28, 0x30000
	s_addc_u32 s23, s29, 0
	s_add_i32 s86, s87, s58
	s_add_i32 s85, 16, 0x1c000
	s_add_i32 s84, s86, 0x2000
	s_add_u32 s20, s38, 0x10080
	s_addc_u32 s21, s39, 0
	s_add_i32 s91, s85, s58
	s_add_i32 s90, s91, 0x2000
	v_lshl_add_u64 v[214:215], s[48:49], 0, v[134:135]
	ds_read_b128 v[158:161], v143
	ds_read_b128 v[162:165], v143 offset:1024
	ds_read_b128 v[166:169], v143 offset:2048
	ds_read_b128 v[170:173], v143 offset:3072
	ds_read_b128 v[174:177], v143 offset:4096
	ds_read_b128 v[178:181], v143 offset:5120
	ds_read_b128 v[182:185], v143 offset:6144
	ds_read_b128 v[198:201], v143 offset:7168
	global_load_lds_dwordx4 v[214:215], off
	v_lshl_add_u64 v[214:215], s[48:49], 0, v[130:131]
	s_mov_b32 m0, s36
	s_nop 0
	global_load_lds_dwordx4 v[214:215], off
	s_waitcnt lgkmcnt(8)
	s_barrier
	s_waitcnt lgkmcnt(0)
	s_waitcnt lgkmcnt(0)
	v_mfma_f32_16x16x32_bf16 v[124:127], v[136:139], v[158:161], v[124:127]
	v_mfma_f32_16x16x32_bf16 v[120:123], v[150:153], v[158:161], v[120:123]
	v_mfma_f32_16x16x32_bf16 v[116:119], v[136:139], v[166:169], v[116:119]
	v_mfma_f32_16x16x32_bf16 v[108:111], v[150:153], v[166:169], v[108:111]
	v_mfma_f32_16x16x32_bf16 v[100:103], v[136:139], v[174:177], v[100:103]
	v_mfma_f32_16x16x32_bf16 v[92:95], v[150:153], v[174:177], v[92:95]
	v_mfma_f32_16x16x32_bf16 v[84:87], v[136:139], v[182:185], v[84:87]
	v_mfma_f32_16x16x32_bf16 v[76:79], v[150:153], v[182:185], v[76:79]
	v_mfma_f32_16x16x32_bf16 v[124:127], v[146:149], v[162:165], v[124:127]
	v_mfma_f32_16x16x32_bf16 v[120:123], v[154:157], v[162:165], v[120:123]
	v_mfma_f32_16x16x32_bf16 v[116:119], v[146:149], v[170:173], v[116:119]
	v_mfma_f32_16x16x32_bf16 v[108:111], v[154:157], v[170:173], v[108:111]
	v_mfma_f32_16x16x32_bf16 v[100:103], v[146:149], v[178:181], v[100:103]
	v_mfma_f32_16x16x32_bf16 v[92:95], v[154:157], v[178:181], v[92:95]
	v_mfma_f32_16x16x32_bf16 v[84:87], v[146:149], v[198:201], v[84:87]
	v_mfma_f32_16x16x32_bf16 v[76:79], v[154:157], v[198:201], v[76:79]
	s_barrier
	s_mov_b32 m0, vcc_lo
	v_add_u32_e32 v145, s95, v141
	v_lshl_add_u64 v[230:231], s[38:39], 0, v[132:133]
	ds_read_b128 v[214:217], v145
	ds_read_b128 v[218:221], v145 offset:1024
	ds_read_b128 v[222:225], v145 offset:2048
	ds_read_b128 v[226:229], v145 offset:3072
	global_load_lds_dwordx4 v[230:231], off
	v_lshl_add_u64 v[232:233], s[38:39], 0, v[128:129]
	s_mov_b32 m0, s94
	s_nop 0
	global_load_lds_dwordx4 v[232:233], off
	s_barrier
	s_waitcnt lgkmcnt(0)
	s_waitcnt lgkmcnt(0)
	v_mfma_f32_16x16x32_bf16 v[112:115], v[214:217], v[158:161], v[112:115]
	v_mfma_f32_16x16x32_bf16 v[104:107], v[222:225], v[158:161], v[104:107]
	v_mfma_f32_16x16x32_bf16 v[96:99], v[214:217], v[166:169], v[96:99]
	v_mfma_f32_16x16x32_bf16 v[88:91], v[222:225], v[166:169], v[88:91]
	v_mfma_f32_16x16x32_bf16 v[80:83], v[214:217], v[174:177], v[80:83]
	v_mfma_f32_16x16x32_bf16 v[72:75], v[222:225], v[174:177], v[72:75]
	v_mfma_f32_16x16x32_bf16 v[68:71], v[214:217], v[182:185], v[68:71]
	v_mfma_f32_16x16x32_bf16 v[64:67], v[222:225], v[182:185], v[64:67]
	v_mfma_f32_16x16x32_bf16 v[112:115], v[218:221], v[162:165], v[112:115]
	v_mfma_f32_16x16x32_bf16 v[104:107], v[226:229], v[162:165], v[104:107]
	v_mfma_f32_16x16x32_bf16 v[96:99], v[218:221], v[170:173], v[96:99]
	v_mfma_f32_16x16x32_bf16 v[88:91], v[226:229], v[170:173], v[88:91]
	v_mfma_f32_16x16x32_bf16 v[80:83], v[218:221], v[178:181], v[80:83]
	v_mfma_f32_16x16x32_bf16 v[72:75], v[226:229], v[178:181], v[72:75]
	v_mfma_f32_16x16x32_bf16 v[68:71], v[218:221], v[198:201], v[68:71]
	v_mfma_f32_16x16x32_bf16 v[64:67], v[226:229], v[198:201], v[64:67]
	s_mov_b32 m0, s59
	v_lshl_add_u64 v[234:235], s[28:29], 0, v[134:135]
	s_barrier
	ds_read_b128 v[158:161], v143 offset:16384
	ds_read_b128 v[162:165], v143 offset:17408
	ds_read_b128 v[166:169], v143 offset:18432
	ds_read_b128 v[170:173], v143 offset:19456
	ds_read_b128 v[174:177], v143 offset:20480
	ds_read_b128 v[178:181], v143 offset:21504
	ds_read_b128 v[182:185], v143 offset:22528
	ds_read_b128 v[198:201], v143 offset:23552
	global_load_lds_dwordx4 v[234:235], off
	v_lshl_add_u64 v[236:237], s[28:29], 0, v[130:131]
	s_mov_b32 m0, s66
	s_nop 0
	global_load_lds_dwordx4 v[236:237], off
	s_barrier
; #define PG8_STAGE(bufoff, gbase, voff) do { _Pragma("unroll") for (int _i = 0; _i < 2; ++_i) \
;     __builtin_amdgcn_global_load_lds((const unsigned*)((const char*)(gbase) + (voff)[_i]), (LAS unsigned*)(lds + (bufoff) + ldsw + _i * 8192), 16, 0, 0); } while (0)
; #define PG8_LDA(dst, b, h) do { _Pragma("unroll") for (int m = 0; m < 4; ++m) _Pragma("unroll") for (int k = 0; k < 2; ++k) dst[m][k] = *(const LAS bf16x8*)(lds + PG8_SA(b, h) + aoff + m * 2048 + k * 1024); } while (0)
; #define PG8_LDB(dst, b, h) do { _Pragma("unroll") for (int n = 0; n < 2; ++n) _Pragma("unroll") for (int k = 0; k < 2; ++k) dst[n][k] = *(const LAS bf16x8*)(lds + PG8_SB(b, h) + boff + n * 2048 + k * 1024); } while (0)
; #define PG8_BAR __builtin_amdgcn_s_barrier()
; template <class Epi, class Sched>
; __device__ __forceinline__ void gemm_phase(LAS unsigned char* lds, const Gemm g, const Sched& S, const Epi& E) {
;     ...
;     for (int t = 0; t < nt; t += 2) {
;       const bool last = (t == nt - 2);
;       const char* a1 = cA + (size_t)(t + 1) * kstep;
;       const char* a2 = last ? nA : cA + (size_t)(t + 2) * kstep; const char* b2 = last ? nB : cB + (size_t)(t + 2) * kstep;
;       const char* a3 = a2 + kstep; const char* b3 = b2 + kstep;
;       PG8_LDB(B0, 0, 0); PG8_SCHED; PG8_LDA(At, 0, 0); PG8_STAGE(PG8_SA(1, 1), a1 + hstepA, voffA);
;       PG8_WAIT_L(8); PG8_BAR; PG8_WAIT_L(0); PG8_MMA(0, 0, At, B0); PG8_BAR; PG8_SCHED;
;       PG8_LDB(B1, 0, 1); PG8_STAGE(PG8_SB(0, 0), b2, voffB);
;       PG8_BAR; PG8_WAIT_L(0); PG8_MMA(0, 1, At, B1); PG8_BAR;
;       PG8_LDA(At, 0, 1); PG8_STAGE(PG8_SA(0, 0), a2, voffA);
;       PG8_BAR; PG8_WAIT_L(0); PG8_MMA(1, 0, At, B0); PG8_BAR; PG8_SCHED;
;       PG8_STAGE(PG8_SB(0, 1), b2 + hstepB, voffB);
;       PG8_WAIT_V(6); PG8_BAR; PG8_MMA(1, 1, At, B1); PG8_BAR;
;       PG8_LDB(B0, 1, 0); PG8_SCHED; PG8_LDA(At, 1, 0); PG8_STAGE(PG8_SA(0, 1), a2 + hstepA, voffA);
;       PG8_WAIT_L(8); PG8_BAR; PG8_WAIT_L(0); PG8_MMA(0, 0, At, B0); PG8_BAR; PG8_SCHED;
;       PG8_LDB(B1, 1, 1); PG8_STAGE(PG8_SB(1, 0), b3, voffB);
;       PG8_BAR; PG8_WAIT_L(0); PG8_MMA(0, 1, At, B1); PG8_BAR;
;       PG8_LDA(At, 1, 1); PG8_STAGE(PG8_SA(1, 0), a3, voffA);
;       PG8_BAR; PG8_WAIT_L(0); PG8_MMA(1, 0, At, B0); PG8_BAR; PG8_SCHED;
;       PG8_STAGE(PG8_SB(1, 1), b3 + hstepB, voffB);
;       PG8_WAIT_V(6); PG8_BAR; PG8_MMA(1, 1, At, B1); PG8_BAR;
;     }
	s_waitcnt lgkmcnt(0)
	s_waitcnt lgkmcnt(0)
	v_mfma_f32_16x16x32_bf16 v[60:63], v[136:139], v[158:161], v[60:63]
	v_mfma_f32_16x16x32_bf16 v[56:59], v[150:153], v[158:161], v[56:59]
	v_mfma_f32_16x16x32_bf16 v[52:55], v[136:139], v[166:169], v[52:55]
	v_mfma_f32_16x16x32_bf16 v[44:47], v[150:153], v[166:169], v[44:47]
	v_mfma_f32_16x16x32_bf16 v[36:39], v[136:139], v[174:177], v[36:39]
	v_mfma_f32_16x16x32_bf16 v[28:31], v[150:153], v[174:177], v[28:31]
	v_mfma_f32_16x16x32_bf16 v[20:23], v[136:139], v[182:185], v[20:23]
	v_mfma_f32_16x16x32_bf16 v[12:15], v[150:153], v[182:185], v[12:15]
	v_mfma_f32_16x16x32_bf16 v[60:63], v[146:149], v[162:165], v[60:63]
	v_mfma_f32_16x16x32_bf16 v[56:59], v[154:157], v[162:165], v[56:59]
	v_mfma_f32_16x16x32_bf16 v[52:55], v[146:149], v[170:173], v[52:55]
	v_mfma_f32_16x16x32_bf16 v[44:47], v[154:157], v[170:173], v[44:47]
	v_mfma_f32_16x16x32_bf16 v[36:39], v[146:149], v[178:181], v[36:39]
	v_mfma_f32_16x16x32_bf16 v[28:31], v[154:157], v[178:181], v[28:31]
	v_mfma_f32_16x16x32_bf16 v[20:23], v[146:149], v[198:201], v[20:23]
	v_mfma_f32_16x16x32_bf16 v[12:15], v[154:157], v[198:201], v[12:15]
	s_barrier
	s_mov_b32 m0, s89
	v_lshl_add_u64 v[136:137], s[26:27], 0, v[132:133]
	global_load_lds_dwordx4 v[136:137], off
	v_lshl_add_u64 v[136:137], s[26:27], 0, v[128:129]
	s_mov_b32 m0, s88
	s_nop 0
	global_load_lds_dwordx4 v[136:137], off
	s_waitcnt vmcnt(6)
	s_barrier
	v_mfma_f32_16x16x32_bf16 v[48:51], v[214:217], v[158:161], v[48:51]
	v_mfma_f32_16x16x32_bf16 v[40:43], v[222:225], v[158:161], v[40:43]
	v_mfma_f32_16x16x32_bf16 v[32:35], v[214:217], v[166:169], v[32:35]
	v_mfma_f32_16x16x32_bf16 v[24:27], v[222:225], v[166:169], v[24:27]
	v_mfma_f32_16x16x32_bf16 v[16:19], v[214:217], v[174:177], v[16:19]
	v_mfma_f32_16x16x32_bf16 v[8:11], v[222:225], v[174:177], v[8:11]
	v_mfma_f32_16x16x32_bf16 v[4:7], v[214:217], v[182:185], v[4:7]
	v_mfma_f32_16x16x32_bf16 v[0:3], v[222:225], v[182:185], v[0:3]
	v_mfma_f32_16x16x32_bf16 v[48:51], v[218:221], v[162:165], v[48:51]
	v_mfma_f32_16x16x32_bf16 v[40:43], v[226:229], v[162:165], v[40:43]
	v_mfma_f32_16x16x32_bf16 v[32:35], v[218:221], v[170:173], v[32:35]
	v_mfma_f32_16x16x32_bf16 v[24:27], v[226:229], v[170:173], v[24:27]
	v_mfma_f32_16x16x32_bf16 v[16:19], v[218:221], v[178:181], v[16:19]
	v_mfma_f32_16x16x32_bf16 v[8:11], v[226:229], v[178:181], v[8:11]
	v_mfma_f32_16x16x32_bf16 v[4:7], v[218:221], v[198:201], v[4:7]
	v_mfma_f32_16x16x32_bf16 v[0:3], v[226:229], v[198:201], v[0:3]
	v_add_u32_e32 v145, s87, v141
	s_barrier
	ds_read_b128 v[136:139], v145
	ds_read_b128 v[146:149], v145 offset:1024
	ds_read_b128 v[150:153], v145 offset:2048
	ds_read_b128 v[154:157], v145 offset:3072
	s_mov_b32 m0, s67
	v_lshl_add_u64 v[214:215], s[22:23], 0, v[134:135]
	ds_read_b128 v[158:161], v143 offset:32768
	ds_read_b128 v[162:165], v143 offset:33792
	ds_read_b128 v[166:169], v143 offset:34816
	ds_read_b128 v[170:173], v143 offset:35840
	ds_read_b128 v[174:177], v143 offset:36864
	ds_read_b128 v[178:181], v143 offset:37888
	ds_read_b128 v[182:185], v143 offset:38912
	ds_read_b128 v[198:201], v143 offset:39936
	global_load_lds_dwordx4 v[214:215], off
	v_lshl_add_u64 v[214:215], s[22:23], 0, v[130:131]
	s_mov_b32 m0, s68
	s_nop 0
	global_load_lds_dwordx4 v[214:215], off
	s_waitcnt lgkmcnt(8)
	s_barrier
	s_waitcnt lgkmcnt(0)
	s_waitcnt lgkmcnt(0)
	v_mfma_f32_16x16x32_bf16 v[124:127], v[136:139], v[158:161], v[124:127]
	v_mfma_f32_16x16x32_bf16 v[120:123], v[150:153], v[158:161], v[120:123]
	v_mfma_f32_16x16x32_bf16 v[116:119], v[136:139], v[166:169], v[116:119]
	v_mfma_f32_16x16x32_bf16 v[108:111], v[150:153], v[166:169], v[108:111]
	v_mfma_f32_16x16x32_bf16 v[100:103], v[136:139], v[174:177], v[100:103]
	v_mfma_f32_16x16x32_bf16 v[92:95], v[150:153], v[174:177], v[92:95]
	v_mfma_f32_16x16x32_bf16 v[84:87], v[136:139], v[182:185], v[84:87]
	v_mfma_f32_16x16x32_bf16 v[76:79], v[150:153], v[182:185], v[76:79]
	v_mfma_f32_16x16x32_bf16 v[124:127], v[146:149], v[162:165], v[124:127]
	v_mfma_f32_16x16x32_bf16 v[120:123], v[154:157], v[162:165], v[120:123]
	v_mfma_f32_16x16x32_bf16 v[116:119], v[146:149], v[170:173], v[116:119]
	v_mfma_f32_16x16x32_bf16 v[108:111], v[154:157], v[170:173], v[108:111]
	v_mfma_f32_16x16x32_bf16 v[100:103], v[146:149], v[178:181], v[100:103]
	v_mfma_f32_16x16x32_bf16 v[92:95], v[154:157], v[178:181], v[92:95]
	v_mfma_f32_16x16x32_bf16 v[84:87], v[146:149], v[198:201], v[84:87]
	v_mfma_f32_16x16x32_bf16 v[76:79], v[154:157], v[198:201], v[76:79]
	s_barrier
	s_mov_b32 m0, s86
	v_add_u32_e32 v145, s85, v141
	v_lshl_add_u64 v[230:231], v[230:231], 0, s[62:63]
	ds_read_b128 v[214:217], v145
	ds_read_b128 v[218:221], v145 offset:1024
	ds_read_b128 v[222:225], v145 offset:2048
	ds_read_b128 v[226:229], v145 offset:3072
	global_load_lds_dwordx4 v[230:231], off
	v_lshl_add_u64 v[230:231], v[232:233], 0, s[62:63]
	s_mov_b32 m0, s84
	s_nop 0
	global_load_lds_dwordx4 v[230:231], off
	s_barrier
	s_waitcnt lgkmcnt(0)
	s_waitcnt lgkmcnt(0)
	v_mfma_f32_16x16x32_bf16 v[112:115], v[214:217], v[158:161], v[112:115]
	v_mfma_f32_16x16x32_bf16 v[104:107], v[222:225], v[158:161], v[104:107]
	v_mfma_f32_16x16x32_bf16 v[96:99], v[214:217], v[166:169], v[96:99]
	v_mfma_f32_16x16x32_bf16 v[88:91], v[222:225], v[166:169], v[88:91]
	v_mfma_f32_16x16x32_bf16 v[80:83], v[214:217], v[174:177], v[80:83]
	v_mfma_f32_16x16x32_bf16 v[72:75], v[222:225], v[174:177], v[72:75]
	v_mfma_f32_16x16x32_bf16 v[68:71], v[214:217], v[182:185], v[68:71]
	v_mfma_f32_16x16x32_bf16 v[64:67], v[222:225], v[182:185], v[64:67]
	v_mfma_f32_16x16x32_bf16 v[112:115], v[218:221], v[162:165], v[112:115]
	v_mfma_f32_16x16x32_bf16 v[104:107], v[226:229], v[162:165], v[104:107]
	v_mfma_f32_16x16x32_bf16 v[96:99], v[218:221], v[170:173], v[96:99]
	v_mfma_f32_16x16x32_bf16 v[88:91], v[226:229], v[170:173], v[88:91]
	v_mfma_f32_16x16x32_bf16 v[80:83], v[218:221], v[178:181], v[80:83]
	v_mfma_f32_16x16x32_bf16 v[72:75], v[226:229], v[178:181], v[72:75]
	v_mfma_f32_16x16x32_bf16 v[68:71], v[218:221], v[198:201], v[68:71]
	v_mfma_f32_16x16x32_bf16 v[64:67], v[226:229], v[198:201], v[64:67]
	s_mov_b32 m0, s69
	v_lshl_add_u64 v[230:231], v[234:235], 0, s[62:63]
	s_barrier
; #define PG8_STAGE(bufoff, gbase, voff) do { _Pragma("unroll") for (int _i = 0; _i < 2; ++_i) \
;     __builtin_amdgcn_global_load_lds((const unsigned*)((const char*)(gbase) + (voff)[_i]), (LAS unsigned*)(lds + (bufoff) + ldsw + _i * 8192), 16, 0, 0); } while (0)
; #define PG8_LDA(dst, b, h) do { _Pragma("unroll") for (int m = 0; m < 4; ++m) _Pragma("unroll") for (int k = 0; k < 2; ++k) dst[m][k] = *(const LAS bf16x8*)(lds + PG8_SA(b, h) + aoff + m * 2048 + k * 1024); } while (0)
; #define PG8_LDB(dst, b, h) do { _Pragma("unroll") for (int n = 0; n < 2; ++n) _Pragma("unroll") for (int k = 0; k < 2; ++k) dst[n][k] = *(const LAS bf16x8*)(lds + PG8_SB(b, h) + boff + n * 2048 + k * 1024); } while (0)
; #define PG8_BAR __builtin_amdgcn_s_barrier()
; template <class Epi, class Sched>
; __device__ __forceinline__ void gemm_phase(LAS unsigned char* lds, const Gemm g, const Sched& S, const Epi& E) {
;     ...
;     for (int t = 0; t < nt; t += 2) {
;       const bool last = (t == nt - 2);
;       const char* a1 = cA + (size_t)(t + 1) * kstep;
;       const char* a2 = last ? nA : cA + (size_t)(t + 2) * kstep; const char* b2 = last ? nB : cB + (size_t)(t + 2) * kstep;
;       const char* a3 = a2 + kstep; const char* b3 = b2 + kstep;
;       PG8_LDB(B0, 0, 0); PG8_SCHED; PG8_LDA(At, 0, 0); PG8_STAGE(PG8_SA(1, 1), a1 + hstepA, voffA);
;       PG8_WAIT_L(8); PG8_BAR; PG8_WAIT_L(0); PG8_MMA(0, 0, At, B0); PG8_BAR; PG8_SCHED;
;       PG8_LDB(B1, 0, 1); PG8_STAGE(PG8_SB(0, 0), b2, voffB);
;       PG8_BAR; PG8_WAIT_L(0); PG8_MMA(0, 1, At, B1); PG8_BAR;
;       PG8_LDA(At, 0, 1); PG8_STAGE(PG8_SA(0, 0), a2, voffA);
;       PG8_BAR; PG8_WAIT_L(0); PG8_MMA(1, 0, At, B0); PG8_BAR; PG8_SCHED;
;       PG8_STAGE(PG8_SB(0, 1), b2 + hstepB, voffB);
;       PG8_WAIT_V(6); PG8_BAR; PG8_MMA(1, 1, At, B1); PG8_BAR;
;       PG8_LDB(B0, 1, 0); PG8_SCHED; PG8_LDA(At, 1, 0); PG8_STAGE(PG8_SA(0, 1), a2 + hstepA, voffA);
;       PG8_WAIT_L(8); PG8_BAR; PG8_WAIT_L(0); PG8_MMA(0, 0, At, B0); PG8_BAR; PG8_SCHED;
;       PG8_LDB(B1, 1, 1); PG8_STAGE(PG8_SB(1, 0), b3, voffB);
;       PG8_BAR; PG8_WAIT_L(0); PG8_MMA(0, 1, At, B1); PG8_BAR;
;       PG8_LDA(At, 1, 1); PG8_STAGE(PG8_SA(1, 0), a3, voffA);
;       PG8_BAR; PG8_WAIT_L(0); PG8_MMA(1, 0, At, B0); PG8_BAR; PG8_SCHED;
;       PG8_STAGE(PG8_SB(1, 1), b3 + hstepB, voffB);
;       PG8_WAIT_V(6); PG8_BAR; PG8_MMA(1, 1, At, B1); PG8_BAR;
;     }
	ds_read_b128 v[158:161], v143 offset:49152
	ds_read_b128 v[162:165], v143 offset:50176
	ds_read_b128 v[166:169], v143 offset:51200
	ds_read_b128 v[170:173], v143 offset:52224
	ds_read_b128 v[174:177], v143 offset:53248
	ds_read_b128 v[178:181], v143 offset:54272
	ds_read_b128 v[182:185], v143 offset:55296
	ds_read_b128 v[198:201], v143 offset:56320
	global_load_lds_dwordx4 v[230:231], off
	v_lshl_add_u64 v[230:231], v[236:237], 0, s[62:63]
	s_mov_b32 m0, s74
	s_nop 0
	global_load_lds_dwordx4 v[230:231], off
	s_barrier
	s_waitcnt lgkmcnt(0)
	s_waitcnt lgkmcnt(0)
	v_mfma_f32_16x16x32_bf16 v[60:63], v[136:139], v[158:161], v[60:63]
	v_mfma_f32_16x16x32_bf16 v[56:59], v[150:153], v[158:161], v[56:59]
	v_mfma_f32_16x16x32_bf16 v[52:55], v[136:139], v[166:169], v[52:55]
	v_mfma_f32_16x16x32_bf16 v[44:47], v[150:153], v[166:169], v[44:47]
	v_mfma_f32_16x16x32_bf16 v[36:39], v[136:139], v[174:177], v[36:39]
	v_mfma_f32_16x16x32_bf16 v[28:31], v[150:153], v[174:177], v[28:31]
	v_mfma_f32_16x16x32_bf16 v[20:23], v[136:139], v[182:185], v[20:23]
	v_mfma_f32_16x16x32_bf16 v[12:15], v[150:153], v[182:185], v[12:15]
	v_mfma_f32_16x16x32_bf16 v[60:63], v[146:149], v[162:165], v[60:63]
	v_mfma_f32_16x16x32_bf16 v[56:59], v[154:157], v[162:165], v[56:59]
	v_mfma_f32_16x16x32_bf16 v[52:55], v[146:149], v[170:173], v[52:55]
	v_mfma_f32_16x16x32_bf16 v[44:47], v[154:157], v[170:173], v[44:47]
	v_mfma_f32_16x16x32_bf16 v[36:39], v[146:149], v[178:181], v[36:39]
	v_mfma_f32_16x16x32_bf16 v[28:31], v[154:157], v[178:181], v[28:31]
	v_mfma_f32_16x16x32_bf16 v[20:23], v[146:149], v[198:201], v[20:23]
	v_mfma_f32_16x16x32_bf16 v[12:15], v[154:157], v[198:201], v[12:15]
	s_barrier
	s_mov_b32 m0, s91
	v_lshl_add_u64 v[136:137], s[20:21], 0, v[132:133]
	global_load_lds_dwordx4 v[136:137], off
	v_lshl_add_u64 v[136:137], s[20:21], 0, v[128:129]
	s_mov_b32 m0, s90
	s_nop 0
	global_load_lds_dwordx4 v[136:137], off
	s_waitcnt vmcnt(6)
	s_barrier
	v_mfma_f32_16x16x32_bf16 v[48:51], v[214:217], v[158:161], v[48:51]
	v_mfma_f32_16x16x32_bf16 v[40:43], v[222:225], v[158:161], v[40:43]
	v_mfma_f32_16x16x32_bf16 v[32:35], v[214:217], v[166:169], v[32:35]
	v_mfma_f32_16x16x32_bf16 v[24:27], v[222:225], v[166:169], v[24:27]
	v_mfma_f32_16x16x32_bf16 v[16:19], v[214:217], v[174:177], v[16:19]
	v_mfma_f32_16x16x32_bf16 v[8:11], v[222:225], v[174:177], v[8:11]
	v_mfma_f32_16x16x32_bf16 v[4:7], v[214:217], v[182:185], v[4:7]
	v_mfma_f32_16x16x32_bf16 v[0:3], v[222:225], v[182:185], v[0:3]
	v_mfma_f32_16x16x32_bf16 v[48:51], v[218:221], v[162:165], v[48:51]
	v_mfma_f32_16x16x32_bf16 v[40:43], v[226:229], v[162:165], v[40:43]
	v_mfma_f32_16x16x32_bf16 v[32:35], v[218:221], v[170:173], v[32:35]
	v_mfma_f32_16x16x32_bf16 v[24:27], v[226:229], v[170:173], v[24:27]
	v_mfma_f32_16x16x32_bf16 v[16:19], v[218:221], v[178:181], v[16:19]
	v_mfma_f32_16x16x32_bf16 v[8:11], v[226:229], v[178:181], v[8:11]
	v_mfma_f32_16x16x32_bf16 v[4:7], v[218:221], v[198:201], v[4:7]
	v_mfma_f32_16x16x32_bf16 v[0:3], v[226:229], v[198:201], v[0:3]
	s_movk_i32 s22, 0x100
	s_andn2_b64 vcc, exec, s[8:9]
	s_mov_b64 s[20:21], -1
	s_mov_b64 s[8:9], 0
	s_barrier
	s_cbranch_vccz .LBB0_2365
; #define PG8_WAIT_V(n) asm volatile("s_waitcnt vmcnt(" #n ")" ::: "memory")
; #define PG8_BAR __builtin_amdgcn_s_barrier()
; template <class Epi, class Sched>
; __device__ __forceinline__ void gemm_phase(LAS unsigned char* lds, const Gemm g, const Sched& S, const Epi& E) {
;     ...
;     E(acc, cur, wr, wc, fr, fq);
;     if (!has_next) break;
; #pragma unroll
;     for (int a = 0; a < 2; ++a)
; #pragma unroll
;       for (int b = 0; b < 2; ++b)
; #pragma unroll
;         for (int m = 0; m < 4; ++m)
; #pragma unroll
;           for (int n = 0; n < 2; ++n) acc[a][b][m][n] = (f32x4){0.f, 0.f, 0.f, 0.f};
;     cur = nxt; cA = nA; cB = nB; ++ui;
;   }
;   PG8_WAIT_V(0);
;   if (wr == 0) PG8_BAR;
;   PG8_BAR;
	v_lshl_or_b32 v138, s79, 8, v142
	v_and_b32_e32 v250, 16, v187
	v_lshrrev_b32_e32 v251, 2, v250
	v_sub_u32_e32 v250, v250, v251
	v_add_u32_e32 v138, v138, v250
	v_lshl_add_u32 v145, s82, 8, v140
	v_mov_b64_e32 v[136:137], s[12:13]
	v_ashrrev_i32_e32 v139, 31, v138
	v_mad_i64_i32 v[146:147], s[8:9], v145, s40, v[136:137]
	v_lshlrev_b64 v[138:139], 1, v[138:139]
	v_lshl_add_u64 v[146:147], v[146:147], 0, v[138:139]
	v_cvt_pk_bf16_f32 v242, v124, v125
	v_cvt_pk_bf16_f32 v243, v126, v127
	v_cvt_pk_bf16_f32 v244, v120, v121
	v_cvt_pk_bf16_f32 v245, v122, v123
	s_nop 1
	v_permlane16_swap_b32_e32 v242, v244
	v_permlane16_swap_b32_e32 v243, v245
	global_store_dwordx4 v[146:147], v[242:245], off offset:1536
	v_cvt_pk_bf16_f32 v246, v112, v113
	v_cvt_pk_bf16_f32 v247, v114, v115
	v_cvt_pk_bf16_f32 v248, v104, v105
	v_cvt_pk_bf16_f32 v249, v106, v107
	s_nop 1
	v_permlane16_swap_b32_e32 v246, v248
	v_permlane16_swap_b32_e32 v247, v249
	global_store_dwordx4 v[146:147], v[246:249], off offset:1792
	v_or_b32_e32 v104, 16, v145
	v_mad_i64_i32 v[104:105], s[8:9], v104, s40, v[136:137]
	v_lshl_add_u64 v[104:105], v[104:105], 0, v[138:139]
	v_cvt_pk_bf16_f32 v242, v116, v117
	v_cvt_pk_bf16_f32 v243, v118, v119
	v_cvt_pk_bf16_f32 v244, v108, v109
	v_cvt_pk_bf16_f32 v245, v110, v111
	s_nop 1
	v_permlane16_swap_b32_e32 v242, v244
	v_permlane16_swap_b32_e32 v243, v245
	global_store_dwordx4 v[104:105], v[242:245], off offset:1536
	v_cvt_pk_bf16_f32 v246, v96, v97
	v_cvt_pk_bf16_f32 v247, v98, v99
	v_cvt_pk_bf16_f32 v248, v88, v89
	v_cvt_pk_bf16_f32 v249, v90, v91
	s_nop 1
	v_permlane16_swap_b32_e32 v246, v248
	v_permlane16_swap_b32_e32 v247, v249
	global_store_dwordx4 v[104:105], v[246:249], off offset:1792
	v_or_b32_e32 v88, 32, v145
	v_mad_i64_i32 v[88:89], s[8:9], v88, s40, v[136:137]
	v_lshl_add_u64 v[88:89], v[88:89], 0, v[138:139]
	v_cvt_pk_bf16_f32 v242, v100, v101
	v_cvt_pk_bf16_f32 v243, v102, v103
	v_cvt_pk_bf16_f32 v244, v92, v93
	v_cvt_pk_bf16_f32 v245, v94, v95
	s_nop 1
	v_permlane16_swap_b32_e32 v242, v244
	v_permlane16_swap_b32_e32 v243, v245
	global_store_dwordx4 v[88:89], v[242:245], off offset:1536
	v_cvt_pk_bf16_f32 v246, v80, v81
	v_cvt_pk_bf16_f32 v247, v82, v83
	v_cvt_pk_bf16_f32 v248, v72, v73
	v_cvt_pk_bf16_f32 v249, v74, v75
	s_nop 1
	v_permlane16_swap_b32_e32 v246, v248
	v_permlane16_swap_b32_e32 v247, v249
	global_store_dwordx4 v[88:89], v[246:249], off offset:1792
	v_or_b32_e32 v72, 48, v145
	v_mad_i64_i32 v[72:73], s[8:9], v72, s40, v[136:137]
	v_lshl_add_u64 v[72:73], v[72:73], 0, v[138:139]
	v_cvt_pk_bf16_f32 v242, v84, v85
	v_cvt_pk_bf16_f32 v243, v86, v87
	v_cvt_pk_bf16_f32 v244, v76, v77
	v_cvt_pk_bf16_f32 v245, v78, v79
	s_nop 1
	v_permlane16_swap_b32_e32 v242, v244
	v_permlane16_swap_b32_e32 v243, v245
	global_store_dwordx4 v[72:73], v[242:245], off offset:1536
	v_cvt_pk_bf16_f32 v246, v68, v69
	v_cvt_pk_bf16_f32 v247, v70, v71
	v_cvt_pk_bf16_f32 v248, v64, v65
	v_cvt_pk_bf16_f32 v249, v66, v67
	s_nop 1
	v_permlane16_swap_b32_e32 v246, v248
	v_permlane16_swap_b32_e32 v247, v249
	global_store_dwordx4 v[72:73], v[246:249], off offset:1792
	v_add_u32_e32 v64, 0x80, v145
	v_mad_i64_i32 v[64:65], s[8:9], v64, s40, v[136:137]
	v_lshl_add_u64 v[64:65], v[64:65], 0, v[138:139]
	v_cvt_pk_bf16_f32 v242, v60, v61
	v_cvt_pk_bf16_f32 v243, v62, v63
	v_cvt_pk_bf16_f32 v244, v56, v57
	v_cvt_pk_bf16_f32 v245, v58, v59
	s_nop 1
	v_permlane16_swap_b32_e32 v242, v244
	v_permlane16_swap_b32_e32 v243, v245
	global_store_dwordx4 v[64:65], v[242:245], off offset:1536
	v_cvt_pk_bf16_f32 v246, v48, v49
	v_cvt_pk_bf16_f32 v247, v50, v51
	v_cvt_pk_bf16_f32 v248, v40, v41
	v_cvt_pk_bf16_f32 v249, v42, v43
	s_nop 1
	v_permlane16_swap_b32_e32 v246, v248
	v_permlane16_swap_b32_e32 v247, v249
	global_store_dwordx4 v[64:65], v[246:249], off offset:1792
	v_add_u32_e32 v40, 0x90, v145
	v_mad_i64_i32 v[40:41], s[8:9], v40, s40, v[136:137]
	v_lshl_add_u64 v[40:41], v[40:41], 0, v[138:139]
	v_cvt_pk_bf16_f32 v242, v52, v53
	v_cvt_pk_bf16_f32 v243, v54, v55
	v_cvt_pk_bf16_f32 v244, v44, v45
	v_cvt_pk_bf16_f32 v245, v46, v47
	s_nop 1
	v_permlane16_swap_b32_e32 v242, v244
	v_permlane16_swap_b32_e32 v243, v245
	global_store_dwordx4 v[40:41], v[242:245], off offset:1536
	v_cvt_pk_bf16_f32 v246, v32, v33
	v_cvt_pk_bf16_f32 v247, v34, v35
	v_cvt_pk_bf16_f32 v248, v24, v25
	v_cvt_pk_bf16_f32 v249, v26, v27
	s_nop 1
	v_permlane16_swap_b32_e32 v246, v248
	v_permlane16_swap_b32_e32 v247, v249
	global_store_dwordx4 v[40:41], v[246:249], off offset:1792
	v_add_u32_e32 v24, 0xa0, v145
	v_mad_i64_i32 v[24:25], s[8:9], v24, s40, v[136:137]
	v_lshl_add_u64 v[24:25], v[24:25], 0, v[138:139]
	v_cvt_pk_bf16_f32 v242, v36, v37
	v_cvt_pk_bf16_f32 v243, v38, v39
	v_cvt_pk_bf16_f32 v244, v28, v29
	v_cvt_pk_bf16_f32 v245, v30, v31
	s_nop 1
	v_permlane16_swap_b32_e32 v242, v244
	v_permlane16_swap_b32_e32 v243, v245
	global_store_dwordx4 v[24:25], v[242:245], off offset:1536
	v_cvt_pk_bf16_f32 v246, v16, v17
	v_cvt_pk_bf16_f32 v247, v18, v19
	v_cvt_pk_bf16_f32 v248, v8, v9
	v_cvt_pk_bf16_f32 v249, v10, v11
	s_nop 1
	v_permlane16_swap_b32_e32 v246, v248
	v_permlane16_swap_b32_e32 v247, v249
	global_store_dwordx4 v[24:25], v[246:249], off offset:1792
	v_add_u32_e32 v8, 0xb0, v145
	v_mad_i64_i32 v[8:9], s[8:9], v8, s40, v[136:137]
	v_lshl_add_u64 v[8:9], v[8:9], 0, v[138:139]
	v_cvt_pk_bf16_f32 v242, v20, v21
	v_cvt_pk_bf16_f32 v243, v22, v23
	s_and_b64 vcc, exec, s[6:7]
	s_mov_b32 s79, s4
	s_mov_b32 s82, s78
	s_mov_b64 s[14:15], s[16:17]
	s_mov_b64 s[18:19], s[10:11]
	s_movk_i32 s90, 0x300
	s_movk_i32 s94, 0x104
	s_movk_i32 s91, 0x60
	s_movk_i32 s95, 0xf8
	s_mov_b32 s88, 0x30000
	s_mov_b32 s89, 0xe000
	s_mov_b32 s87, 0x80000
	s_movk_i32 s86, 0x4100
	v_cvt_pk_bf16_f32 v244, v12, v13
	v_cvt_pk_bf16_f32 v245, v14, v15
	s_nop 1
	v_permlane16_swap_b32_e32 v242, v244
	v_permlane16_swap_b32_e32 v243, v245
	global_store_dwordx4 v[8:9], v[242:245], off offset:1536
	v_cvt_pk_bf16_f32 v246, v4, v5
	v_cvt_pk_bf16_f32 v247, v6, v7
	v_cvt_pk_bf16_f32 v248, v0, v1
	v_cvt_pk_bf16_f32 v249, v2, v3
	s_nop 1
	v_permlane16_swap_b32_e32 v246, v248
	v_permlane16_swap_b32_e32 v247, v249
	global_store_dwordx4 v[8:9], v[246:249], off offset:1792
	s_cbranch_vccz .LBB0_2356
	s_waitcnt vmcnt(0)
	s_cmpk_gt_u32 s24, 0xff
	s_mov_b32 s74, 0x8000
	s_mov_b32 s75, 0x10000
	s_movk_i32 s79, 0x40ff
	s_movk_i32 s78, 0x2000
	s_cbranch_scc1 .LBB0_2369
	s_barrier

; #define PG8_STAGE(bufoff, gbase, voff) do { _Pragma("unroll") for (int _i = 0; _i < 2; ++_i) \
;     __builtin_amdgcn_global_load_lds((const unsigned*)((const char*)(gbase) + (voff)[_i]), (LAS unsigned*)(lds + (bufoff) + ldsw + _i * 8192), 16, 0, 0); } while (0)
; #define PG8_LDA(dst, b, h) do { _Pragma("unroll") for (int m = 0; m < 4; ++m) _Pragma("unroll") for (int k = 0; k < 2; ++k) dst[m][k] = *(const LAS bf16x8*)(lds + PG8_SA(b, h) + aoff + m * 2048 + k * 1024); } while (0)
; #define PG8_LDB(dst, b, h) do { _Pragma("unroll") for (int n = 0; n < 2; ++n) _Pragma("unroll") for (int k = 0; k < 2; ++k) dst[n][k] = *(const LAS bf16x8*)(lds + PG8_SB(b, h) + boff + n * 2048 + k * 1024); } while (0)
; #define PG8_BAR __builtin_amdgcn_s_barrier()
; template <class Epi, class Sched>
; __device__ __forceinline__ void gemm_phase(LAS unsigned char* lds, const Gemm g, const Sched& S, const Epi& E) {
;     ...
;     for (int t = 0; t < nt; t += 2) {
;       const bool last = (t == nt - 2);
;       const char* a1 = cA + (size_t)(t + 1) * kstep;
;       const char* a2 = last ? nA : cA + (size_t)(t + 2) * kstep; const char* b2 = last ? nB : cB + (size_t)(t + 2) * kstep;
;       const char* a3 = a2 + kstep; const char* b3 = b2 + kstep;
;       PG8_LDB(B0, 0, 0); PG8_SCHED; PG8_LDA(At, 0, 0); PG8_STAGE(PG8_SA(1, 1), a1 + hstepA, voffA);
;       PG8_WAIT_L(8); PG8_BAR; PG8_WAIT_L(0); PG8_MMA(0, 0, At, B0); PG8_BAR; PG8_SCHED;
;       PG8_LDB(B1, 0, 1); PG8_STAGE(PG8_SB(0, 0), b2, voffB);
;       PG8_BAR; PG8_WAIT_L(0); PG8_MMA(0, 1, At, B1); PG8_BAR;
;       PG8_LDA(At, 0, 1); PG8_STAGE(PG8_SA(0, 0), a2, voffA);
;       PG8_BAR; PG8_WAIT_L(0); PG8_MMA(1, 0, At, B0); PG8_BAR; PG8_SCHED;
;       PG8_STAGE(PG8_SB(0, 1), b2 + hstepB, voffB);
;       PG8_WAIT_V(6); PG8_BAR; PG8_MMA(1, 1, At, B1); PG8_BAR;
;       PG8_LDB(B0, 1, 0); PG8_SCHED; PG8_LDA(At, 1, 0); PG8_STAGE(PG8_SA(0, 1), a2 + hstepA, voffA);
;       PG8_WAIT_L(8); PG8_BAR; PG8_WAIT_L(0); PG8_MMA(0, 0, At, B0); PG8_BAR; PG8_SCHED;
;       PG8_LDB(B1, 1, 1); PG8_STAGE(PG8_SB(1, 0), b3, voffB);
;       PG8_BAR; PG8_WAIT_L(0); PG8_MMA(0, 1, At, B1); PG8_BAR;
;       PG8_LDA(At, 1, 1); PG8_STAGE(PG8_SA(1, 0), a3, voffA);
;       PG8_BAR; PG8_WAIT_L(0); PG8_MMA(1, 0, At, B0); PG8_BAR; PG8_SCHED;
;       PG8_STAGE(PG8_SB(1, 1), b3 + hstepB, voffB);
;       PG8_WAIT_V(6); PG8_BAR; PG8_MMA(1, 1, At, B1); PG8_BAR;
;     }
.LBB0_2615:
	s_add_u32 s29, s20, s28
	s_addc_u32 s49, s21, 0
	s_add_u32 s38, s29, 0x100
	s_addc_u32 s39, s49, 0
	s_and_b64 s[36:37], s[26:27], exec
	s_cselect_b32 s39, s11, s39
	s_cselect_b32 s38, s83, s38
	s_add_u32 s28, s18, s28
	s_addc_u32 s36, s19, 0
	s_add_u32 s28, s28, 0x100
	s_addc_u32 s36, s36, 0
	s_add_i32 s76, 16, 0x10000
	s_and_b64 s[26:27], s[26:27], exec
	s_cselect_b32 s47, s9, s36
	s_cselect_b32 s46, s84, s28
	s_add_u32 s48, s29, 0x40080
	s_addc_u32 s49, s49, 0
	s_add_i32 vcc_hi, s76, s51
	s_add_i32 m0, s58, 0xc000
	s_add_i32 s77, s58, 0xe000
	s_add_i32 vcc_lo, 16, 0x14000
	s_add_i32 s95, vcc_hi, 0x2000
	s_add_u32 s36, s46, 0x40000
	v_add_u32_e32 v154, s76, v145
	s_addc_u32 s37, s47, 0
	s_add_i32 s90, vcc_lo, s51
	ds_read_b128 v[150:153], v154
	ds_read_b128 v[158:161], v154 offset:1024
	ds_read_b128 v[162:165], v154 offset:2048
	ds_read_b128 v[166:169], v154 offset:3072
	s_add_i32 s89, s90, 0x2000
	s_add_i32 s88, 16, 0x18000
	s_add_u32 s28, s38, 0x40000
	s_addc_u32 s29, s39, 0
	s_add_i32 s87, s88, s51
	s_add_i32 s86, 16, 0x1c000
	s_add_i32 s85, s87, 0x2000
	s_add_u32 s26, s46, 0x40080
	s_addc_u32 s27, s47, 0
	s_add_i32 s94, s86, s51
	s_add_i32 s91, s94, 0x2000
	v_lshl_add_u64 v[154:155], s[48:49], 0, v[130:131]
	ds_read_b128 v[170:173], v157
	ds_read_b128 v[174:177], v157 offset:1024
	ds_read_b128 v[178:181], v157 offset:2048
	ds_read_b128 v[182:185], v157 offset:3072
	ds_read_b128 v[198:201], v157 offset:4096
	ds_read_b128 v[214:217], v157 offset:5120
	ds_read_b128 v[218:221], v157 offset:6144
	ds_read_b128 v[222:225], v157 offset:7168
	global_load_lds_dwordx4 v[154:155], off
	v_lshl_add_u64 v[154:155], s[48:49], 0, v[128:129]
	s_mov_b32 m0, s77
	s_nop 0
	global_load_lds_dwordx4 v[154:155], off
	s_waitcnt lgkmcnt(8)
	s_barrier
	s_waitcnt lgkmcnt(0)
	s_waitcnt lgkmcnt(0)
	v_mfma_f32_16x16x32_bf16 v[124:127], v[150:153], v[170:173], v[124:127]
	v_mfma_f32_16x16x32_bf16 v[120:123], v[162:165], v[170:173], v[120:123]
	v_mfma_f32_16x16x32_bf16 v[112:115], v[150:153], v[178:181], v[112:115]
	v_mfma_f32_16x16x32_bf16 v[104:107], v[162:165], v[178:181], v[104:107]
	v_mfma_f32_16x16x32_bf16 v[96:99], v[150:153], v[198:201], v[96:99]
	v_mfma_f32_16x16x32_bf16 v[88:91], v[162:165], v[198:201], v[88:91]
	v_mfma_f32_16x16x32_bf16 v[80:83], v[150:153], v[218:221], v[80:83]
	v_mfma_f32_16x16x32_bf16 v[72:75], v[162:165], v[218:221], v[72:75]
	v_mfma_f32_16x16x32_bf16 v[124:127], v[158:161], v[174:177], v[124:127]
	v_mfma_f32_16x16x32_bf16 v[120:123], v[166:169], v[174:177], v[120:123]
	v_mfma_f32_16x16x32_bf16 v[112:115], v[158:161], v[182:185], v[112:115]
	v_mfma_f32_16x16x32_bf16 v[104:107], v[166:169], v[182:185], v[104:107]
	v_mfma_f32_16x16x32_bf16 v[96:99], v[158:161], v[214:217], v[96:99]
	v_mfma_f32_16x16x32_bf16 v[88:91], v[166:169], v[214:217], v[88:91]
	v_mfma_f32_16x16x32_bf16 v[80:83], v[158:161], v[222:225], v[80:83]
	v_mfma_f32_16x16x32_bf16 v[72:75], v[166:169], v[222:225], v[72:75]
	s_barrier
	v_add_u32_e32 v154, vcc_lo, v145
	s_mov_b32 m0, vcc_hi
	ds_read_b128 v[226:229], v154
	ds_read_b128 v[230:233], v154 offset:1024
	ds_read_b128 v[234:237], v154 offset:2048
	ds_read_b128 v[238:241], v154 offset:3072
	v_lshl_add_u64 v[154:155], s[46:47], 0, v[130:131]
	global_load_lds_dwordx4 v[154:155], off
	v_lshl_add_u64 v[242:243], s[46:47], 0, v[128:129]
	s_mov_b32 m0, s95
	s_nop 0
	global_load_lds_dwordx4 v[242:243], off
	s_barrier
	s_waitcnt lgkmcnt(0)
	s_waitcnt lgkmcnt(0)
	v_mfma_f32_16x16x32_bf16 v[116:119], v[226:229], v[170:173], v[116:119]
	v_mfma_f32_16x16x32_bf16 v[108:111], v[234:237], v[170:173], v[108:111]
	v_mfma_f32_16x16x32_bf16 v[100:103], v[226:229], v[178:181], v[100:103]
	v_mfma_f32_16x16x32_bf16 v[92:95], v[234:237], v[178:181], v[92:95]
	v_mfma_f32_16x16x32_bf16 v[84:87], v[226:229], v[198:201], v[84:87]
	v_mfma_f32_16x16x32_bf16 v[76:79], v[234:237], v[198:201], v[76:79]
	v_mfma_f32_16x16x32_bf16 v[68:71], v[226:229], v[218:221], v[68:71]
	v_mfma_f32_16x16x32_bf16 v[64:67], v[234:237], v[218:221], v[64:67]
	v_mfma_f32_16x16x32_bf16 v[116:119], v[230:233], v[174:177], v[116:119]
	v_mfma_f32_16x16x32_bf16 v[108:111], v[238:241], v[174:177], v[108:111]
	v_mfma_f32_16x16x32_bf16 v[100:103], v[230:233], v[182:185], v[100:103]
	v_mfma_f32_16x16x32_bf16 v[92:95], v[238:241], v[182:185], v[92:95]
	v_mfma_f32_16x16x32_bf16 v[84:87], v[230:233], v[214:217], v[84:87]
	v_mfma_f32_16x16x32_bf16 v[76:79], v[238:241], v[214:217], v[76:79]
	v_mfma_f32_16x16x32_bf16 v[68:71], v[230:233], v[222:225], v[68:71]
	v_mfma_f32_16x16x32_bf16 v[64:67], v[238:241], v[222:225], v[64:67]
	s_mov_b32 m0, s58
	v_lshl_add_u64 v[244:245], s[38:39], 0, v[130:131]
	s_barrier
	ds_read_b128 v[170:173], v157 offset:16384
	ds_read_b128 v[174:177], v157 offset:17408
	ds_read_b128 v[178:181], v157 offset:18432
	ds_read_b128 v[182:185], v157 offset:19456
	ds_read_b128 v[198:201], v157 offset:20480
	ds_read_b128 v[214:217], v157 offset:21504
	ds_read_b128 v[218:221], v157 offset:22528
	ds_read_b128 v[222:225], v157 offset:23552
	global_load_lds_dwordx4 v[244:245], off
	v_lshl_add_u64 v[246:247], s[38:39], 0, v[128:129]
	s_mov_b32 m0, s59
	s_nop 0
	global_load_lds_dwordx4 v[246:247], off
	s_barrier
; #define PG8_STAGE(bufoff, gbase, voff) do { _Pragma("unroll") for (int _i = 0; _i < 2; ++_i) \
;     __builtin_amdgcn_global_load_lds((const unsigned*)((const char*)(gbase) + (voff)[_i]), (LAS unsigned*)(lds + (bufoff) + ldsw + _i * 8192), 16, 0, 0); } while (0)
; #define PG8_LDA(dst, b, h) do { _Pragma("unroll") for (int m = 0; m < 4; ++m) _Pragma("unroll") for (int k = 0; k < 2; ++k) dst[m][k] = *(const LAS bf16x8*)(lds + PG8_SA(b, h) + aoff + m * 2048 + k * 1024); } while (0)
; #define PG8_LDB(dst, b, h) do { _Pragma("unroll") for (int n = 0; n < 2; ++n) _Pragma("unroll") for (int k = 0; k < 2; ++k) dst[n][k] = *(const LAS bf16x8*)(lds + PG8_SB(b, h) + boff + n * 2048 + k * 1024); } while (0)
; #define PG8_BAR __builtin_amdgcn_s_barrier()
; template <class Epi, class Sched>
; __device__ __forceinline__ void gemm_phase(LAS unsigned char* lds, const Gemm g, const Sched& S, const Epi& E) {
;     ...
;     for (int t = 0; t < nt; t += 2) {
;       const bool last = (t == nt - 2);
;       const char* a1 = cA + (size_t)(t + 1) * kstep;
;       const char* a2 = last ? nA : cA + (size_t)(t + 2) * kstep; const char* b2 = last ? nB : cB + (size_t)(t + 2) * kstep;
;       const char* a3 = a2 + kstep; const char* b3 = b2 + kstep;
;       PG8_LDB(B0, 0, 0); PG8_SCHED; PG8_LDA(At, 0, 0); PG8_STAGE(PG8_SA(1, 1), a1 + hstepA, voffA);
;       PG8_WAIT_L(8); PG8_BAR; PG8_WAIT_L(0); PG8_MMA(0, 0, At, B0); PG8_BAR; PG8_SCHED;
;       PG8_LDB(B1, 0, 1); PG8_STAGE(PG8_SB(0, 0), b2, voffB);
;       PG8_BAR; PG8_WAIT_L(0); PG8_MMA(0, 1, At, B1); PG8_BAR;
;       PG8_LDA(At, 0, 1); PG8_STAGE(PG8_SA(0, 0), a2, voffA);
;       PG8_BAR; PG8_WAIT_L(0); PG8_MMA(1, 0, At, B0); PG8_BAR; PG8_SCHED;
;       PG8_STAGE(PG8_SB(0, 1), b2 + hstepB, voffB);
;       PG8_WAIT_V(6); PG8_BAR; PG8_MMA(1, 1, At, B1); PG8_BAR;
;       PG8_LDB(B0, 1, 0); PG8_SCHED; PG8_LDA(At, 1, 0); PG8_STAGE(PG8_SA(0, 1), a2 + hstepA, voffA);
;       PG8_WAIT_L(8); PG8_BAR; PG8_WAIT_L(0); PG8_MMA(0, 0, At, B0); PG8_BAR; PG8_SCHED;
;       PG8_LDB(B1, 1, 1); PG8_STAGE(PG8_SB(1, 0), b3, voffB);
;       PG8_BAR; PG8_WAIT_L(0); PG8_MMA(0, 1, At, B1); PG8_BAR;
;       PG8_LDA(At, 1, 1); PG8_STAGE(PG8_SA(1, 0), a3, voffA);
;       PG8_BAR; PG8_WAIT_L(0); PG8_MMA(1, 0, At, B0); PG8_BAR; PG8_SCHED;
;       PG8_STAGE(PG8_SB(1, 1), b3 + hstepB, voffB);
;       PG8_WAIT_V(6); PG8_BAR; PG8_MMA(1, 1, At, B1); PG8_BAR;
;     }
	s_waitcnt lgkmcnt(0)
	s_waitcnt lgkmcnt(0)
	v_mfma_f32_16x16x32_bf16 v[60:63], v[150:153], v[170:173], v[60:63]
	v_mfma_f32_16x16x32_bf16 v[56:59], v[162:165], v[170:173], v[56:59]
	v_mfma_f32_16x16x32_bf16 v[48:51], v[150:153], v[178:181], v[48:51]
	v_mfma_f32_16x16x32_bf16 v[40:43], v[162:165], v[178:181], v[40:43]
	v_mfma_f32_16x16x32_bf16 v[32:35], v[150:153], v[198:201], v[32:35]
	v_mfma_f32_16x16x32_bf16 v[24:27], v[162:165], v[198:201], v[24:27]
	v_mfma_f32_16x16x32_bf16 v[16:19], v[150:153], v[218:221], v[16:19]
	v_mfma_f32_16x16x32_bf16 v[8:11], v[162:165], v[218:221], v[8:11]
	v_mfma_f32_16x16x32_bf16 v[60:63], v[158:161], v[174:177], v[60:63]
	v_mfma_f32_16x16x32_bf16 v[56:59], v[166:169], v[174:177], v[56:59]
	v_mfma_f32_16x16x32_bf16 v[48:51], v[158:161], v[182:185], v[48:51]
	v_mfma_f32_16x16x32_bf16 v[40:43], v[166:169], v[182:185], v[40:43]
	v_mfma_f32_16x16x32_bf16 v[32:35], v[158:161], v[214:217], v[32:35]
	v_mfma_f32_16x16x32_bf16 v[24:27], v[166:169], v[214:217], v[24:27]
	v_mfma_f32_16x16x32_bf16 v[16:19], v[158:161], v[222:225], v[16:19]
	v_mfma_f32_16x16x32_bf16 v[8:11], v[166:169], v[222:225], v[8:11]
	s_barrier
	s_mov_b32 m0, s90
	v_lshl_add_u64 v[150:151], s[36:37], 0, v[130:131]
	global_load_lds_dwordx4 v[150:151], off
	v_lshl_add_u64 v[150:151], s[36:37], 0, v[128:129]
	s_mov_b32 m0, s89
	s_nop 0
	global_load_lds_dwordx4 v[150:151], off
	s_waitcnt vmcnt(6)
	s_barrier
	v_mfma_f32_16x16x32_bf16 v[52:55], v[226:229], v[170:173], v[52:55]
	v_mfma_f32_16x16x32_bf16 v[44:47], v[234:237], v[170:173], v[44:47]
	v_mfma_f32_16x16x32_bf16 v[36:39], v[226:229], v[178:181], v[36:39]
	v_mfma_f32_16x16x32_bf16 v[28:31], v[234:237], v[178:181], v[28:31]
	v_mfma_f32_16x16x32_bf16 v[20:23], v[226:229], v[198:201], v[20:23]
	v_mfma_f32_16x16x32_bf16 v[12:15], v[234:237], v[198:201], v[12:15]
	v_mfma_f32_16x16x32_bf16 v[4:7], v[226:229], v[218:221], v[4:7]
	v_mfma_f32_16x16x32_bf16 v[0:3], v[234:237], v[218:221], v[0:3]
	v_mfma_f32_16x16x32_bf16 v[52:55], v[230:233], v[174:177], v[52:55]
	v_mfma_f32_16x16x32_bf16 v[44:47], v[238:241], v[174:177], v[44:47]
	v_mfma_f32_16x16x32_bf16 v[36:39], v[230:233], v[182:185], v[36:39]
	v_mfma_f32_16x16x32_bf16 v[28:31], v[238:241], v[182:185], v[28:31]
	v_mfma_f32_16x16x32_bf16 v[20:23], v[230:233], v[214:217], v[20:23]
	v_mfma_f32_16x16x32_bf16 v[12:15], v[238:241], v[214:217], v[12:15]
	v_mfma_f32_16x16x32_bf16 v[4:7], v[230:233], v[222:225], v[4:7]
	v_mfma_f32_16x16x32_bf16 v[0:3], v[238:241], v[222:225], v[0:3]
	v_add_u32_e32 v166, s88, v145
	s_barrier
	ds_read_b128 v[150:153], v166
	ds_read_b128 v[158:161], v166 offset:1024
	ds_read_b128 v[162:165], v166 offset:2048
	ds_read_b128 v[166:169], v166 offset:3072
	s_mov_b32 m0, s66
	v_lshl_add_u64 v[226:227], s[28:29], 0, v[130:131]
	ds_read_b128 v[170:173], v157 offset:32768
	ds_read_b128 v[174:177], v157 offset:33792
	ds_read_b128 v[178:181], v157 offset:34816
	ds_read_b128 v[182:185], v157 offset:35840
	ds_read_b128 v[198:201], v157 offset:36864
	ds_read_b128 v[214:217], v157 offset:37888
	ds_read_b128 v[218:221], v157 offset:38912
	ds_read_b128 v[222:225], v157 offset:39936
	global_load_lds_dwordx4 v[226:227], off
	v_lshl_add_u64 v[226:227], s[28:29], 0, v[128:129]
	s_mov_b32 m0, s67
	s_nop 0
	global_load_lds_dwordx4 v[226:227], off
	s_waitcnt lgkmcnt(8)
	s_barrier
	s_waitcnt lgkmcnt(0)
	s_waitcnt lgkmcnt(0)
	v_mfma_f32_16x16x32_bf16 v[124:127], v[150:153], v[170:173], v[124:127]
	v_mfma_f32_16x16x32_bf16 v[120:123], v[162:165], v[170:173], v[120:123]
	v_mfma_f32_16x16x32_bf16 v[112:115], v[150:153], v[178:181], v[112:115]
	v_mfma_f32_16x16x32_bf16 v[104:107], v[162:165], v[178:181], v[104:107]
	v_mfma_f32_16x16x32_bf16 v[96:99], v[150:153], v[198:201], v[96:99]
	v_mfma_f32_16x16x32_bf16 v[88:91], v[162:165], v[198:201], v[88:91]
	v_mfma_f32_16x16x32_bf16 v[80:83], v[150:153], v[218:221], v[80:83]
	v_mfma_f32_16x16x32_bf16 v[72:75], v[162:165], v[218:221], v[72:75]
	v_mfma_f32_16x16x32_bf16 v[124:127], v[158:161], v[174:177], v[124:127]
	v_mfma_f32_16x16x32_bf16 v[120:123], v[166:169], v[174:177], v[120:123]
	v_mfma_f32_16x16x32_bf16 v[112:115], v[158:161], v[182:185], v[112:115]
	v_mfma_f32_16x16x32_bf16 v[104:107], v[166:169], v[182:185], v[104:107]
	v_mfma_f32_16x16x32_bf16 v[96:99], v[158:161], v[214:217], v[96:99]
	v_mfma_f32_16x16x32_bf16 v[88:91], v[166:169], v[214:217], v[88:91]
	v_mfma_f32_16x16x32_bf16 v[80:83], v[158:161], v[222:225], v[80:83]
	v_mfma_f32_16x16x32_bf16 v[72:75], v[166:169], v[222:225], v[72:75]
	s_barrier
	s_mov_b32 m0, s87
	v_add_u32_e32 v189, s86, v145
	v_lshl_add_u64 v[154:155], v[154:155], 0, s[62:63]
	ds_read_b128 v[226:229], v189
	ds_read_b128 v[230:233], v189 offset:1024
	ds_read_b128 v[234:237], v189 offset:2048
	ds_read_b128 v[238:241], v189 offset:3072
	global_load_lds_dwordx4 v[154:155], off
	v_lshl_add_u64 v[154:155], v[242:243], 0, s[62:63]
	s_mov_b32 m0, s85
	s_nop 0
	global_load_lds_dwordx4 v[154:155], off
	s_barrier
	s_waitcnt lgkmcnt(0)
	s_waitcnt lgkmcnt(0)
	v_mfma_f32_16x16x32_bf16 v[116:119], v[226:229], v[170:173], v[116:119]
	v_mfma_f32_16x16x32_bf16 v[108:111], v[234:237], v[170:173], v[108:111]
	v_mfma_f32_16x16x32_bf16 v[100:103], v[226:229], v[178:181], v[100:103]
	v_mfma_f32_16x16x32_bf16 v[92:95], v[234:237], v[178:181], v[92:95]
	v_mfma_f32_16x16x32_bf16 v[84:87], v[226:229], v[198:201], v[84:87]
	v_mfma_f32_16x16x32_bf16 v[76:79], v[234:237], v[198:201], v[76:79]
	v_mfma_f32_16x16x32_bf16 v[68:71], v[226:229], v[218:221], v[68:71]
	v_mfma_f32_16x16x32_bf16 v[64:67], v[234:237], v[218:221], v[64:67]
	v_mfma_f32_16x16x32_bf16 v[116:119], v[230:233], v[174:177], v[116:119]
	v_mfma_f32_16x16x32_bf16 v[108:111], v[238:241], v[174:177], v[108:111]
	v_mfma_f32_16x16x32_bf16 v[100:103], v[230:233], v[182:185], v[100:103]
	v_mfma_f32_16x16x32_bf16 v[92:95], v[238:241], v[182:185], v[92:95]
	v_mfma_f32_16x16x32_bf16 v[84:87], v[230:233], v[214:217], v[84:87]
	v_mfma_f32_16x16x32_bf16 v[76:79], v[238:241], v[214:217], v[76:79]
	v_mfma_f32_16x16x32_bf16 v[68:71], v[230:233], v[222:225], v[68:71]
	v_mfma_f32_16x16x32_bf16 v[64:67], v[238:241], v[222:225], v[64:67]
	s_mov_b32 m0, s74
	v_lshl_add_u64 v[154:155], v[244:245], 0, s[62:63]
	s_barrier
; #define PG8_STAGE(bufoff, gbase, voff) do { _Pragma("unroll") for (int _i = 0; _i < 2; ++_i) \
;     __builtin_amdgcn_global_load_lds((const unsigned*)((const char*)(gbase) + (voff)[_i]), (LAS unsigned*)(lds + (bufoff) + ldsw + _i * 8192), 16, 0, 0); } while (0)
; #define PG8_LDA(dst, b, h) do { _Pragma("unroll") for (int m = 0; m < 4; ++m) _Pragma("unroll") for (int k = 0; k < 2; ++k) dst[m][k] = *(const LAS bf16x8*)(lds + PG8_SA(b, h) + aoff + m * 2048 + k * 1024); } while (0)
; #define PG8_LDB(dst, b, h) do { _Pragma("unroll") for (int n = 0; n < 2; ++n) _Pragma("unroll") for (int k = 0; k < 2; ++k) dst[n][k] = *(const LAS bf16x8*)(lds + PG8_SB(b, h) + boff + n * 2048 + k * 1024); } while (0)
; #define PG8_BAR __builtin_amdgcn_s_barrier()
; template <class Epi, class Sched>
; __device__ __forceinline__ void gemm_phase(LAS unsigned char* lds, const Gemm g, const Sched& S, const Epi& E) {
;     ...
;     for (int t = 0; t < nt; t += 2) {
;       const bool last = (t == nt - 2);
;       const char* a1 = cA + (size_t)(t + 1) * kstep;
;       const char* a2 = last ? nA : cA + (size_t)(t + 2) * kstep; const char* b2 = last ? nB : cB + (size_t)(t + 2) * kstep;
;       const char* a3 = a2 + kstep; const char* b3 = b2 + kstep;
;       PG8_LDB(B0, 0, 0); PG8_SCHED; PG8_LDA(At, 0, 0); PG8_STAGE(PG8_SA(1, 1), a1 + hstepA, voffA);
;       PG8_WAIT_L(8); PG8_BAR; PG8_WAIT_L(0); PG8_MMA(0, 0, At, B0); PG8_BAR; PG8_SCHED;
;       PG8_LDB(B1, 0, 1); PG8_STAGE(PG8_SB(0, 0), b2, voffB);
;       PG8_BAR; PG8_WAIT_L(0); PG8_MMA(0, 1, At, B1); PG8_BAR;
;       PG8_LDA(At, 0, 1); PG8_STAGE(PG8_SA(0, 0), a2, voffA);
;       PG8_BAR; PG8_WAIT_L(0); PG8_MMA(1, 0, At, B0); PG8_BAR; PG8_SCHED;
;       PG8_STAGE(PG8_SB(0, 1), b2 + hstepB, voffB);
;       PG8_WAIT_V(6); PG8_BAR; PG8_MMA(1, 1, At, B1); PG8_BAR;
;       PG8_LDB(B0, 1, 0); PG8_SCHED; PG8_LDA(At, 1, 0); PG8_STAGE(PG8_SA(0, 1), a2 + hstepA, voffA);
;       PG8_WAIT_L(8); PG8_BAR; PG8_WAIT_L(0); PG8_MMA(0, 0, At, B0); PG8_BAR; PG8_SCHED;
;       PG8_LDB(B1, 1, 1); PG8_STAGE(PG8_SB(1, 0), b3, voffB);
;       PG8_BAR; PG8_WAIT_L(0); PG8_MMA(0, 1, At, B1); PG8_BAR;
;       PG8_LDA(At, 1, 1); PG8_STAGE(PG8_SA(1, 0), a3, voffA);
;       PG8_BAR; PG8_WAIT_L(0); PG8_MMA(1, 0, At, B0); PG8_BAR; PG8_SCHED;
;       PG8_STAGE(PG8_SB(1, 1), b3 + hstepB, voffB);
;       PG8_WAIT_V(6); PG8_BAR; PG8_MMA(1, 1, At, B1); PG8_BAR;
;     }
	ds_read_b128 v[170:173], v157 offset:49152
	ds_read_b128 v[174:177], v157 offset:50176
	ds_read_b128 v[178:181], v157 offset:51200
	ds_read_b128 v[182:185], v157 offset:52224
	ds_read_b128 v[198:201], v157 offset:53248
	ds_read_b128 v[214:217], v157 offset:54272
	ds_read_b128 v[218:221], v157 offset:55296
	ds_read_b128 v[222:225], v157 offset:56320
	global_load_lds_dwordx4 v[154:155], off
	v_lshl_add_u64 v[154:155], v[246:247], 0, s[62:63]
	s_mov_b32 m0, s75
	s_nop 0
	global_load_lds_dwordx4 v[154:155], off
	s_barrier
	s_waitcnt lgkmcnt(0)
	s_waitcnt lgkmcnt(0)
	v_mfma_f32_16x16x32_bf16 v[60:63], v[150:153], v[170:173], v[60:63]
	v_mfma_f32_16x16x32_bf16 v[56:59], v[162:165], v[170:173], v[56:59]
	v_mfma_f32_16x16x32_bf16 v[48:51], v[150:153], v[178:181], v[48:51]
	v_mfma_f32_16x16x32_bf16 v[40:43], v[162:165], v[178:181], v[40:43]
	v_mfma_f32_16x16x32_bf16 v[32:35], v[150:153], v[198:201], v[32:35]
	v_mfma_f32_16x16x32_bf16 v[24:27], v[162:165], v[198:201], v[24:27]
	v_mfma_f32_16x16x32_bf16 v[16:19], v[150:153], v[218:221], v[16:19]
	v_mfma_f32_16x16x32_bf16 v[8:11], v[162:165], v[218:221], v[8:11]
	v_mfma_f32_16x16x32_bf16 v[60:63], v[158:161], v[174:177], v[60:63]
	v_mfma_f32_16x16x32_bf16 v[56:59], v[166:169], v[174:177], v[56:59]
	v_mfma_f32_16x16x32_bf16 v[48:51], v[158:161], v[182:185], v[48:51]
	v_mfma_f32_16x16x32_bf16 v[40:43], v[166:169], v[182:185], v[40:43]
	v_mfma_f32_16x16x32_bf16 v[32:35], v[158:161], v[214:217], v[32:35]
	v_mfma_f32_16x16x32_bf16 v[24:27], v[166:169], v[214:217], v[24:27]
	v_mfma_f32_16x16x32_bf16 v[16:19], v[158:161], v[222:225], v[16:19]
	v_mfma_f32_16x16x32_bf16 v[8:11], v[166:169], v[222:225], v[8:11]
	s_barrier
	s_mov_b32 m0, s94
	v_lshl_add_u64 v[150:151], s[26:27], 0, v[130:131]
	global_load_lds_dwordx4 v[150:151], off
	v_lshl_add_u64 v[150:151], s[26:27], 0, v[128:129]
	s_mov_b32 m0, s91
	s_nop 0
	global_load_lds_dwordx4 v[150:151], off
	s_waitcnt vmcnt(6)
	s_barrier
	v_mfma_f32_16x16x32_bf16 v[52:55], v[226:229], v[170:173], v[52:55]
	v_mfma_f32_16x16x32_bf16 v[44:47], v[234:237], v[170:173], v[44:47]
	v_mfma_f32_16x16x32_bf16 v[36:39], v[226:229], v[178:181], v[36:39]
	v_mfma_f32_16x16x32_bf16 v[28:31], v[234:237], v[178:181], v[28:31]
	v_mfma_f32_16x16x32_bf16 v[20:23], v[226:229], v[198:201], v[20:23]
	v_mfma_f32_16x16x32_bf16 v[12:15], v[234:237], v[198:201], v[12:15]
	v_mfma_f32_16x16x32_bf16 v[4:7], v[226:229], v[218:221], v[4:7]
	v_mfma_f32_16x16x32_bf16 v[0:3], v[234:237], v[218:221], v[0:3]
	v_mfma_f32_16x16x32_bf16 v[52:55], v[230:233], v[174:177], v[52:55]
	v_mfma_f32_16x16x32_bf16 v[44:47], v[238:241], v[174:177], v[44:47]
	v_mfma_f32_16x16x32_bf16 v[36:39], v[230:233], v[182:185], v[36:39]
	v_mfma_f32_16x16x32_bf16 v[28:31], v[238:241], v[182:185], v[28:31]
	v_mfma_f32_16x16x32_bf16 v[20:23], v[230:233], v[214:217], v[20:23]
	v_mfma_f32_16x16x32_bf16 v[12:15], v[238:241], v[214:217], v[12:15]
	v_mfma_f32_16x16x32_bf16 v[4:7], v[230:233], v[222:225], v[4:7]
	v_mfma_f32_16x16x32_bf16 v[0:3], v[238:241], v[222:225], v[0:3]
	s_movk_i32 s28, 0x100
	s_andn2_b64 vcc, exec, s[22:23]
	s_mov_b64 s[26:27], -1
	s_mov_b64 s[22:23], 0
	s_barrier
	s_cbranch_vccz .LBB0_2615
	v_lshl_or_b32 v162, s82, 8, v156
	v_ashrrev_i32_e32 v163, 31, v162
	v_lshlrev_b64 v[150:151], 2, v[162:163]
	v_lshl_add_u64 v[152:153], s[4:5], 0, v[150:151]
	global_load_dwordx4 v[214:217], v[152:153], off
	global_load_dwordx4 v[218:221], v[152:153], off offset:64
	global_load_dwordx4 v[222:225], v[152:153], off offset:512
	global_load_dwordx4 v[226:229], v[152:153], off offset:576
	s_ashr_i32 s9, s79, 31
	s_lshr_b32 s9, s9, 24
	s_add_i32 s9, s79, s9
	s_ashr_i32 s18, s9, 8
	s_ashr_i32 s19, s18, 31
	s_lshl_b64 s[18:19], s[18:19], 20
	s_add_u32 s18, s68, s18
	s_addc_u32 s19, s69, s19
	v_or_b32_e32 v154, 16, v162
	v_lshl_add_u64 v[164:165], s[18:19], 0, v[132:133]
	v_ashrrev_i32_e32 v155, 31, v154
	v_lshl_add_u64 v[164:165], v[164:165], 0, v[150:151]
	v_lshl_add_u64 v[154:155], v[154:155], 2, s[4:5]
	s_mov_b32 s82, s8
	s_mov_b64 s[20:21], s[14:15]
	s_mov_b32 s79, s10
	s_and_b64 vcc, exec, s[12:13]
	s_waitcnt vmcnt(0)
; #define PG8_WAIT_V(n) asm volatile("s_waitcnt vmcnt(" #n ")" ::: "memory")
; #define PG8_BAR __builtin_amdgcn_s_barrier()
; template <class Epi, class Sched>
; __device__ __forceinline__ void gemm_phase(LAS unsigned char* lds, const Gemm g, const Sched& S, const Epi& E) {
;     ...
;     E(acc, cur, wr, wc, fr, fq);
;     if (!has_next) break;
; #pragma unroll
;     for (int a = 0; a < 2; ++a)
; #pragma unroll
;       for (int b = 0; b < 2; ++b)
; #pragma unroll
;         for (int m = 0; m < 4; ++m)
; #pragma unroll
;           for (int n = 0; n < 2; ++n) acc[a][b][m][n] = (f32x4){0.f, 0.f, 0.f, 0.f};
;     cur = nxt; cA = nA; cB = nB; ++ui;
;   }
;   PG8_WAIT_V(0);
;   if (wr == 0) PG8_BAR;
;   PG8_BAR;
	v_pk_mul_f32 v[126:127], v[126:127], v[216:217]
	v_pk_mul_f32 v[124:125], v[124:125], v[214:215]
	global_store_dwordx4 v[164:165], v[124:127], off
	s_nop 1
	v_pk_mul_f32 v[122:123], v[122:123], v[220:221]
	v_or_b32_e32 v124, 0x80, v162
	v_ashrrev_i32_e32 v125, 31, v124
	v_pk_mul_f32 v[120:121], v[120:121], v[218:219]
	v_lshl_add_u64 v[124:125], v[124:125], 2, s[4:5]
	global_store_dwordx4 v[164:165], v[120:123], off offset:64
	s_nop 1
	v_pk_mul_f32 v[118:119], v[118:119], v[224:225]
	v_or_b32_e32 v120, 0x90, v162
	v_ashrrev_i32_e32 v121, 31, v120
	v_pk_mul_f32 v[116:117], v[116:117], v[222:223]
	v_lshl_add_u64 v[120:121], v[120:121], 2, s[4:5]
	global_store_dwordx4 v[164:165], v[116:119], off offset:512
	s_nop 1
	v_pk_mul_f32 v[110:111], v[110:111], v[228:229]
	v_pk_mul_f32 v[108:109], v[108:109], v[226:227]
	global_store_dwordx4 v[164:165], v[108:111], off offset:576
	s_nop 1
	v_lshl_add_u64 v[116:117], s[18:19], 0, v[134:135]
	v_lshl_add_u64 v[116:117], v[116:117], 0, v[150:151]
	v_pk_mul_f32 v[110:111], v[114:115], v[216:217]
	v_pk_mul_f32 v[108:109], v[112:113], v[214:215]
	global_store_dwordx4 v[116:117], v[108:111], off
	s_nop 1
	v_pk_mul_f32 v[106:107], v[106:107], v[220:221]
	v_pk_mul_f32 v[104:105], v[104:105], v[218:219]
	global_store_dwordx4 v[116:117], v[104:107], off offset:64
	s_nop 1
	v_pk_mul_f32 v[102:103], v[102:103], v[224:225]
	v_pk_mul_f32 v[100:101], v[100:101], v[222:223]
	global_store_dwordx4 v[116:117], v[100:103], off offset:512
	s_nop 1
	v_pk_mul_f32 v[94:95], v[94:95], v[228:229]
	v_pk_mul_f32 v[92:93], v[92:93], v[226:227]
	global_store_dwordx4 v[116:117], v[92:95], off offset:576
	s_nop 1
	v_lshl_add_u64 v[100:101], s[18:19], 0, v[136:137]
	v_lshl_add_u64 v[100:101], v[100:101], 0, v[150:151]
	v_pk_mul_f32 v[94:95], v[98:99], v[216:217]
	v_pk_mul_f32 v[92:93], v[96:97], v[214:215]
	global_store_dwordx4 v[100:101], v[92:95], off
	s_nop 1
	v_pk_mul_f32 v[90:91], v[90:91], v[220:221]
	v_pk_mul_f32 v[88:89], v[88:89], v[218:219]
	global_store_dwordx4 v[100:101], v[88:91], off offset:64
	s_nop 1
	v_pk_mul_f32 v[86:87], v[86:87], v[224:225]
	v_pk_mul_f32 v[84:85], v[84:85], v[222:223]
	global_store_dwordx4 v[100:101], v[84:87], off offset:512
	s_nop 1
	v_pk_mul_f32 v[78:79], v[78:79], v[228:229]
	v_pk_mul_f32 v[76:77], v[76:77], v[226:227]
	global_store_dwordx4 v[100:101], v[76:79], off offset:576
	s_nop 1
	v_lshl_add_u64 v[84:85], s[18:19], 0, v[138:139]
	v_lshl_add_u64 v[84:85], v[84:85], 0, v[150:151]
	v_pk_mul_f32 v[78:79], v[82:83], v[216:217]
	v_pk_mul_f32 v[76:77], v[80:81], v[214:215]
	global_store_dwordx4 v[84:85], v[76:79], off
	s_nop 1
	v_pk_mul_f32 v[74:75], v[74:75], v[220:221]
	v_pk_mul_f32 v[72:73], v[72:73], v[218:219]
	global_store_dwordx4 v[84:85], v[72:75], off offset:64
	s_nop 1
	v_pk_mul_f32 v[70:71], v[70:71], v[224:225]
	v_pk_mul_f32 v[68:69], v[68:69], v[222:223]
	global_store_dwordx4 v[84:85], v[68:71], off offset:512
	s_nop 1
	v_pk_mul_f32 v[66:67], v[66:67], v[228:229]
	v_pk_mul_f32 v[64:65], v[64:65], v[226:227]
	global_store_dwordx4 v[84:85], v[64:67], off offset:576
	s_nop 1
	v_lshl_add_u64 v[68:69], s[18:19], 0, v[140:141]
	v_lshl_add_u64 v[68:69], v[68:69], 0, v[150:151]
	v_pk_mul_f32 v[62:63], v[62:63], v[216:217]
	v_pk_mul_f32 v[60:61], v[60:61], v[214:215]
	global_store_dwordx4 v[68:69], v[60:63], off
	s_nop 1
	v_pk_mul_f32 v[58:59], v[58:59], v[220:221]
	v_pk_mul_f32 v[56:57], v[56:57], v[218:219]
	global_store_dwordx4 v[68:69], v[56:59], off offset:64
	s_nop 1
	v_pk_mul_f32 v[54:55], v[54:55], v[224:225]
	v_pk_mul_f32 v[52:53], v[52:53], v[222:223]
	global_store_dwordx4 v[68:69], v[52:55], off offset:512
	s_nop 1
	v_pk_mul_f32 v[46:47], v[46:47], v[228:229]
	v_pk_mul_f32 v[44:45], v[44:45], v[226:227]
	global_store_dwordx4 v[68:69], v[44:47], off offset:576
	s_nop 1
	v_lshl_add_u64 v[52:53], s[18:19], 0, v[142:143]
	v_lshl_add_u64 v[52:53], v[52:53], 0, v[150:151]
	v_pk_mul_f32 v[46:47], v[50:51], v[216:217]
	v_pk_mul_f32 v[44:45], v[48:49], v[214:215]
	global_store_dwordx4 v[52:53], v[44:47], off
	s_nop 1
	v_pk_mul_f32 v[42:43], v[42:43], v[220:221]
	v_pk_mul_f32 v[40:41], v[40:41], v[218:219]
	global_store_dwordx4 v[52:53], v[40:43], off offset:64
	s_nop 1
	v_pk_mul_f32 v[38:39], v[38:39], v[224:225]
	v_pk_mul_f32 v[36:37], v[36:37], v[222:223]
	global_store_dwordx4 v[52:53], v[36:39], off offset:512
	s_nop 1
	v_pk_mul_f32 v[30:31], v[30:31], v[228:229]
	v_pk_mul_f32 v[28:29], v[28:29], v[226:227]
	global_store_dwordx4 v[52:53], v[28:31], off offset:576
	s_nop 1
	v_lshl_add_u64 v[36:37], s[18:19], 0, v[146:147]
	v_lshl_add_u64 v[36:37], v[36:37], 0, v[150:151]
	v_pk_mul_f32 v[30:31], v[34:35], v[216:217]
	v_pk_mul_f32 v[28:29], v[32:33], v[214:215]
	global_store_dwordx4 v[36:37], v[28:31], off
	s_nop 1
	v_pk_mul_f32 v[26:27], v[26:27], v[220:221]
	v_pk_mul_f32 v[24:25], v[24:25], v[218:219]
	global_store_dwordx4 v[36:37], v[24:27], off offset:64
	s_nop 1
	v_pk_mul_f32 v[22:23], v[22:23], v[224:225]
	v_pk_mul_f32 v[20:21], v[20:21], v[222:223]
	global_store_dwordx4 v[36:37], v[20:23], off offset:512
	s_nop 1
	v_pk_mul_f32 v[14:15], v[14:15], v[228:229]
	v_pk_mul_f32 v[12:13], v[12:13], v[226:227]
	global_store_dwordx4 v[36:37], v[12:15], off offset:576
	s_nop 1
	v_lshl_add_u64 v[20:21], s[18:19], 0, v[148:149]
	v_lshl_add_u64 v[20:21], v[20:21], 0, v[150:151]
	s_mov_b64 s[18:19], s[16:17]
	v_pk_mul_f32 v[14:15], v[18:19], v[216:217]
	v_pk_mul_f32 v[12:13], v[16:17], v[214:215]
	global_store_dwordx4 v[20:21], v[12:15], off
	s_nop 1
	v_pk_mul_f32 v[10:11], v[10:11], v[220:221]
	v_pk_mul_f32 v[8:9], v[8:9], v[218:219]
	global_store_dwordx4 v[20:21], v[8:11], off offset:64
	s_nop 1
	v_pk_mul_f32 v[6:7], v[6:7], v[224:225]
	v_pk_mul_f32 v[4:5], v[4:5], v[222:223]
	global_store_dwordx4 v[20:21], v[4:7], off offset:512
	s_nop 1
	v_pk_mul_f32 v[2:3], v[2:3], v[228:229]
	v_pk_mul_f32 v[0:1], v[0:1], v[226:227]
	global_store_dwordx4 v[20:21], v[0:3], off offset:576
	s_nop 1
	s_cbranch_vccz .LBB0_2612
	s_waitcnt vmcnt(0)
	v_readlane_b32 s82, v255, 17
	v_readlane_b32 s68, v255, 20
	s_cmpk_gt_u32 s24, 0xff
	v_readlane_b32 s83, v255, 18
	s_mov_b32 s74, 0x8000
	s_mov_b32 s75, 0x10000
	s_movk_i32 s79, 0x40ff
	s_movk_i32 s78, 0x2000
	v_readlane_b32 s69, v255, 21
	s_cbranch_scc1 .LBB0_2619
	s_barrier

; #define PG8_STAGE(bufoff, gbase, voff) do { _Pragma("unroll") for (int _i = 0; _i < 2; ++_i) \
;     __builtin_amdgcn_global_load_lds((const unsigned*)((const char*)(gbase) + (voff)[_i]), (LAS unsigned*)(lds + (bufoff) + ldsw + _i * 8192), 16, 0, 0); } while (0)
; #define PG8_LDA(dst, b, h) do { _Pragma("unroll") for (int m = 0; m < 4; ++m) _Pragma("unroll") for (int k = 0; k < 2; ++k) dst[m][k] = *(const LAS bf16x8*)(lds + PG8_SA(b, h) + aoff + m * 2048 + k * 1024); } while (0)
; #define PG8_LDB(dst, b, h) do { _Pragma("unroll") for (int n = 0; n < 2; ++n) _Pragma("unroll") for (int k = 0; k < 2; ++k) dst[n][k] = *(const LAS bf16x8*)(lds + PG8_SB(b, h) + boff + n * 2048 + k * 1024); } while (0)
; #define PG8_BAR __builtin_amdgcn_s_barrier()
; template <class Epi, class Sched>
; __device__ __forceinline__ void gemm_phase(LAS unsigned char* lds, const Gemm g, const Sched& S, const Epi& E) {
;     ...
;     for (int t = 0; t < nt; t += 2) {
;       const bool last = (t == nt - 2);
;       const char* a1 = cA + (size_t)(t + 1) * kstep;
;       const char* a2 = last ? nA : cA + (size_t)(t + 2) * kstep; const char* b2 = last ? nB : cB + (size_t)(t + 2) * kstep;
;       const char* a3 = a2 + kstep; const char* b3 = b2 + kstep;
;       PG8_LDB(B0, 0, 0); PG8_SCHED; PG8_LDA(At, 0, 0); PG8_STAGE(PG8_SA(1, 1), a1 + hstepA, voffA);
;       PG8_WAIT_L(8); PG8_BAR; PG8_WAIT_L(0); PG8_MMA(0, 0, At, B0); PG8_BAR; PG8_SCHED;
;       PG8_LDB(B1, 0, 1); PG8_STAGE(PG8_SB(0, 0), b2, voffB);
;       PG8_BAR; PG8_WAIT_L(0); PG8_MMA(0, 1, At, B1); PG8_BAR;
;       PG8_LDA(At, 0, 1); PG8_STAGE(PG8_SA(0, 0), a2, voffA);
;       PG8_BAR; PG8_WAIT_L(0); PG8_MMA(1, 0, At, B0); PG8_BAR; PG8_SCHED;
;       PG8_STAGE(PG8_SB(0, 1), b2 + hstepB, voffB);
;       PG8_WAIT_V(6); PG8_BAR; PG8_MMA(1, 1, At, B1); PG8_BAR;
;       PG8_LDB(B0, 1, 0); PG8_SCHED; PG8_LDA(At, 1, 0); PG8_STAGE(PG8_SA(0, 1), a2 + hstepA, voffA);
;       PG8_WAIT_L(8); PG8_BAR; PG8_WAIT_L(0); PG8_MMA(0, 0, At, B0); PG8_BAR; PG8_SCHED;
;       PG8_LDB(B1, 1, 1); PG8_STAGE(PG8_SB(1, 0), b3, voffB);
;       PG8_BAR; PG8_WAIT_L(0); PG8_MMA(0, 1, At, B1); PG8_BAR;
;       PG8_LDA(At, 1, 1); PG8_STAGE(PG8_SA(1, 0), a3, voffA);
;       PG8_BAR; PG8_WAIT_L(0); PG8_MMA(1, 0, At, B0); PG8_BAR; PG8_SCHED;
;       PG8_STAGE(PG8_SB(1, 1), b3 + hstepB, voffB);
;       PG8_WAIT_V(6); PG8_BAR; PG8_MMA(1, 1, At, B1); PG8_BAR;
;     }
.LBB0_2633:
	s_add_u32 s36, s28, 0xfffc0080
	s_addc_u32 s37, s29, -1
	s_add_i32 s76, 16, 0x10000
	v_add_u32_e32 v149, s76, v146
	ds_read_b128 v[136:139], v149
	ds_read_b128 v[140:143], v149 offset:1024
	ds_read_b128 v[150:153], v149 offset:2048
	ds_read_b128 v[154:157], v149 offset:3072
	s_cmp_eq_u32 s86, 12
	s_cselect_b32 s39, s21, s37
	s_cselect_b32 s38, s82, s36
	s_cselect_b32 s37, s19, s85
	s_cselect_b32 s36, s83, s84
	v_lshl_add_u64 v[214:215], s[28:29], 0, v[132:133]
	s_add_i32 m0, s48, 0xc000
	ds_read_b128 v[158:161], v148
	ds_read_b128 v[162:165], v148 offset:1024
	ds_read_b128 v[166:169], v148 offset:2048
	ds_read_b128 v[170:173], v148 offset:3072
	ds_read_b128 v[174:177], v148 offset:4096
	ds_read_b128 v[178:181], v148 offset:5120
	ds_read_b128 v[182:185], v148 offset:6144
	ds_read_b128 v[198:201], v148 offset:7168
	global_load_lds_dwordx4 v[214:215], off
	v_lshl_add_u64 v[214:215], s[28:29], 0, v[134:135]
	s_add_i32 m0, s48, 0xe000
	s_nop 0
	global_load_lds_dwordx4 v[214:215], off
	s_waitcnt lgkmcnt(8)
	s_barrier
	s_waitcnt lgkmcnt(0)
	s_waitcnt lgkmcnt(0)
	v_mfma_f32_16x16x32_bf16 v[124:127], v[136:139], v[158:161], v[124:127]
	v_mfma_f32_16x16x32_bf16 v[120:123], v[150:153], v[158:161], v[120:123]
	v_mfma_f32_16x16x32_bf16 v[112:115], v[136:139], v[166:169], v[112:115]
	v_mfma_f32_16x16x32_bf16 v[104:107], v[150:153], v[166:169], v[104:107]
	v_mfma_f32_16x16x32_bf16 v[96:99], v[136:139], v[174:177], v[96:99]
	v_mfma_f32_16x16x32_bf16 v[88:91], v[150:153], v[174:177], v[88:91]
	v_mfma_f32_16x16x32_bf16 v[80:83], v[136:139], v[182:185], v[80:83]
	v_mfma_f32_16x16x32_bf16 v[72:75], v[150:153], v[182:185], v[72:75]
	v_mfma_f32_16x16x32_bf16 v[124:127], v[140:143], v[162:165], v[124:127]
	v_mfma_f32_16x16x32_bf16 v[120:123], v[154:157], v[162:165], v[120:123]
	v_mfma_f32_16x16x32_bf16 v[112:115], v[140:143], v[170:173], v[112:115]
	v_mfma_f32_16x16x32_bf16 v[104:107], v[154:157], v[170:173], v[104:107]
	v_mfma_f32_16x16x32_bf16 v[96:99], v[140:143], v[178:181], v[96:99]
	v_mfma_f32_16x16x32_bf16 v[88:91], v[154:157], v[178:181], v[88:91]
	v_mfma_f32_16x16x32_bf16 v[80:83], v[140:143], v[198:201], v[80:83]
	v_mfma_f32_16x16x32_bf16 v[72:75], v[154:157], v[198:201], v[72:75]
	s_barrier
	s_add_i32 s87, 16, 0x14000
	s_add_i32 s76, s76, s25
	v_add_u32_e32 v149, s87, v146
	v_lshl_add_u64 v[230:231], s[36:37], 0, v[130:131]
	s_mov_b32 m0, s76
	ds_read_b128 v[214:217], v149
	ds_read_b128 v[218:221], v149 offset:1024
	ds_read_b128 v[222:225], v149 offset:2048
	ds_read_b128 v[226:229], v149 offset:3072
	global_load_lds_dwordx4 v[230:231], off
	v_lshl_add_u64 v[232:233], s[36:37], 0, v[128:129]
	s_add_i32 m0, s76, 0x2000
	s_nop 0
	global_load_lds_dwordx4 v[232:233], off
	s_barrier
	s_waitcnt lgkmcnt(0)
	s_waitcnt lgkmcnt(0)
	v_mfma_f32_16x16x32_bf16 v[116:119], v[214:217], v[158:161], v[116:119]
	v_mfma_f32_16x16x32_bf16 v[108:111], v[222:225], v[158:161], v[108:111]
	v_mfma_f32_16x16x32_bf16 v[100:103], v[214:217], v[166:169], v[100:103]
	v_mfma_f32_16x16x32_bf16 v[92:95], v[222:225], v[166:169], v[92:95]
	v_mfma_f32_16x16x32_bf16 v[84:87], v[214:217], v[174:177], v[84:87]
	v_mfma_f32_16x16x32_bf16 v[76:79], v[222:225], v[174:177], v[76:79]
	v_mfma_f32_16x16x32_bf16 v[68:71], v[214:217], v[182:185], v[68:71]
	v_mfma_f32_16x16x32_bf16 v[64:67], v[222:225], v[182:185], v[64:67]
	v_mfma_f32_16x16x32_bf16 v[116:119], v[218:221], v[162:165], v[116:119]
	v_mfma_f32_16x16x32_bf16 v[108:111], v[226:229], v[162:165], v[108:111]
	v_mfma_f32_16x16x32_bf16 v[100:103], v[218:221], v[170:173], v[100:103]
	v_mfma_f32_16x16x32_bf16 v[92:95], v[226:229], v[170:173], v[92:95]
	v_mfma_f32_16x16x32_bf16 v[84:87], v[218:221], v[178:181], v[84:87]
	v_mfma_f32_16x16x32_bf16 v[76:79], v[226:229], v[178:181], v[76:79]
	v_mfma_f32_16x16x32_bf16 v[68:71], v[218:221], v[198:201], v[68:71]
	v_mfma_f32_16x16x32_bf16 v[64:67], v[226:229], v[198:201], v[64:67]
	s_mov_b32 m0, s48
	v_lshl_add_u64 v[234:235], s[38:39], 0, v[130:131]
	s_barrier
	ds_read_b128 v[158:161], v148 offset:16384
	ds_read_b128 v[162:165], v148 offset:17408
	ds_read_b128 v[166:169], v148 offset:18432
	ds_read_b128 v[170:173], v148 offset:19456
	ds_read_b128 v[174:177], v148 offset:20480
	ds_read_b128 v[178:181], v148 offset:21504
	ds_read_b128 v[182:185], v148 offset:22528
	ds_read_b128 v[198:201], v148 offset:23552
	global_load_lds_dwordx4 v[234:235], off
	v_lshl_add_u64 v[236:237], s[38:39], 0, v[128:129]
	s_mov_b32 m0, s49
	s_nop 0
	global_load_lds_dwordx4 v[236:237], off
	s_barrier
	s_waitcnt lgkmcnt(0)
	s_waitcnt lgkmcnt(0)
	v_mfma_f32_16x16x32_bf16 v[60:63], v[136:139], v[158:161], v[60:63]
	v_mfma_f32_16x16x32_bf16 v[56:59], v[150:153], v[158:161], v[56:59]
	v_mfma_f32_16x16x32_bf16 v[48:51], v[136:139], v[166:169], v[48:51]
	v_mfma_f32_16x16x32_bf16 v[40:43], v[150:153], v[166:169], v[40:43]
	v_mfma_f32_16x16x32_bf16 v[32:35], v[136:139], v[174:177], v[32:35]
	v_mfma_f32_16x16x32_bf16 v[24:27], v[150:153], v[174:177], v[24:27]
	v_mfma_f32_16x16x32_bf16 v[16:19], v[136:139], v[182:185], v[16:19]
	v_mfma_f32_16x16x32_bf16 v[8:11], v[150:153], v[182:185], v[8:11]
	v_mfma_f32_16x16x32_bf16 v[60:63], v[140:143], v[162:165], v[60:63]
	v_mfma_f32_16x16x32_bf16 v[56:59], v[154:157], v[162:165], v[56:59]
	v_mfma_f32_16x16x32_bf16 v[48:51], v[140:143], v[170:173], v[48:51]
	v_mfma_f32_16x16x32_bf16 v[40:43], v[154:157], v[170:173], v[40:43]
	v_mfma_f32_16x16x32_bf16 v[32:35], v[140:143], v[178:181], v[32:35]
	v_mfma_f32_16x16x32_bf16 v[24:27], v[154:157], v[178:181], v[24:27]
	v_mfma_f32_16x16x32_bf16 v[16:19], v[140:143], v[198:201], v[16:19]
	v_mfma_f32_16x16x32_bf16 v[8:11], v[154:157], v[198:201], v[8:11]
	s_barrier
; #define PG8_STAGE(bufoff, gbase, voff) do { _Pragma("unroll") for (int _i = 0; _i < 2; ++_i) \
;     __builtin_amdgcn_global_load_lds((const unsigned*)((const char*)(gbase) + (voff)[_i]), (LAS unsigned*)(lds + (bufoff) + ldsw + _i * 8192), 16, 0, 0); } while (0)
; #define PG8_LDA(dst, b, h) do { _Pragma("unroll") for (int m = 0; m < 4; ++m) _Pragma("unroll") for (int k = 0; k < 2; ++k) dst[m][k] = *(const LAS bf16x8*)(lds + PG8_SA(b, h) + aoff + m * 2048 + k * 1024); } while (0)
; #define PG8_LDB(dst, b, h) do { _Pragma("unroll") for (int n = 0; n < 2; ++n) _Pragma("unroll") for (int k = 0; k < 2; ++k) dst[n][k] = *(const LAS bf16x8*)(lds + PG8_SB(b, h) + boff + n * 2048 + k * 1024); } while (0)
; #define PG8_BAR __builtin_amdgcn_s_barrier()
; template <class Epi, class Sched>
; __device__ __forceinline__ void gemm_phase(LAS unsigned char* lds, const Gemm g, const Sched& S, const Epi& E) {
;     ...
;     for (int t = 0; t < nt; t += 2) {
;       const bool last = (t == nt - 2);
;       const char* a1 = cA + (size_t)(t + 1) * kstep;
;       const char* a2 = last ? nA : cA + (size_t)(t + 2) * kstep; const char* b2 = last ? nB : cB + (size_t)(t + 2) * kstep;
;       const char* a3 = a2 + kstep; const char* b3 = b2 + kstep;
;       PG8_LDB(B0, 0, 0); PG8_SCHED; PG8_LDA(At, 0, 0); PG8_STAGE(PG8_SA(1, 1), a1 + hstepA, voffA);
;       PG8_WAIT_L(8); PG8_BAR; PG8_WAIT_L(0); PG8_MMA(0, 0, At, B0); PG8_BAR; PG8_SCHED;
;       PG8_LDB(B1, 0, 1); PG8_STAGE(PG8_SB(0, 0), b2, voffB);
;       PG8_BAR; PG8_WAIT_L(0); PG8_MMA(0, 1, At, B1); PG8_BAR;
;       PG8_LDA(At, 0, 1); PG8_STAGE(PG8_SA(0, 0), a2, voffA);
;       PG8_BAR; PG8_WAIT_L(0); PG8_MMA(1, 0, At, B0); PG8_BAR; PG8_SCHED;
;       PG8_STAGE(PG8_SB(0, 1), b2 + hstepB, voffB);
;       PG8_WAIT_V(6); PG8_BAR; PG8_MMA(1, 1, At, B1); PG8_BAR;
;       PG8_LDB(B0, 1, 0); PG8_SCHED; PG8_LDA(At, 1, 0); PG8_STAGE(PG8_SA(0, 1), a2 + hstepA, voffA);
;       PG8_WAIT_L(8); PG8_BAR; PG8_WAIT_L(0); PG8_MMA(0, 0, At, B0); PG8_BAR; PG8_SCHED;
;       PG8_LDB(B1, 1, 1); PG8_STAGE(PG8_SB(1, 0), b3, voffB);
;       PG8_BAR; PG8_WAIT_L(0); PG8_MMA(0, 1, At, B1); PG8_BAR;
;       PG8_LDA(At, 1, 1); PG8_STAGE(PG8_SA(1, 0), a3, voffA);
;       PG8_BAR; PG8_WAIT_L(0); PG8_MMA(1, 0, At, B0); PG8_BAR; PG8_SCHED;
;       PG8_STAGE(PG8_SB(1, 1), b3 + hstepB, voffB);
;       PG8_WAIT_V(6); PG8_BAR; PG8_MMA(1, 1, At, B1); PG8_BAR;
;     }
	s_add_u32 s76, s36, 0x40000
	s_addc_u32 s77, s37, 0
	s_add_i32 s87, s87, s25
	v_lshl_add_u64 v[136:137], s[76:77], 0, v[130:131]
	s_mov_b32 m0, s87
	s_nop 0
	global_load_lds_dwordx4 v[136:137], off
	v_lshl_add_u64 v[136:137], s[76:77], 0, v[128:129]
	s_add_i32 m0, s87, 0x2000
	s_nop 0
	global_load_lds_dwordx4 v[136:137], off
	s_waitcnt vmcnt(6)
	s_barrier
	v_mfma_f32_16x16x32_bf16 v[52:55], v[214:217], v[158:161], v[52:55]
	v_mfma_f32_16x16x32_bf16 v[44:47], v[222:225], v[158:161], v[44:47]
	v_mfma_f32_16x16x32_bf16 v[36:39], v[214:217], v[166:169], v[36:39]
	v_mfma_f32_16x16x32_bf16 v[28:31], v[222:225], v[166:169], v[28:31]
	v_mfma_f32_16x16x32_bf16 v[20:23], v[214:217], v[174:177], v[20:23]
	v_mfma_f32_16x16x32_bf16 v[12:15], v[222:225], v[174:177], v[12:15]
	v_mfma_f32_16x16x32_bf16 v[4:7], v[214:217], v[182:185], v[4:7]
	v_mfma_f32_16x16x32_bf16 v[0:3], v[222:225], v[182:185], v[0:3]
	v_mfma_f32_16x16x32_bf16 v[52:55], v[218:221], v[162:165], v[52:55]
	v_mfma_f32_16x16x32_bf16 v[44:47], v[226:229], v[162:165], v[44:47]
	v_mfma_f32_16x16x32_bf16 v[36:39], v[218:221], v[170:173], v[36:39]
	v_mfma_f32_16x16x32_bf16 v[28:31], v[226:229], v[170:173], v[28:31]
	v_mfma_f32_16x16x32_bf16 v[20:23], v[218:221], v[178:181], v[20:23]
	v_mfma_f32_16x16x32_bf16 v[12:15], v[226:229], v[178:181], v[12:15]
	v_mfma_f32_16x16x32_bf16 v[4:7], v[218:221], v[198:201], v[4:7]
	v_mfma_f32_16x16x32_bf16 v[0:3], v[226:229], v[198:201], v[0:3]
	s_add_i32 s76, 16, 0x18000
	v_add_u32_e32 v149, s76, v146
	s_barrier
	ds_read_b128 v[136:139], v149
	ds_read_b128 v[140:143], v149 offset:1024
	ds_read_b128 v[150:153], v149 offset:2048
	ds_read_b128 v[154:157], v149 offset:3072
	s_add_u32 s38, s38, 0x40000
	s_addc_u32 s39, s39, 0
	s_mov_b32 m0, s51
	v_lshl_add_u64 v[214:215], s[38:39], 0, v[130:131]
	ds_read_b128 v[158:161], v148 offset:32768
	ds_read_b128 v[162:165], v148 offset:33792
	ds_read_b128 v[166:169], v148 offset:34816
	ds_read_b128 v[170:173], v148 offset:35840
	ds_read_b128 v[174:177], v148 offset:36864
	ds_read_b128 v[178:181], v148 offset:37888
	ds_read_b128 v[182:185], v148 offset:38912
	ds_read_b128 v[198:201], v148 offset:39936
	global_load_lds_dwordx4 v[214:215], off
	v_lshl_add_u64 v[214:215], s[38:39], 0, v[128:129]
	s_mov_b32 m0, s58
	s_nop 0
	global_load_lds_dwordx4 v[214:215], off
	s_waitcnt lgkmcnt(8)
	s_barrier
	s_waitcnt lgkmcnt(0)
	s_waitcnt lgkmcnt(0)
	v_mfma_f32_16x16x32_bf16 v[124:127], v[136:139], v[158:161], v[124:127]
	v_mfma_f32_16x16x32_bf16 v[120:123], v[150:153], v[158:161], v[120:123]
	v_mfma_f32_16x16x32_bf16 v[112:115], v[136:139], v[166:169], v[112:115]
	v_mfma_f32_16x16x32_bf16 v[104:107], v[150:153], v[166:169], v[104:107]
	v_mfma_f32_16x16x32_bf16 v[96:99], v[136:139], v[174:177], v[96:99]
	v_mfma_f32_16x16x32_bf16 v[88:91], v[150:153], v[174:177], v[88:91]
	v_mfma_f32_16x16x32_bf16 v[80:83], v[136:139], v[182:185], v[80:83]
	v_mfma_f32_16x16x32_bf16 v[72:75], v[150:153], v[182:185], v[72:75]
	v_mfma_f32_16x16x32_bf16 v[124:127], v[140:143], v[162:165], v[124:127]
	v_mfma_f32_16x16x32_bf16 v[120:123], v[154:157], v[162:165], v[120:123]
	v_mfma_f32_16x16x32_bf16 v[112:115], v[140:143], v[170:173], v[112:115]
	v_mfma_f32_16x16x32_bf16 v[104:107], v[154:157], v[170:173], v[104:107]
	v_mfma_f32_16x16x32_bf16 v[96:99], v[140:143], v[178:181], v[96:99]
	v_mfma_f32_16x16x32_bf16 v[88:91], v[154:157], v[178:181], v[88:91]
	v_mfma_f32_16x16x32_bf16 v[80:83], v[140:143], v[198:201], v[80:83]
	v_mfma_f32_16x16x32_bf16 v[72:75], v[154:157], v[198:201], v[72:75]
	s_barrier
	s_add_i32 s38, 16, 0x1c000
	s_add_i32 s39, s76, s25
	v_add_u32_e32 v149, s38, v146
	v_lshl_add_u64 v[230:231], v[230:231], 0, s[62:63]
	s_mov_b32 m0, s39
	ds_read_b128 v[214:217], v149
	ds_read_b128 v[218:221], v149 offset:1024
	ds_read_b128 v[222:225], v149 offset:2048
	ds_read_b128 v[226:229], v149 offset:3072
	global_load_lds_dwordx4 v[230:231], off
	v_lshl_add_u64 v[230:231], v[232:233], 0, s[62:63]
	s_add_i32 m0, s39, 0x2000
	s_nop 0
	global_load_lds_dwordx4 v[230:231], off
	s_barrier
	s_waitcnt lgkmcnt(0)
	s_waitcnt lgkmcnt(0)
	v_mfma_f32_16x16x32_bf16 v[116:119], v[214:217], v[158:161], v[116:119]
	v_mfma_f32_16x16x32_bf16 v[108:111], v[222:225], v[158:161], v[108:111]
	v_mfma_f32_16x16x32_bf16 v[100:103], v[214:217], v[166:169], v[100:103]
	v_mfma_f32_16x16x32_bf16 v[92:95], v[222:225], v[166:169], v[92:95]
	v_mfma_f32_16x16x32_bf16 v[84:87], v[214:217], v[174:177], v[84:87]
	v_mfma_f32_16x16x32_bf16 v[76:79], v[222:225], v[174:177], v[76:79]
	v_mfma_f32_16x16x32_bf16 v[68:71], v[214:217], v[182:185], v[68:71]
	v_mfma_f32_16x16x32_bf16 v[64:67], v[222:225], v[182:185], v[64:67]
	v_mfma_f32_16x16x32_bf16 v[116:119], v[218:221], v[162:165], v[116:119]
	v_mfma_f32_16x16x32_bf16 v[108:111], v[226:229], v[162:165], v[108:111]
	v_mfma_f32_16x16x32_bf16 v[100:103], v[218:221], v[170:173], v[100:103]
	v_mfma_f32_16x16x32_bf16 v[92:95], v[226:229], v[170:173], v[92:95]
	v_mfma_f32_16x16x32_bf16 v[84:87], v[218:221], v[178:181], v[84:87]
	v_mfma_f32_16x16x32_bf16 v[76:79], v[226:229], v[178:181], v[76:79]
	v_mfma_f32_16x16x32_bf16 v[68:71], v[218:221], v[198:201], v[68:71]
	v_mfma_f32_16x16x32_bf16 v[64:67], v[226:229], v[198:201], v[64:67]
	s_mov_b32 m0, s69
	v_lshl_add_u64 v[230:231], v[234:235], 0, s[62:63]
	s_barrier
	ds_read_b128 v[158:161], v148 offset:49152
	ds_read_b128 v[162:165], v148 offset:50176
	ds_read_b128 v[166:169], v148 offset:51200
	ds_read_b128 v[170:173], v148 offset:52224
	ds_read_b128 v[174:177], v148 offset:53248
	ds_read_b128 v[178:181], v148 offset:54272
	ds_read_b128 v[182:185], v148 offset:55296
	ds_read_b128 v[198:201], v148 offset:56320
	global_load_lds_dwordx4 v[230:231], off
	v_lshl_add_u64 v[230:231], v[236:237], 0, s[62:63]
	s_mov_b32 m0, s74
	s_nop 0
	global_load_lds_dwordx4 v[230:231], off
	s_barrier
; #define PG8_STAGE(bufoff, gbase, voff) do { _Pragma("unroll") for (int _i = 0; _i < 2; ++_i) \
;     __builtin_amdgcn_global_load_lds((const unsigned*)((const char*)(gbase) + (voff)[_i]), (LAS unsigned*)(lds + (bufoff) + ldsw + _i * 8192), 16, 0, 0); } while (0)
; #define PG8_LDA(dst, b, h) do { _Pragma("unroll") for (int m = 0; m < 4; ++m) _Pragma("unroll") for (int k = 0; k < 2; ++k) dst[m][k] = *(const LAS bf16x8*)(lds + PG8_SA(b, h) + aoff + m * 2048 + k * 1024); } while (0)
; #define PG8_LDB(dst, b, h) do { _Pragma("unroll") for (int n = 0; n < 2; ++n) _Pragma("unroll") for (int k = 0; k < 2; ++k) dst[n][k] = *(const LAS bf16x8*)(lds + PG8_SB(b, h) + boff + n * 2048 + k * 1024); } while (0)
; #define PG8_BAR __builtin_amdgcn_s_barrier()
; template <class Epi, class Sched>
; __device__ __forceinline__ void gemm_phase(LAS unsigned char* lds, const Gemm g, const Sched& S, const Epi& E) {
;     ...
;     for (int t = 0; t < nt; t += 2) {
;       const bool last = (t == nt - 2);
;       const char* a1 = cA + (size_t)(t + 1) * kstep;
;       const char* a2 = last ? nA : cA + (size_t)(t + 2) * kstep; const char* b2 = last ? nB : cB + (size_t)(t + 2) * kstep;
;       const char* a3 = a2 + kstep; const char* b3 = b2 + kstep;
;       PG8_LDB(B0, 0, 0); PG8_SCHED; PG8_LDA(At, 0, 0); PG8_STAGE(PG8_SA(1, 1), a1 + hstepA, voffA);
;       PG8_WAIT_L(8); PG8_BAR; PG8_WAIT_L(0); PG8_MMA(0, 0, At, B0); PG8_BAR; PG8_SCHED;
;       PG8_LDB(B1, 0, 1); PG8_STAGE(PG8_SB(0, 0), b2, voffB);
;       PG8_BAR; PG8_WAIT_L(0); PG8_MMA(0, 1, At, B1); PG8_BAR;
;       PG8_LDA(At, 0, 1); PG8_STAGE(PG8_SA(0, 0), a2, voffA);
;       PG8_BAR; PG8_WAIT_L(0); PG8_MMA(1, 0, At, B0); PG8_BAR; PG8_SCHED;
;       PG8_STAGE(PG8_SB(0, 1), b2 + hstepB, voffB);
;       PG8_WAIT_V(6); PG8_BAR; PG8_MMA(1, 1, At, B1); PG8_BAR;
;       PG8_LDB(B0, 1, 0); PG8_SCHED; PG8_LDA(At, 1, 0); PG8_STAGE(PG8_SA(0, 1), a2 + hstepA, voffA);
;       PG8_WAIT_L(8); PG8_BAR; PG8_WAIT_L(0); PG8_MMA(0, 0, At, B0); PG8_BAR; PG8_SCHED;
;       PG8_LDB(B1, 1, 1); PG8_STAGE(PG8_SB(1, 0), b3, voffB);
;       PG8_BAR; PG8_WAIT_L(0); PG8_MMA(0, 1, At, B1); PG8_BAR;
;       PG8_LDA(At, 1, 1); PG8_STAGE(PG8_SA(1, 0), a3, voffA);
;       PG8_BAR; PG8_WAIT_L(0); PG8_MMA(1, 0, At, B0); PG8_BAR; PG8_SCHED;
;       PG8_STAGE(PG8_SB(1, 1), b3 + hstepB, voffB);
;       PG8_WAIT_V(6); PG8_BAR; PG8_MMA(1, 1, At, B1); PG8_BAR;
;     }
	s_waitcnt lgkmcnt(0)
	s_waitcnt lgkmcnt(0)
	v_mfma_f32_16x16x32_bf16 v[60:63], v[136:139], v[158:161], v[60:63]
	v_mfma_f32_16x16x32_bf16 v[56:59], v[150:153], v[158:161], v[56:59]
	v_mfma_f32_16x16x32_bf16 v[48:51], v[136:139], v[166:169], v[48:51]
	v_mfma_f32_16x16x32_bf16 v[40:43], v[150:153], v[166:169], v[40:43]
	v_mfma_f32_16x16x32_bf16 v[32:35], v[136:139], v[174:177], v[32:35]
	v_mfma_f32_16x16x32_bf16 v[24:27], v[150:153], v[174:177], v[24:27]
	v_mfma_f32_16x16x32_bf16 v[16:19], v[136:139], v[182:185], v[16:19]
	v_mfma_f32_16x16x32_bf16 v[8:11], v[150:153], v[182:185], v[8:11]
	v_mfma_f32_16x16x32_bf16 v[60:63], v[140:143], v[162:165], v[60:63]
	v_mfma_f32_16x16x32_bf16 v[56:59], v[154:157], v[162:165], v[56:59]
	v_mfma_f32_16x16x32_bf16 v[48:51], v[140:143], v[170:173], v[48:51]
	v_mfma_f32_16x16x32_bf16 v[40:43], v[154:157], v[170:173], v[40:43]
	v_mfma_f32_16x16x32_bf16 v[32:35], v[140:143], v[178:181], v[32:35]
	v_mfma_f32_16x16x32_bf16 v[24:27], v[154:157], v[178:181], v[24:27]
	v_mfma_f32_16x16x32_bf16 v[16:19], v[140:143], v[198:201], v[16:19]
	v_mfma_f32_16x16x32_bf16 v[8:11], v[154:157], v[198:201], v[8:11]
	s_barrier
	s_add_u32 s36, s36, 0x40080
	s_addc_u32 s37, s37, 0
	s_add_i32 s38, s38, s25
	v_lshl_add_u64 v[136:137], s[36:37], 0, v[130:131]
	s_mov_b32 m0, s38
	s_nop 0
	global_load_lds_dwordx4 v[136:137], off
	v_lshl_add_u64 v[136:137], s[36:37], 0, v[128:129]
	s_add_i32 m0, s38, 0x2000
	s_nop 0
	global_load_lds_dwordx4 v[136:137], off
	s_waitcnt vmcnt(6)
	s_barrier
	v_mfma_f32_16x16x32_bf16 v[52:55], v[214:217], v[158:161], v[52:55]
	v_mfma_f32_16x16x32_bf16 v[44:47], v[222:225], v[158:161], v[44:47]
	v_mfma_f32_16x16x32_bf16 v[36:39], v[214:217], v[166:169], v[36:39]
	v_mfma_f32_16x16x32_bf16 v[28:31], v[222:225], v[166:169], v[28:31]
	v_mfma_f32_16x16x32_bf16 v[20:23], v[214:217], v[174:177], v[20:23]
	v_mfma_f32_16x16x32_bf16 v[12:15], v[222:225], v[174:177], v[12:15]
	v_mfma_f32_16x16x32_bf16 v[4:7], v[214:217], v[182:185], v[4:7]
	v_mfma_f32_16x16x32_bf16 v[0:3], v[222:225], v[182:185], v[0:3]
	v_mfma_f32_16x16x32_bf16 v[52:55], v[218:221], v[162:165], v[52:55]
	v_mfma_f32_16x16x32_bf16 v[44:47], v[226:229], v[162:165], v[44:47]
	v_mfma_f32_16x16x32_bf16 v[36:39], v[218:221], v[170:173], v[36:39]
	v_mfma_f32_16x16x32_bf16 v[28:31], v[226:229], v[170:173], v[28:31]
	v_mfma_f32_16x16x32_bf16 v[20:23], v[218:221], v[178:181], v[20:23]
	v_mfma_f32_16x16x32_bf16 v[12:15], v[226:229], v[178:181], v[12:15]
	v_mfma_f32_16x16x32_bf16 v[4:7], v[218:221], v[198:201], v[4:7]
	v_mfma_f32_16x16x32_bf16 v[0:3], v[226:229], v[198:201], v[0:3]
	s_add_i32 s86, s86, 2
	s_add_u32 s28, s28, 0x100
	s_addc_u32 s29, s29, 0
	s_add_u32 s84, s84, 0x100
	s_addc_u32 s85, s85, 0
	s_cmp_gt_u32 s86, 13
	s_barrier
	s_cbranch_scc0 .LBB0_2633
	v_lshl_add_u32 v140, s79, 8, v145
	v_lshl_or_b32 v136, s78, 8, v147
	v_ashrrev_i32_e32 v141, 31, v140
	v_lshlrev_b64 v[138:139], 12, v[140:141]
	v_ashrrev_i32_e32 v137, 31, v136
	v_lshlrev_b64 v[142:143], 2, v[136:137]
	v_lshl_add_u64 v[136:137], s[14:15], 0, v[138:139]
	v_lshl_add_u64 v[138:139], s[16:17], 0, v[138:139]
	s_mov_b32 s28, 0xfff00000
	v_mov_b32_e32 v141, s66
	v_mov_b32_e32 v149, s68
	v_cmp_gt_i32_e32 vcc, s73, v140
	v_mov_b32_e32 v150, s59
	v_mov_b32_e32 v151, s67
	v_lshl_add_u64 v[138:139], v[138:139], 0, v[142:143]
	s_mov_b32 s29, -1
	v_cndmask_b32_e32 v153, v141, v149, vcc
	v_cndmask_b32_e32 v152, v150, v151, vcc
	v_lshl_add_u64 v[136:137], v[136:137], 0, v[142:143]
	v_lshl_add_u64 v[156:157], v[138:139], 0, s[28:29]
	v_lshl_add_u64 v[160:161], v[152:153], 0, v[142:143]
	v_cndmask_b32_e64 v163, v157, v137, s[8:9]
	v_cndmask_b32_e64 v162, v156, v136, s[8:9]
	global_load_dwordx4 v[214:217], v[160:161], off
	global_load_dwordx4 v[218:221], v[160:161], off offset:64
	global_load_dwordx4 v[222:225], v[160:161], off offset:512
	global_load_dwordx4 v[226:229], v[160:161], off offset:576
	global_load_dwordx4 v[230:233], v[162:163], off
	global_load_dwordx4 v[234:237], v[162:163], off offset:64
	global_load_dwordx4 v[238:241], v[162:163], off offset:512
	global_load_dwordx4 v[242:245], v[162:163], off offset:576
	s_mov_b32 s28, 0xfff10000
	s_mov_b32 s29, -1
	s_movk_i32 s19, 0x80
	s_mov_b32 s87, 0x80000
	s_mov_b32 s78, s18
	s_mov_b32 s79, s20
	s_mov_b64 s[36:37], s[26:27]
	s_movk_i32 s86, 0x4100
	s_waitcnt vmcnt(3)
	v_pk_fma_f32 v[126:127], v[126:127], v[216:217], v[232:233]
	v_pk_fma_f32 v[124:125], v[124:125], v[214:215], v[230:231]
	global_store_dwordx4 v[136:137], v[124:127], off
	s_nop 0
	s_waitcnt vmcnt(3)
	v_pk_fma_f32 v[122:123], v[122:123], v[220:221], v[236:237]
	v_pk_fma_f32 v[120:121], v[120:121], v[218:219], v[234:235]
	global_store_dwordx4 v[136:137], v[120:123], off offset:64
	s_nop 0
	v_lshl_add_u64 v[152:153], v[138:139], 0, s[28:29]
	s_mov_b32 s28, 0xfff20000
	s_mov_b32 s29, -1
	s_waitcnt vmcnt(3)
	v_pk_fma_f32 v[118:119], v[118:119], v[224:225], v[240:241]
	v_pk_fma_f32 v[116:117], v[116:117], v[222:223], v[238:239]
	global_store_dwordx4 v[136:137], v[116:119], off offset:512
	s_nop 0
	v_or_b32_e32 v124, 16, v140
	v_ashrrev_i32_e32 v125, 31, v124
	v_cmp_gt_i32_e32 vcc, s73, v124
	v_lshlrev_b64 v[124:125], 12, v[124:125]
	v_lshl_add_u64 v[124:125], s[14:15], 0, v[124:125]
	v_cndmask_b32_e32 v127, v141, v149, vcc
	v_cndmask_b32_e32 v126, v150, v151, vcc
	v_lshl_add_u64 v[126:127], v[126:127], 0, v[142:143]
	v_lshl_add_u64 v[124:125], v[124:125], 0, v[142:143]
	v_cndmask_b32_e64 v153, v153, v125, s[8:9]
	v_cndmask_b32_e64 v152, v152, v124, s[8:9]
	s_waitcnt vmcnt(3)
	v_pk_fma_f32 v[110:111], v[110:111], v[228:229], v[244:245]
	v_pk_fma_f32 v[108:109], v[108:109], v[226:227], v[242:243]
	global_store_dwordx4 v[136:137], v[108:111], off offset:576
	global_load_dwordx4 v[230:233], v[152:153], off
	global_load_dwordx4 v[234:237], v[152:153], off offset:64
	global_load_dwordx4 v[238:241], v[152:153], off offset:512
	global_load_dwordx4 v[242:245], v[152:153], off offset:576
	s_nop 0
	s_waitcnt vmcnt(3)
	v_pk_fma_f32 v[110:111], v[114:115], v[216:217], v[232:233]
	v_pk_fma_f32 v[108:109], v[112:113], v[214:215], v[230:231]
	global_store_dwordx4 v[124:125], v[108:111], off
	s_nop 0
	s_waitcnt vmcnt(3)
	v_pk_fma_f32 v[106:107], v[106:107], v[220:221], v[236:237]
	v_pk_fma_f32 v[104:105], v[104:105], v[218:219], v[234:235]
	global_store_dwordx4 v[124:125], v[104:107], off offset:64
	s_nop 0
	v_lshl_add_u64 v[112:113], v[138:139], 0, s[28:29]
	s_mov_b32 s28, 0xfff30000
	s_mov_b32 s29, -1
	s_waitcnt vmcnt(3)
	v_pk_fma_f32 v[102:103], v[102:103], v[224:225], v[240:241]
	v_pk_fma_f32 v[100:101], v[100:101], v[222:223], v[238:239]
	global_store_dwordx4 v[124:125], v[100:103], off offset:512
	s_nop 0
	v_or_b32_e32 v108, 32, v140
	v_ashrrev_i32_e32 v109, 31, v108
	v_cmp_gt_i32_e32 vcc, s73, v108
	v_lshlrev_b64 v[108:109], 12, v[108:109]
	v_lshl_add_u64 v[108:109], s[14:15], 0, v[108:109]
	v_cndmask_b32_e32 v111, v141, v149, vcc
	v_cndmask_b32_e32 v110, v150, v151, vcc
	v_lshl_add_u64 v[110:111], v[110:111], 0, v[142:143]
	v_lshl_add_u64 v[108:109], v[108:109], 0, v[142:143]
	v_cndmask_b32_e64 v113, v113, v109, s[8:9]
	v_cndmask_b32_e64 v112, v112, v108, s[8:9]
	s_waitcnt vmcnt(3)
	v_pk_fma_f32 v[94:95], v[94:95], v[228:229], v[244:245]
	v_pk_fma_f32 v[92:93], v[92:93], v[226:227], v[242:243]
	global_store_dwordx4 v[124:125], v[92:95], off offset:576
	global_load_dwordx4 v[230:233], v[112:113], off
	global_load_dwordx4 v[234:237], v[112:113], off offset:64
	global_load_dwordx4 v[238:241], v[112:113], off offset:512
	global_load_dwordx4 v[242:245], v[112:113], off offset:576
	s_nop 0
	s_waitcnt vmcnt(3)
	v_pk_fma_f32 v[94:95], v[98:99], v[216:217], v[232:233]
	v_pk_fma_f32 v[92:93], v[96:97], v[214:215], v[230:231]
	global_store_dwordx4 v[108:109], v[92:95], off
	s_nop 0
	s_waitcnt vmcnt(3)
	v_pk_fma_f32 v[90:91], v[90:91], v[220:221], v[236:237]
	v_pk_fma_f32 v[88:89], v[88:89], v[218:219], v[234:235]
	global_store_dwordx4 v[108:109], v[88:91], off offset:64
	s_nop 0
	v_lshl_add_u64 v[96:97], v[138:139], 0, s[28:29]
	s_mov_b64 s[28:29], 0x80000
	s_waitcnt vmcnt(3)
	v_pk_fma_f32 v[86:87], v[86:87], v[224:225], v[240:241]
	v_pk_fma_f32 v[84:85], v[84:85], v[222:223], v[238:239]
	global_store_dwordx4 v[108:109], v[84:87], off offset:512
	s_nop 0
	v_or_b32_e32 v92, 48, v140
	v_ashrrev_i32_e32 v93, 31, v92
	v_cmp_gt_i32_e32 vcc, s73, v92
	v_lshlrev_b64 v[92:93], 12, v[92:93]
	v_lshl_add_u64 v[92:93], s[14:15], 0, v[92:93]
	v_cndmask_b32_e32 v95, v141, v149, vcc
	v_cndmask_b32_e32 v94, v150, v151, vcc
	v_lshl_add_u64 v[94:95], v[94:95], 0, v[142:143]
	v_lshl_add_u64 v[92:93], v[92:93], 0, v[142:143]
	v_cndmask_b32_e64 v97, v97, v93, s[8:9]
	v_cndmask_b32_e64 v96, v96, v92, s[8:9]
	v_cmp_gt_i32_e32 vcc, s19, v140
	s_mov_b32 s19, 0x90000
	s_waitcnt vmcnt(3)
	v_pk_fma_f32 v[78:79], v[78:79], v[228:229], v[244:245]
	v_pk_fma_f32 v[76:77], v[76:77], v[226:227], v[242:243]
	global_store_dwordx4 v[108:109], v[76:79], off offset:576
	global_load_dwordx4 v[230:233], v[96:97], off
	global_load_dwordx4 v[234:237], v[96:97], off offset:64
	global_load_dwordx4 v[238:241], v[96:97], off offset:512
	global_load_dwordx4 v[242:245], v[96:97], off offset:576
	s_nop 0
	s_waitcnt vmcnt(3)
	v_pk_fma_f32 v[78:79], v[82:83], v[216:217], v[232:233]
	v_pk_fma_f32 v[76:77], v[80:81], v[214:215], v[230:231]
	global_store_dwordx4 v[92:93], v[76:79], off
	s_nop 0
	s_waitcnt vmcnt(3)
	v_pk_fma_f32 v[74:75], v[74:75], v[220:221], v[236:237]
	v_pk_fma_f32 v[72:73], v[72:73], v[218:219], v[234:235]
	global_store_dwordx4 v[92:93], v[72:75], off offset:64
	s_nop 0
	s_waitcnt vmcnt(3)
	v_pk_fma_f32 v[70:71], v[70:71], v[224:225], v[240:241]
	v_pk_fma_f32 v[68:69], v[68:69], v[222:223], v[238:239]
	global_store_dwordx4 v[92:93], v[68:71], off offset:512
	s_nop 0
	v_lshl_add_u64 v[78:79], v[136:137], 0, s[28:29]
	s_mov_b32 s28, 0xfff80000
	v_cndmask_b32_e32 v77, v141, v149, vcc
	v_cndmask_b32_e32 v76, v150, v151, vcc
	s_mov_b32 s29, -1
	v_lshl_add_u64 v[76:77], v[76:77], 0, v[142:143]
	v_lshl_add_u64 v[80:81], v[138:139], 0, s[28:29]
	v_cndmask_b32_e64 v81, v81, v79, s[8:9]
	v_cndmask_b32_e64 v80, v80, v78, s[8:9]
	s_mov_b64 s[28:29], 0x90000
	s_waitcnt vmcnt(3)
	v_pk_fma_f32 v[66:67], v[66:67], v[228:229], v[244:245]
	v_pk_fma_f32 v[64:65], v[64:65], v[226:227], v[242:243]
	global_store_dwordx4 v[92:93], v[64:67], off offset:576
	global_load_dwordx4 v[230:233], v[80:81], off
	global_load_dwordx4 v[234:237], v[80:81], off offset:64
	global_load_dwordx4 v[238:241], v[80:81], off offset:512
	global_load_dwordx4 v[242:245], v[80:81], off offset:576
	s_nop 0
	v_add_co_u32_e32 v72, vcc, s87, v136
	s_waitcnt vmcnt(3)
	v_pk_fma_f32 v[62:63], v[62:63], v[216:217], v[232:233]
	v_addc_co_u32_e32 v73, vcc, 0, v137, vcc
	v_pk_fma_f32 v[60:61], v[60:61], v[214:215], v[230:231]
	global_store_dwordx4 v[72:73], v[60:63], off
	s_nop 0
	v_cmp_gt_i32_e32 vcc, s40, v140
	s_waitcnt vmcnt(3)
; #define PG8_WAIT_V(n) asm volatile("s_waitcnt vmcnt(" #n ")" ::: "memory")
; #define PG8_BAR __builtin_amdgcn_s_barrier()
; template <class Epi, class Sched>
; __device__ __forceinline__ void gemm_phase(LAS unsigned char* lds, const Gemm g, const Sched& S, const Epi& E) {
;     ...
;     E(acc, cur, wr, wc, fr, fq);
;     if (!has_next) break;
; #pragma unroll
;     for (int a = 0; a < 2; ++a)
; #pragma unroll
;       for (int b = 0; b < 2; ++b)
; #pragma unroll
;         for (int m = 0; m < 4; ++m)
; #pragma unroll
;           for (int n = 0; n < 2; ++n) acc[a][b][m][n] = (f32x4){0.f, 0.f, 0.f, 0.f};
;     cur = nxt; cA = nA; cB = nB; ++ui;
;   }
;   PG8_WAIT_V(0);
;   if (wr == 0) PG8_BAR;
;   PG8_BAR;
	v_pk_fma_f32 v[58:59], v[58:59], v[220:221], v[236:237]
	v_pk_fma_f32 v[56:57], v[56:57], v[218:219], v[234:235]
	global_store_dwordx4 v[78:79], v[56:59], off offset:64
	s_nop 0
	s_waitcnt vmcnt(3)
	v_pk_fma_f32 v[54:55], v[54:55], v[224:225], v[240:241]
	v_pk_fma_f32 v[52:53], v[52:53], v[222:223], v[238:239]
	global_store_dwordx4 v[78:79], v[52:55], off offset:512
	s_nop 0
	v_lshl_add_u64 v[62:63], v[136:137], 0, s[28:29]
	s_mov_b32 s28, 0xfff90000
	v_cndmask_b32_e32 v61, v141, v149, vcc
	v_cndmask_b32_e32 v60, v150, v151, vcc
	s_mov_b32 s29, -1
	v_lshl_add_u64 v[60:61], v[60:61], 0, v[142:143]
	v_lshl_add_u64 v[64:65], v[138:139], 0, s[28:29]
	v_cndmask_b32_e64 v65, v65, v63, s[8:9]
	v_cndmask_b32_e64 v64, v64, v62, s[8:9]
	s_mov_b64 s[28:29], 0xa0000
	s_waitcnt vmcnt(3)
	v_pk_fma_f32 v[46:47], v[46:47], v[228:229], v[244:245]
	v_pk_fma_f32 v[44:45], v[44:45], v[226:227], v[242:243]
	global_store_dwordx4 v[78:79], v[44:47], off offset:576
	global_load_dwordx4 v[230:233], v[64:65], off
	global_load_dwordx4 v[234:237], v[64:65], off offset:64
	global_load_dwordx4 v[238:241], v[64:65], off offset:512
	global_load_dwordx4 v[242:245], v[64:65], off offset:576
	s_nop 0
	v_add_co_u32_e32 v56, vcc, s19, v136
	s_mov_b32 s19, 0xa0000
	s_nop 0
	v_addc_co_u32_e32 v57, vcc, 0, v137, vcc
	v_cmp_gt_i32_e32 vcc, s91, v140
	s_waitcnt vmcnt(3)
	v_pk_fma_f32 v[46:47], v[50:51], v[216:217], v[232:233]
	v_pk_fma_f32 v[44:45], v[48:49], v[214:215], v[230:231]
	global_store_dwordx4 v[56:57], v[44:47], off
	s_nop 0
	s_waitcnt vmcnt(3)
	v_pk_fma_f32 v[42:43], v[42:43], v[220:221], v[236:237]
	v_pk_fma_f32 v[40:41], v[40:41], v[218:219], v[234:235]
	global_store_dwordx4 v[62:63], v[40:43], off offset:64
	s_nop 0
	s_waitcnt vmcnt(3)
	v_pk_fma_f32 v[38:39], v[38:39], v[224:225], v[240:241]
	v_pk_fma_f32 v[36:37], v[36:37], v[222:223], v[238:239]
	global_store_dwordx4 v[62:63], v[36:39], off offset:512
	s_nop 0
	v_lshl_add_u64 v[46:47], v[136:137], 0, s[28:29]
	s_mov_b32 s28, 0xfffa0000
	v_cndmask_b32_e32 v45, v141, v149, vcc
	v_cndmask_b32_e32 v44, v150, v151, vcc
	s_mov_b32 s29, -1
	v_lshl_add_u64 v[44:45], v[44:45], 0, v[142:143]
	v_lshl_add_u64 v[48:49], v[138:139], 0, s[28:29]
	v_cndmask_b32_e64 v49, v49, v47, s[8:9]
	v_cndmask_b32_e64 v48, v48, v46, s[8:9]
	s_mov_b64 s[28:29], 0xb0000
	s_waitcnt vmcnt(3)
	v_pk_fma_f32 v[30:31], v[30:31], v[228:229], v[244:245]
	v_pk_fma_f32 v[28:29], v[28:29], v[226:227], v[242:243]
	global_store_dwordx4 v[62:63], v[28:31], off offset:576
	global_load_dwordx4 v[230:233], v[48:49], off
	global_load_dwordx4 v[234:237], v[48:49], off offset:64
	global_load_dwordx4 v[238:241], v[48:49], off offset:512
	global_load_dwordx4 v[242:245], v[48:49], off offset:576
	s_nop 0
	v_add_co_u32_e32 v40, vcc, s19, v136
	s_mov_b32 s19, 0xb0000
	s_nop 0
	v_addc_co_u32_e32 v41, vcc, 0, v137, vcc
	v_cmp_gt_i32_e32 vcc, s41, v140
	s_waitcnt vmcnt(3)
	v_pk_fma_f32 v[30:31], v[34:35], v[216:217], v[232:233]
	v_pk_fma_f32 v[28:29], v[32:33], v[214:215], v[230:231]
	global_store_dwordx4 v[40:41], v[28:31], off
	s_nop 0
	s_waitcnt vmcnt(3)
	v_pk_fma_f32 v[26:27], v[26:27], v[220:221], v[236:237]
	v_pk_fma_f32 v[24:25], v[24:25], v[218:219], v[234:235]
	global_store_dwordx4 v[46:47], v[24:27], off offset:64
	s_nop 0
	s_waitcnt vmcnt(3)
	v_pk_fma_f32 v[22:23], v[22:23], v[224:225], v[240:241]
	v_pk_fma_f32 v[20:21], v[20:21], v[222:223], v[238:239]
	global_store_dwordx4 v[46:47], v[20:23], off offset:512
	s_nop 0
	v_lshl_add_u64 v[30:31], v[136:137], 0, s[28:29]
	s_mov_b32 s28, 0xfffb0000
	v_cndmask_b32_e32 v29, v141, v149, vcc
	v_cndmask_b32_e32 v28, v150, v151, vcc
	s_mov_b32 s29, -1
	v_lshl_add_u64 v[28:29], v[28:29], 0, v[142:143]
	v_lshl_add_u64 v[32:33], v[138:139], 0, s[28:29]
	v_cndmask_b32_e64 v33, v33, v31, s[8:9]
	v_cndmask_b32_e64 v32, v32, v30, s[8:9]
	s_mov_b64 s[28:29], s[22:23]
	s_waitcnt vmcnt(3)
	v_pk_fma_f32 v[14:15], v[14:15], v[228:229], v[244:245]
	v_pk_fma_f32 v[12:13], v[12:13], v[226:227], v[242:243]
	global_store_dwordx4 v[46:47], v[12:15], off offset:576
	global_load_dwordx4 v[230:233], v[32:33], off
	global_load_dwordx4 v[234:237], v[32:33], off offset:64
	global_load_dwordx4 v[238:241], v[32:33], off offset:512
	global_load_dwordx4 v[242:245], v[32:33], off offset:576
	s_nop 0
	v_add_co_u32_e32 v24, vcc, s19, v136
	s_waitcnt vmcnt(3)
	v_pk_fma_f32 v[14:15], v[18:19], v[216:217], v[232:233]
	v_addc_co_u32_e32 v25, vcc, 0, v137, vcc
	v_pk_fma_f32 v[12:13], v[16:17], v[214:215], v[230:231]
	global_store_dwordx4 v[24:25], v[12:15], off
	s_nop 0
	s_and_b64 vcc, exec, s[10:11]
	s_waitcnt vmcnt(3)
	v_pk_fma_f32 v[10:11], v[10:11], v[220:221], v[236:237]
	v_pk_fma_f32 v[8:9], v[8:9], v[218:219], v[234:235]
	global_store_dwordx4 v[30:31], v[8:11], off offset:64
	s_nop 0
	s_waitcnt vmcnt(3)
	v_pk_fma_f32 v[6:7], v[6:7], v[224:225], v[240:241]
	v_pk_fma_f32 v[4:5], v[4:5], v[222:223], v[238:239]
	global_store_dwordx4 v[30:31], v[4:7], off offset:512
	s_nop 0
	s_waitcnt vmcnt(3)
	v_pk_fma_f32 v[2:3], v[2:3], v[228:229], v[244:245]
	v_pk_fma_f32 v[0:1], v[0:1], v[226:227], v[242:243]
	global_store_dwordx4 v[30:31], v[0:3], off offset:576
	s_cbranch_vccz .LBB0_2626
	s_waitcnt vmcnt(0)
	v_readlane_b32 s82, v255, 17
	v_readlane_b32 s68, v255, 20
	s_cmpk_gt_u32 s24, 0xff
	v_readlane_b32 s83, v255, 18
	s_mov_b32 s74, 0x8000
	s_mov_b32 s75, 0x10000
	s_movk_i32 s79, 0x40ff
	s_movk_i32 s78, 0x2000
	v_readlane_b32 s69, v255, 21
	v_readlane_b32 s59, v255, 19
	s_cbranch_scc1 .LBB0_2637
	s_barrier

; #define PG8_STAGE(bufoff, gbase, voff) do { _Pragma("unroll") for (int _i = 0; _i < 2; ++_i) \
;     __builtin_amdgcn_global_load_lds((const unsigned*)((const char*)(gbase) + (voff)[_i]), (LAS unsigned*)(lds + (bufoff) + ldsw + _i * 8192), 16, 0, 0); } while (0)
; #define PG8_LDA(dst, b, h) do { _Pragma("unroll") for (int m = 0; m < 4; ++m) _Pragma("unroll") for (int k = 0; k < 2; ++k) dst[m][k] = *(const LAS bf16x8*)(lds + PG8_SA(b, h) + aoff + m * 2048 + k * 1024); } while (0)
; #define PG8_LDB(dst, b, h) do { _Pragma("unroll") for (int n = 0; n < 2; ++n) _Pragma("unroll") for (int k = 0; k < 2; ++k) dst[n][k] = *(const LAS bf16x8*)(lds + PG8_SB(b, h) + boff + n * 2048 + k * 1024); } while (0)
; #define PG8_BAR __builtin_amdgcn_s_barrier()
; template <class Epi, class Sched>
; __device__ __forceinline__ void gemm_phase(LAS unsigned char* lds, const Gemm g, const Sched& S, const Epi& E) {
;     ...
;     for (int t = 0; t < nt; t += 2) {
;       const bool last = (t == nt - 2);
;       const char* a1 = cA + (size_t)(t + 1) * kstep;
;       const char* a2 = last ? nA : cA + (size_t)(t + 2) * kstep; const char* b2 = last ? nB : cB + (size_t)(t + 2) * kstep;
;       const char* a3 = a2 + kstep; const char* b3 = b2 + kstep;
;       PG8_LDB(B0, 0, 0); PG8_SCHED; PG8_LDA(At, 0, 0); PG8_STAGE(PG8_SA(1, 1), a1 + hstepA, voffA);
;       PG8_WAIT_L(8); PG8_BAR; PG8_WAIT_L(0); PG8_MMA(0, 0, At, B0); PG8_BAR; PG8_SCHED;
;       PG8_LDB(B1, 0, 1); PG8_STAGE(PG8_SB(0, 0), b2, voffB);
;       PG8_BAR; PG8_WAIT_L(0); PG8_MMA(0, 1, At, B1); PG8_BAR;
;       PG8_LDA(At, 0, 1); PG8_STAGE(PG8_SA(0, 0), a2, voffA);
;       PG8_BAR; PG8_WAIT_L(0); PG8_MMA(1, 0, At, B0); PG8_BAR; PG8_SCHED;
;       PG8_STAGE(PG8_SB(0, 1), b2 + hstepB, voffB);
;       PG8_WAIT_V(6); PG8_BAR; PG8_MMA(1, 1, At, B1); PG8_BAR;
;       PG8_LDB(B0, 1, 0); PG8_SCHED; PG8_LDA(At, 1, 0); PG8_STAGE(PG8_SA(0, 1), a2 + hstepA, voffA);
;       PG8_WAIT_L(8); PG8_BAR; PG8_WAIT_L(0); PG8_MMA(0, 0, At, B0); PG8_BAR; PG8_SCHED;
;       PG8_LDB(B1, 1, 1); PG8_STAGE(PG8_SB(1, 0), b3, voffB);
;       PG8_BAR; PG8_WAIT_L(0); PG8_MMA(0, 1, At, B1); PG8_BAR;
;       PG8_LDA(At, 1, 1); PG8_STAGE(PG8_SA(1, 0), a3, voffA);
;       PG8_BAR; PG8_WAIT_L(0); PG8_MMA(1, 0, At, B0); PG8_BAR; PG8_SCHED;
;       PG8_STAGE(PG8_SB(1, 1), b3 + hstepB, voffB);
;       PG8_WAIT_V(6); PG8_BAR; PG8_MMA(1, 1, At, B1); PG8_BAR;
;     }
.LBB0_2773:
	s_add_u32 s28, s26, 0xfffc0080
	s_addc_u32 s29, s27, -1
	s_add_i32 s76, 16, 0x10000
	v_add_u32_e32 v145, s76, v137
	ds_read_b128 v[140:143], v145
	ds_read_b128 v[146:149], v145 offset:1024
	ds_read_b128 v[150:153], v145 offset:2048
	ds_read_b128 v[154:157], v145 offset:3072
	s_cmp_eq_u32 s78, 12
	s_cselect_b32 s37, s15, s29
	s_cselect_b32 s36, s68, s28
	s_cselect_b32 s29, s11, s75
	s_cselect_b32 s28, s69, s74
	v_lshl_add_u64 v[214:215], s[26:27], 0, v[132:133]
	s_add_i32 m0, s21, 0xc000
	ds_read_b128 v[158:161], v139
	ds_read_b128 v[162:165], v139 offset:1024
	ds_read_b128 v[166:169], v139 offset:2048
	ds_read_b128 v[170:173], v139 offset:3072
	ds_read_b128 v[174:177], v139 offset:4096
	ds_read_b128 v[178:181], v139 offset:5120
	ds_read_b128 v[182:185], v139 offset:6144
	ds_read_b128 v[198:201], v139 offset:7168
	global_load_lds_dwordx4 v[214:215], off
	v_lshl_add_u64 v[214:215], s[26:27], 0, v[134:135]
	s_add_i32 m0, s21, 0xe000
	s_nop 0
	global_load_lds_dwordx4 v[214:215], off
	s_waitcnt lgkmcnt(8)
	s_barrier
	s_waitcnt lgkmcnt(0)
	s_waitcnt lgkmcnt(0)
	v_mfma_f32_16x16x32_bf16 v[124:127], v[140:143], v[158:161], v[124:127]
	v_mfma_f32_16x16x32_bf16 v[120:123], v[150:153], v[158:161], v[120:123]
	v_mfma_f32_16x16x32_bf16 v[112:115], v[140:143], v[166:169], v[112:115]
	v_mfma_f32_16x16x32_bf16 v[104:107], v[150:153], v[166:169], v[104:107]
	v_mfma_f32_16x16x32_bf16 v[96:99], v[140:143], v[174:177], v[96:99]
	v_mfma_f32_16x16x32_bf16 v[88:91], v[150:153], v[174:177], v[88:91]
	v_mfma_f32_16x16x32_bf16 v[80:83], v[140:143], v[182:185], v[80:83]
	v_mfma_f32_16x16x32_bf16 v[72:75], v[150:153], v[182:185], v[72:75]
	v_mfma_f32_16x16x32_bf16 v[124:127], v[146:149], v[162:165], v[124:127]
	v_mfma_f32_16x16x32_bf16 v[120:123], v[154:157], v[162:165], v[120:123]
	v_mfma_f32_16x16x32_bf16 v[112:115], v[146:149], v[170:173], v[112:115]
	v_mfma_f32_16x16x32_bf16 v[104:107], v[154:157], v[170:173], v[104:107]
	v_mfma_f32_16x16x32_bf16 v[96:99], v[146:149], v[178:181], v[96:99]
	v_mfma_f32_16x16x32_bf16 v[88:91], v[154:157], v[178:181], v[88:91]
	v_mfma_f32_16x16x32_bf16 v[80:83], v[146:149], v[198:201], v[80:83]
	v_mfma_f32_16x16x32_bf16 v[72:75], v[154:157], v[198:201], v[72:75]
	s_barrier
	s_add_i32 s79, 16, 0x14000
	s_add_i32 s76, s76, s48
	v_add_u32_e32 v145, s79, v137
	v_lshl_add_u64 v[230:231], s[28:29], 0, v[130:131]
	s_mov_b32 m0, s76
	ds_read_b128 v[214:217], v145
	ds_read_b128 v[218:221], v145 offset:1024
	ds_read_b128 v[222:225], v145 offset:2048
	ds_read_b128 v[226:229], v145 offset:3072
	global_load_lds_dwordx4 v[230:231], off
	v_lshl_add_u64 v[232:233], s[28:29], 0, v[128:129]
	s_add_i32 m0, s76, 0x2000
	s_nop 0
	global_load_lds_dwordx4 v[232:233], off
	s_barrier
	s_waitcnt lgkmcnt(0)
	s_waitcnt lgkmcnt(0)
	v_mfma_f32_16x16x32_bf16 v[116:119], v[214:217], v[158:161], v[116:119]
	v_mfma_f32_16x16x32_bf16 v[108:111], v[222:225], v[158:161], v[108:111]
	v_mfma_f32_16x16x32_bf16 v[100:103], v[214:217], v[166:169], v[100:103]
	v_mfma_f32_16x16x32_bf16 v[92:95], v[222:225], v[166:169], v[92:95]
	v_mfma_f32_16x16x32_bf16 v[84:87], v[214:217], v[174:177], v[84:87]
	v_mfma_f32_16x16x32_bf16 v[76:79], v[222:225], v[174:177], v[76:79]
	v_mfma_f32_16x16x32_bf16 v[68:71], v[214:217], v[182:185], v[68:71]
	v_mfma_f32_16x16x32_bf16 v[64:67], v[222:225], v[182:185], v[64:67]
	v_mfma_f32_16x16x32_bf16 v[116:119], v[218:221], v[162:165], v[116:119]
	v_mfma_f32_16x16x32_bf16 v[108:111], v[226:229], v[162:165], v[108:111]
	v_mfma_f32_16x16x32_bf16 v[100:103], v[218:221], v[170:173], v[100:103]
	v_mfma_f32_16x16x32_bf16 v[92:95], v[226:229], v[170:173], v[92:95]
	v_mfma_f32_16x16x32_bf16 v[84:87], v[218:221], v[178:181], v[84:87]
	v_mfma_f32_16x16x32_bf16 v[76:79], v[226:229], v[178:181], v[76:79]
	v_mfma_f32_16x16x32_bf16 v[68:71], v[218:221], v[198:201], v[68:71]
	v_mfma_f32_16x16x32_bf16 v[64:67], v[226:229], v[198:201], v[64:67]
	s_mov_b32 m0, s21
	v_lshl_add_u64 v[234:235], s[36:37], 0, v[130:131]
	s_barrier
	ds_read_b128 v[158:161], v139 offset:16384
	ds_read_b128 v[162:165], v139 offset:17408
	ds_read_b128 v[166:169], v139 offset:18432
	ds_read_b128 v[170:173], v139 offset:19456
	ds_read_b128 v[174:177], v139 offset:20480
	ds_read_b128 v[178:181], v139 offset:21504
	ds_read_b128 v[182:185], v139 offset:22528
	ds_read_b128 v[198:201], v139 offset:23552
	global_load_lds_dwordx4 v[234:235], off
	v_lshl_add_u64 v[236:237], s[36:37], 0, v[128:129]
	s_mov_b32 m0, s23
	s_nop 0
	global_load_lds_dwordx4 v[236:237], off
	s_barrier
	s_waitcnt lgkmcnt(0)
	s_waitcnt lgkmcnt(0)
	v_mfma_f32_16x16x32_bf16 v[60:63], v[140:143], v[158:161], v[60:63]
	v_mfma_f32_16x16x32_bf16 v[56:59], v[150:153], v[158:161], v[56:59]
	v_mfma_f32_16x16x32_bf16 v[48:51], v[140:143], v[166:169], v[48:51]
	v_mfma_f32_16x16x32_bf16 v[40:43], v[150:153], v[166:169], v[40:43]
	v_mfma_f32_16x16x32_bf16 v[32:35], v[140:143], v[174:177], v[32:35]
	v_mfma_f32_16x16x32_bf16 v[24:27], v[150:153], v[174:177], v[24:27]
	v_mfma_f32_16x16x32_bf16 v[16:19], v[140:143], v[182:185], v[16:19]
	v_mfma_f32_16x16x32_bf16 v[8:11], v[150:153], v[182:185], v[8:11]
	v_mfma_f32_16x16x32_bf16 v[60:63], v[146:149], v[162:165], v[60:63]
	v_mfma_f32_16x16x32_bf16 v[56:59], v[154:157], v[162:165], v[56:59]
	v_mfma_f32_16x16x32_bf16 v[48:51], v[146:149], v[170:173], v[48:51]
	v_mfma_f32_16x16x32_bf16 v[40:43], v[154:157], v[170:173], v[40:43]
	v_mfma_f32_16x16x32_bf16 v[32:35], v[146:149], v[178:181], v[32:35]
	v_mfma_f32_16x16x32_bf16 v[24:27], v[154:157], v[178:181], v[24:27]
	v_mfma_f32_16x16x32_bf16 v[16:19], v[146:149], v[198:201], v[16:19]
	v_mfma_f32_16x16x32_bf16 v[8:11], v[154:157], v[198:201], v[8:11]
	s_barrier
; #define PG8_STAGE(bufoff, gbase, voff) do { _Pragma("unroll") for (int _i = 0; _i < 2; ++_i) \
;     __builtin_amdgcn_global_load_lds((const unsigned*)((const char*)(gbase) + (voff)[_i]), (LAS unsigned*)(lds + (bufoff) + ldsw + _i * 8192), 16, 0, 0); } while (0)
; #define PG8_LDA(dst, b, h) do { _Pragma("unroll") for (int m = 0; m < 4; ++m) _Pragma("unroll") for (int k = 0; k < 2; ++k) dst[m][k] = *(const LAS bf16x8*)(lds + PG8_SA(b, h) + aoff + m * 2048 + k * 1024); } while (0)
; #define PG8_LDB(dst, b, h) do { _Pragma("unroll") for (int n = 0; n < 2; ++n) _Pragma("unroll") for (int k = 0; k < 2; ++k) dst[n][k] = *(const LAS bf16x8*)(lds + PG8_SB(b, h) + boff + n * 2048 + k * 1024); } while (0)
; #define PG8_BAR __builtin_amdgcn_s_barrier()
; template <class Epi, class Sched>
; __device__ __forceinline__ void gemm_phase(LAS unsigned char* lds, const Gemm g, const Sched& S, const Epi& E) {
;     ...
;     for (int t = 0; t < nt; t += 2) {
;       const bool last = (t == nt - 2);
;       const char* a1 = cA + (size_t)(t + 1) * kstep;
;       const char* a2 = last ? nA : cA + (size_t)(t + 2) * kstep; const char* b2 = last ? nB : cB + (size_t)(t + 2) * kstep;
;       const char* a3 = a2 + kstep; const char* b3 = b2 + kstep;
;       PG8_LDB(B0, 0, 0); PG8_SCHED; PG8_LDA(At, 0, 0); PG8_STAGE(PG8_SA(1, 1), a1 + hstepA, voffA);
;       PG8_WAIT_L(8); PG8_BAR; PG8_WAIT_L(0); PG8_MMA(0, 0, At, B0); PG8_BAR; PG8_SCHED;
;       PG8_LDB(B1, 0, 1); PG8_STAGE(PG8_SB(0, 0), b2, voffB);
;       PG8_BAR; PG8_WAIT_L(0); PG8_MMA(0, 1, At, B1); PG8_BAR;
;       PG8_LDA(At, 0, 1); PG8_STAGE(PG8_SA(0, 0), a2, voffA);
;       PG8_BAR; PG8_WAIT_L(0); PG8_MMA(1, 0, At, B0); PG8_BAR; PG8_SCHED;
;       PG8_STAGE(PG8_SB(0, 1), b2 + hstepB, voffB);
;       PG8_WAIT_V(6); PG8_BAR; PG8_MMA(1, 1, At, B1); PG8_BAR;
;       PG8_LDB(B0, 1, 0); PG8_SCHED; PG8_LDA(At, 1, 0); PG8_STAGE(PG8_SA(0, 1), a2 + hstepA, voffA);
;       PG8_WAIT_L(8); PG8_BAR; PG8_WAIT_L(0); PG8_MMA(0, 0, At, B0); PG8_BAR; PG8_SCHED;
;       PG8_LDB(B1, 1, 1); PG8_STAGE(PG8_SB(1, 0), b3, voffB);
;       PG8_BAR; PG8_WAIT_L(0); PG8_MMA(0, 1, At, B1); PG8_BAR;
;       PG8_LDA(At, 1, 1); PG8_STAGE(PG8_SA(1, 0), a3, voffA);
;       PG8_BAR; PG8_WAIT_L(0); PG8_MMA(1, 0, At, B0); PG8_BAR; PG8_SCHED;
;       PG8_STAGE(PG8_SB(1, 1), b3 + hstepB, voffB);
;       PG8_WAIT_V(6); PG8_BAR; PG8_MMA(1, 1, At, B1); PG8_BAR;
;     }
	s_add_u32 s76, s28, 0x40000
	s_addc_u32 s77, s29, 0
	s_add_i32 s79, s79, s48
	v_lshl_add_u64 v[140:141], s[76:77], 0, v[130:131]
	s_mov_b32 m0, s79
	s_nop 0
	global_load_lds_dwordx4 v[140:141], off
	v_lshl_add_u64 v[140:141], s[76:77], 0, v[128:129]
	s_add_i32 m0, s79, 0x2000
	s_nop 0
	global_load_lds_dwordx4 v[140:141], off
	s_waitcnt vmcnt(6)
	s_barrier
	v_mfma_f32_16x16x32_bf16 v[52:55], v[214:217], v[158:161], v[52:55]
	v_mfma_f32_16x16x32_bf16 v[44:47], v[222:225], v[158:161], v[44:47]
	v_mfma_f32_16x16x32_bf16 v[36:39], v[214:217], v[166:169], v[36:39]
	v_mfma_f32_16x16x32_bf16 v[28:31], v[222:225], v[166:169], v[28:31]
	v_mfma_f32_16x16x32_bf16 v[20:23], v[214:217], v[174:177], v[20:23]
	v_mfma_f32_16x16x32_bf16 v[12:15], v[222:225], v[174:177], v[12:15]
	v_mfma_f32_16x16x32_bf16 v[4:7], v[214:217], v[182:185], v[4:7]
	v_mfma_f32_16x16x32_bf16 v[0:3], v[222:225], v[182:185], v[0:3]
	v_mfma_f32_16x16x32_bf16 v[52:55], v[218:221], v[162:165], v[52:55]
	v_mfma_f32_16x16x32_bf16 v[44:47], v[226:229], v[162:165], v[44:47]
	v_mfma_f32_16x16x32_bf16 v[36:39], v[218:221], v[170:173], v[36:39]
	v_mfma_f32_16x16x32_bf16 v[28:31], v[226:229], v[170:173], v[28:31]
	v_mfma_f32_16x16x32_bf16 v[20:23], v[218:221], v[178:181], v[20:23]
	v_mfma_f32_16x16x32_bf16 v[12:15], v[226:229], v[178:181], v[12:15]
	v_mfma_f32_16x16x32_bf16 v[4:7], v[218:221], v[198:201], v[4:7]
	v_mfma_f32_16x16x32_bf16 v[0:3], v[226:229], v[198:201], v[0:3]
	s_add_i32 s76, 16, 0x18000
	v_add_u32_e32 v145, s76, v137
	s_barrier
	ds_read_b128 v[140:143], v145
	ds_read_b128 v[146:149], v145 offset:1024
	ds_read_b128 v[150:153], v145 offset:2048
	ds_read_b128 v[154:157], v145 offset:3072
	s_add_u32 s36, s36, 0x40000
	s_addc_u32 s37, s37, 0
	s_mov_b32 m0, s51
	v_lshl_add_u64 v[214:215], s[36:37], 0, v[130:131]
	ds_read_b128 v[158:161], v139 offset:32768
	ds_read_b128 v[162:165], v139 offset:33792
	ds_read_b128 v[166:169], v139 offset:34816
	ds_read_b128 v[170:173], v139 offset:35840
	ds_read_b128 v[174:177], v139 offset:36864
	ds_read_b128 v[178:181], v139 offset:37888
	ds_read_b128 v[182:185], v139 offset:38912
	ds_read_b128 v[198:201], v139 offset:39936
	global_load_lds_dwordx4 v[214:215], off
	v_lshl_add_u64 v[214:215], s[36:37], 0, v[128:129]
	s_mov_b32 m0, s58
	s_nop 0
	global_load_lds_dwordx4 v[214:215], off
	s_waitcnt lgkmcnt(8)
	s_barrier
	s_waitcnt lgkmcnt(0)
	s_waitcnt lgkmcnt(0)
	v_mfma_f32_16x16x32_bf16 v[124:127], v[140:143], v[158:161], v[124:127]
	v_mfma_f32_16x16x32_bf16 v[120:123], v[150:153], v[158:161], v[120:123]
	v_mfma_f32_16x16x32_bf16 v[112:115], v[140:143], v[166:169], v[112:115]
	v_mfma_f32_16x16x32_bf16 v[104:107], v[150:153], v[166:169], v[104:107]
	v_mfma_f32_16x16x32_bf16 v[96:99], v[140:143], v[174:177], v[96:99]
	v_mfma_f32_16x16x32_bf16 v[88:91], v[150:153], v[174:177], v[88:91]
	v_mfma_f32_16x16x32_bf16 v[80:83], v[140:143], v[182:185], v[80:83]
	v_mfma_f32_16x16x32_bf16 v[72:75], v[150:153], v[182:185], v[72:75]
	v_mfma_f32_16x16x32_bf16 v[124:127], v[146:149], v[162:165], v[124:127]
	v_mfma_f32_16x16x32_bf16 v[120:123], v[154:157], v[162:165], v[120:123]
	v_mfma_f32_16x16x32_bf16 v[112:115], v[146:149], v[170:173], v[112:115]
	v_mfma_f32_16x16x32_bf16 v[104:107], v[154:157], v[170:173], v[104:107]
	v_mfma_f32_16x16x32_bf16 v[96:99], v[146:149], v[178:181], v[96:99]
	v_mfma_f32_16x16x32_bf16 v[88:91], v[154:157], v[178:181], v[88:91]
	v_mfma_f32_16x16x32_bf16 v[80:83], v[146:149], v[198:201], v[80:83]
	v_mfma_f32_16x16x32_bf16 v[72:75], v[154:157], v[198:201], v[72:75]
	s_barrier
	s_add_i32 s36, 16, 0x1c000
	s_add_i32 s37, s76, s48
	v_add_u32_e32 v145, s36, v137
	v_lshl_add_u64 v[230:231], v[230:231], 0, s[62:63]
	s_mov_b32 m0, s37
	ds_read_b128 v[214:217], v145
	ds_read_b128 v[218:221], v145 offset:1024
	ds_read_b128 v[222:225], v145 offset:2048
	ds_read_b128 v[226:229], v145 offset:3072
	global_load_lds_dwordx4 v[230:231], off
	v_lshl_add_u64 v[230:231], v[232:233], 0, s[62:63]
	s_add_i32 m0, s37, 0x2000
	s_nop 0
	global_load_lds_dwordx4 v[230:231], off
	s_barrier
	s_waitcnt lgkmcnt(0)
	s_waitcnt lgkmcnt(0)
	v_mfma_f32_16x16x32_bf16 v[116:119], v[214:217], v[158:161], v[116:119]
	v_mfma_f32_16x16x32_bf16 v[108:111], v[222:225], v[158:161], v[108:111]
	v_mfma_f32_16x16x32_bf16 v[100:103], v[214:217], v[166:169], v[100:103]
	v_mfma_f32_16x16x32_bf16 v[92:95], v[222:225], v[166:169], v[92:95]
	v_mfma_f32_16x16x32_bf16 v[84:87], v[214:217], v[174:177], v[84:87]
	v_mfma_f32_16x16x32_bf16 v[76:79], v[222:225], v[174:177], v[76:79]
	v_mfma_f32_16x16x32_bf16 v[68:71], v[214:217], v[182:185], v[68:71]
	v_mfma_f32_16x16x32_bf16 v[64:67], v[222:225], v[182:185], v[64:67]
	v_mfma_f32_16x16x32_bf16 v[116:119], v[218:221], v[162:165], v[116:119]
	v_mfma_f32_16x16x32_bf16 v[108:111], v[226:229], v[162:165], v[108:111]
	v_mfma_f32_16x16x32_bf16 v[100:103], v[218:221], v[170:173], v[100:103]
	v_mfma_f32_16x16x32_bf16 v[92:95], v[226:229], v[170:173], v[92:95]
	v_mfma_f32_16x16x32_bf16 v[84:87], v[218:221], v[178:181], v[84:87]
	v_mfma_f32_16x16x32_bf16 v[76:79], v[226:229], v[178:181], v[76:79]
	v_mfma_f32_16x16x32_bf16 v[68:71], v[218:221], v[198:201], v[68:71]
	v_mfma_f32_16x16x32_bf16 v[64:67], v[226:229], v[198:201], v[64:67]
	s_mov_b32 m0, s59
	v_lshl_add_u64 v[230:231], v[234:235], 0, s[62:63]
	s_barrier
	ds_read_b128 v[158:161], v139 offset:49152
	ds_read_b128 v[162:165], v139 offset:50176
	ds_read_b128 v[166:169], v139 offset:51200
	ds_read_b128 v[170:173], v139 offset:52224
	ds_read_b128 v[174:177], v139 offset:53248
	ds_read_b128 v[178:181], v139 offset:54272
	ds_read_b128 v[182:185], v139 offset:55296
	ds_read_b128 v[198:201], v139 offset:56320
	global_load_lds_dwordx4 v[230:231], off
	v_lshl_add_u64 v[230:231], v[236:237], 0, s[62:63]
	s_mov_b32 m0, s66
	s_nop 0
	global_load_lds_dwordx4 v[230:231], off
	s_barrier
; #define PG8_STAGE(bufoff, gbase, voff) do { _Pragma("unroll") for (int _i = 0; _i < 2; ++_i) \
;     __builtin_amdgcn_global_load_lds((const unsigned*)((const char*)(gbase) + (voff)[_i]), (LAS unsigned*)(lds + (bufoff) + ldsw + _i * 8192), 16, 0, 0); } while (0)
; #define PG8_LDA(dst, b, h) do { _Pragma("unroll") for (int m = 0; m < 4; ++m) _Pragma("unroll") for (int k = 0; k < 2; ++k) dst[m][k] = *(const LAS bf16x8*)(lds + PG8_SA(b, h) + aoff + m * 2048 + k * 1024); } while (0)
; #define PG8_LDB(dst, b, h) do { _Pragma("unroll") for (int n = 0; n < 2; ++n) _Pragma("unroll") for (int k = 0; k < 2; ++k) dst[n][k] = *(const LAS bf16x8*)(lds + PG8_SB(b, h) + boff + n * 2048 + k * 1024); } while (0)
; #define PG8_BAR __builtin_amdgcn_s_barrier()
; template <class Epi, class Sched>
; __device__ __forceinline__ void gemm_phase(LAS unsigned char* lds, const Gemm g, const Sched& S, const Epi& E) {
;     ...
;     for (int t = 0; t < nt; t += 2) {
;       const bool last = (t == nt - 2);
;       const char* a1 = cA + (size_t)(t + 1) * kstep;
;       const char* a2 = last ? nA : cA + (size_t)(t + 2) * kstep; const char* b2 = last ? nB : cB + (size_t)(t + 2) * kstep;
;       const char* a3 = a2 + kstep; const char* b3 = b2 + kstep;
;       PG8_LDB(B0, 0, 0); PG8_SCHED; PG8_LDA(At, 0, 0); PG8_STAGE(PG8_SA(1, 1), a1 + hstepA, voffA);
;       PG8_WAIT_L(8); PG8_BAR; PG8_WAIT_L(0); PG8_MMA(0, 0, At, B0); PG8_BAR; PG8_SCHED;
;       PG8_LDB(B1, 0, 1); PG8_STAGE(PG8_SB(0, 0), b2, voffB);
;       PG8_BAR; PG8_WAIT_L(0); PG8_MMA(0, 1, At, B1); PG8_BAR;
;       PG8_LDA(At, 0, 1); PG8_STAGE(PG8_SA(0, 0), a2, voffA);
;       PG8_BAR; PG8_WAIT_L(0); PG8_MMA(1, 0, At, B0); PG8_BAR; PG8_SCHED;
;       PG8_STAGE(PG8_SB(0, 1), b2 + hstepB, voffB);
;       PG8_WAIT_V(6); PG8_BAR; PG8_MMA(1, 1, At, B1); PG8_BAR;
;       PG8_LDB(B0, 1, 0); PG8_SCHED; PG8_LDA(At, 1, 0); PG8_STAGE(PG8_SA(0, 1), a2 + hstepA, voffA);
;       PG8_WAIT_L(8); PG8_BAR; PG8_WAIT_L(0); PG8_MMA(0, 0, At, B0); PG8_BAR; PG8_SCHED;
;       PG8_LDB(B1, 1, 1); PG8_STAGE(PG8_SB(1, 0), b3, voffB);
;       PG8_BAR; PG8_WAIT_L(0); PG8_MMA(0, 1, At, B1); PG8_BAR;
;       PG8_LDA(At, 1, 1); PG8_STAGE(PG8_SA(1, 0), a3, voffA);
;       PG8_BAR; PG8_WAIT_L(0); PG8_MMA(1, 0, At, B0); PG8_BAR; PG8_SCHED;
;       PG8_STAGE(PG8_SB(1, 1), b3 + hstepB, voffB);
;       PG8_WAIT_V(6); PG8_BAR; PG8_MMA(1, 1, At, B1); PG8_BAR;
;     }
	s_waitcnt lgkmcnt(0)
	s_waitcnt lgkmcnt(0)
	v_mfma_f32_16x16x32_bf16 v[60:63], v[140:143], v[158:161], v[60:63]
	v_mfma_f32_16x16x32_bf16 v[56:59], v[150:153], v[158:161], v[56:59]
	v_mfma_f32_16x16x32_bf16 v[48:51], v[140:143], v[166:169], v[48:51]
	v_mfma_f32_16x16x32_bf16 v[40:43], v[150:153], v[166:169], v[40:43]
	v_mfma_f32_16x16x32_bf16 v[32:35], v[140:143], v[174:177], v[32:35]
	v_mfma_f32_16x16x32_bf16 v[24:27], v[150:153], v[174:177], v[24:27]
	v_mfma_f32_16x16x32_bf16 v[16:19], v[140:143], v[182:185], v[16:19]
	v_mfma_f32_16x16x32_bf16 v[8:11], v[150:153], v[182:185], v[8:11]
	v_mfma_f32_16x16x32_bf16 v[60:63], v[146:149], v[162:165], v[60:63]
	v_mfma_f32_16x16x32_bf16 v[56:59], v[154:157], v[162:165], v[56:59]
	v_mfma_f32_16x16x32_bf16 v[48:51], v[146:149], v[170:173], v[48:51]
	v_mfma_f32_16x16x32_bf16 v[40:43], v[154:157], v[170:173], v[40:43]
	v_mfma_f32_16x16x32_bf16 v[32:35], v[146:149], v[178:181], v[32:35]
	v_mfma_f32_16x16x32_bf16 v[24:27], v[154:157], v[178:181], v[24:27]
	v_mfma_f32_16x16x32_bf16 v[16:19], v[146:149], v[198:201], v[16:19]
	v_mfma_f32_16x16x32_bf16 v[8:11], v[154:157], v[198:201], v[8:11]
	s_barrier
	s_add_u32 s28, s28, 0x40080
	s_addc_u32 s29, s29, 0
	s_add_i32 s36, s36, s48
	v_lshl_add_u64 v[140:141], s[28:29], 0, v[130:131]
	s_mov_b32 m0, s36
	s_nop 0
	global_load_lds_dwordx4 v[140:141], off
	v_lshl_add_u64 v[140:141], s[28:29], 0, v[128:129]
	s_add_i32 m0, s36, 0x2000
	s_nop 0
	global_load_lds_dwordx4 v[140:141], off
	s_waitcnt vmcnt(6)
	s_barrier
	v_mfma_f32_16x16x32_bf16 v[52:55], v[214:217], v[158:161], v[52:55]
	v_mfma_f32_16x16x32_bf16 v[44:47], v[222:225], v[158:161], v[44:47]
	v_mfma_f32_16x16x32_bf16 v[36:39], v[214:217], v[166:169], v[36:39]
	v_mfma_f32_16x16x32_bf16 v[28:31], v[222:225], v[166:169], v[28:31]
	v_mfma_f32_16x16x32_bf16 v[20:23], v[214:217], v[174:177], v[20:23]
	v_mfma_f32_16x16x32_bf16 v[12:15], v[222:225], v[174:177], v[12:15]
	v_mfma_f32_16x16x32_bf16 v[4:7], v[214:217], v[182:185], v[4:7]
	v_mfma_f32_16x16x32_bf16 v[0:3], v[222:225], v[182:185], v[0:3]
	v_mfma_f32_16x16x32_bf16 v[52:55], v[218:221], v[162:165], v[52:55]
	v_mfma_f32_16x16x32_bf16 v[44:47], v[226:229], v[162:165], v[44:47]
	v_mfma_f32_16x16x32_bf16 v[36:39], v[218:221], v[170:173], v[36:39]
	v_mfma_f32_16x16x32_bf16 v[28:31], v[226:229], v[170:173], v[28:31]
	v_mfma_f32_16x16x32_bf16 v[20:23], v[218:221], v[178:181], v[20:23]
	v_mfma_f32_16x16x32_bf16 v[12:15], v[226:229], v[178:181], v[12:15]
	v_mfma_f32_16x16x32_bf16 v[4:7], v[218:221], v[198:201], v[4:7]
	v_mfma_f32_16x16x32_bf16 v[0:3], v[226:229], v[198:201], v[0:3]
	s_add_i32 s78, s78, 2
	s_add_u32 s26, s26, 0x100
	s_addc_u32 s27, s27, 0
	s_add_u32 s74, s74, 0x100
	s_addc_u32 s75, s75, 0
	s_cmp_gt_u32 s78, 13
	s_barrier
	s_cbranch_scc0 .LBB0_2773
	v_max_f32_e32 v124, v124, v124
	v_max_f32_e32 v124, 0, v124
	v_mul_f32_e32 v145, v124, v124
	v_max_f32_e32 v124, v125, v125
	v_max_f32_e32 v124, 0, v124
	v_mul_f32_e32 v146, v124, v124
	v_max_f32_e32 v124, v126, v126
	v_max_f32_e32 v124, 0, v124
	v_lshl_add_u32 v140, s22, 8, v136
	v_mul_f32_e32 v147, v124, v124
	v_max_f32_e32 v124, v127, v127
	v_lshl_or_b32 v142, s20, 8, v138
	v_and_b32_e32 v250, 16, v187
	v_lshrrev_b32_e32 v251, 2, v250
	v_sub_u32_e32 v250, v250, v251
	v_add_u32_e32 v142, v142, v250
	v_ashrrev_i32_e32 v141, 31, v140
	v_max_f32_e32 v124, 0, v124
	v_mul_f32_e32 v148, v124, v124
	v_lshlrev_b64 v[124:125], 13, v[140:141]
	v_ashrrev_i32_e32 v143, 31, v142
	v_max_f32_e32 v120, v120, v120
	v_max_f32_e32 v121, v121, v121
	v_max_f32_e32 v116, v116, v116
	v_max_f32_e32 v117, v117, v117
	v_max_f32_e32 v108, v108, v108
	v_lshl_add_u64 v[124:125], s[12:13], 0, v[124:125]
	v_lshlrev_b64 v[126:127], 1, v[142:143]
	v_max_f32_e32 v120, 0, v120
	v_max_f32_e32 v121, 0, v121
	v_max_f32_e32 v122, v122, v122
	v_max_f32_e32 v123, v123, v123
	v_max_f32_e32 v116, 0, v116
	v_max_f32_e32 v117, 0, v117
	v_max_f32_e32 v118, v118, v118
	v_max_f32_e32 v119, v119, v119
	v_max_f32_e32 v108, 0, v108
	v_max_f32_e32 v109, v109, v109
	v_lshl_add_u64 v[124:125], v[124:125], 0, v[126:127]
	v_mul_f32_e32 v120, v120, v120
	v_mul_f32_e32 v121, v121, v121
	v_max_f32_e32 v122, 0, v122
	v_max_f32_e32 v123, 0, v123
	v_mul_f32_e32 v116, v116, v116
	v_mul_f32_e32 v117, v117, v117
	v_max_f32_e32 v118, 0, v118
	v_max_f32_e32 v119, 0, v119
	v_mul_f32_e32 v108, v108, v108
	v_max_f32_e32 v109, 0, v109
	v_max_f32_e32 v110, v110, v110
	v_max_f32_e32 v111, v111, v111
	v_cvt_pk_bf16_f32 v238, v145, v146
	v_cvt_pk_bf16_f32 v239, v147, v148
	v_mul_f32_e32 v122, v122, v122
	v_mul_f32_e32 v123, v123, v123
	v_cvt_pk_bf16_f32 v240, v120, v121
	v_cvt_pk_bf16_f32 v241, v122, v123
	s_nop 1
	v_permlane16_swap_b32_e32 v238, v240
	v_permlane16_swap_b32_e32 v239, v241
	global_store_dwordx4 v[124:125], v[238:241], off
	v_mul_f32_e32 v118, v118, v118
	v_mul_f32_e32 v119, v119, v119
	v_cvt_pk_bf16_f32 v242, v116, v117
	v_cvt_pk_bf16_f32 v243, v118, v119
	v_mul_f32_e32 v109, v109, v109
	v_max_f32_e32 v110, 0, v110
	v_max_f32_e32 v111, 0, v111
	v_cvt_pk_bf16_f32 v244, v108, v109
	v_mul_f32_e32 v110, v110, v110
	v_mul_f32_e32 v111, v111, v111
	v_cvt_pk_bf16_f32 v245, v110, v111
	s_nop 1
	v_permlane16_swap_b32_e32 v242, v244
	v_permlane16_swap_b32_e32 v243, v245
	global_store_dwordx4 v[124:125], v[242:245], off offset:256
	v_or_b32_e32 v108, 16, v140
	v_ashrrev_i32_e32 v109, 31, v108
	v_max_f32_e32 v110, v112, v112
	v_max_f32_e32 v111, v113, v113
	v_lshlrev_b64 v[108:109], 13, v[108:109]
	v_max_f32_e32 v104, v104, v104
	v_max_f32_e32 v105, v105, v105
	v_max_f32_e32 v100, v100, v100
	v_max_f32_e32 v101, v101, v101
	v_max_f32_e32 v92, v92, v92
	v_max_f32_e32 v110, 0, v110
	v_max_f32_e32 v111, 0, v111
	v_max_f32_e32 v112, v114, v114
	v_max_f32_e32 v113, v115, v115
	v_lshl_add_u64 v[108:109], s[12:13], 0, v[108:109]
	v_max_f32_e32 v104, 0, v104
	v_max_f32_e32 v105, 0, v105
	v_max_f32_e32 v106, v106, v106
	v_max_f32_e32 v107, v107, v107
	v_max_f32_e32 v100, 0, v100
	v_max_f32_e32 v101, 0, v101
	v_max_f32_e32 v102, v102, v102
	v_max_f32_e32 v103, v103, v103
	v_max_f32_e32 v92, 0, v92
	v_max_f32_e32 v93, v93, v93
	v_mul_f32_e32 v110, v110, v110
	v_mul_f32_e32 v111, v111, v111
	v_max_f32_e32 v112, 0, v112
	v_max_f32_e32 v113, 0, v113
	v_lshl_add_u64 v[108:109], v[108:109], 0, v[126:127]
	v_mul_f32_e32 v104, v104, v104
	v_mul_f32_e32 v105, v105, v105
	v_max_f32_e32 v106, 0, v106
	v_max_f32_e32 v107, 0, v107
	v_mul_f32_e32 v100, v100, v100
	v_mul_f32_e32 v101, v101, v101
	v_max_f32_e32 v102, 0, v102
	v_max_f32_e32 v103, 0, v103
	v_mul_f32_e32 v92, v92, v92
	v_max_f32_e32 v93, 0, v93
	v_max_f32_e32 v94, v94, v94
	v_max_f32_e32 v95, v95, v95
	v_mul_f32_e32 v112, v112, v112
	v_mul_f32_e32 v113, v113, v113
	v_cvt_pk_bf16_f32 v246, v110, v111
	v_cvt_pk_bf16_f32 v247, v112, v113
	v_mul_f32_e32 v106, v106, v106
	v_mul_f32_e32 v107, v107, v107
	v_cvt_pk_bf16_f32 v248, v104, v105
	v_cvt_pk_bf16_f32 v249, v106, v107
	s_nop 1
	v_permlane16_swap_b32_e32 v246, v248
	v_permlane16_swap_b32_e32 v247, v249
	global_store_dwordx4 v[108:109], v[246:249], off
	v_mul_f32_e32 v102, v102, v102
	v_mul_f32_e32 v103, v103, v103
	v_cvt_pk_bf16_f32 v238, v100, v101
	v_cvt_pk_bf16_f32 v239, v102, v103
	v_mul_f32_e32 v93, v93, v93
	v_max_f32_e32 v94, 0, v94
	v_max_f32_e32 v95, 0, v95
	v_cvt_pk_bf16_f32 v240, v92, v93
	v_mul_f32_e32 v94, v94, v94
	v_mul_f32_e32 v95, v95, v95
	v_cvt_pk_bf16_f32 v241, v94, v95
	s_nop 1
	v_permlane16_swap_b32_e32 v238, v240
	v_permlane16_swap_b32_e32 v239, v241
	global_store_dwordx4 v[108:109], v[238:241], off offset:256
	v_or_b32_e32 v92, 32, v140
	v_ashrrev_i32_e32 v93, 31, v92
	v_max_f32_e32 v94, v96, v96
	v_max_f32_e32 v95, v97, v97
	v_lshlrev_b64 v[92:93], 13, v[92:93]
	v_max_f32_e32 v88, v88, v88
	v_max_f32_e32 v89, v89, v89
	v_max_f32_e32 v84, v84, v84
	v_max_f32_e32 v85, v85, v85
	v_max_f32_e32 v76, v76, v76
	v_max_f32_e32 v94, 0, v94
	v_max_f32_e32 v95, 0, v95
	v_max_f32_e32 v96, v98, v98
	v_max_f32_e32 v97, v99, v99
	v_lshl_add_u64 v[92:93], s[12:13], 0, v[92:93]
	v_max_f32_e32 v88, 0, v88
	v_max_f32_e32 v89, 0, v89
	v_max_f32_e32 v90, v90, v90
	v_max_f32_e32 v91, v91, v91
	v_max_f32_e32 v84, 0, v84
	v_max_f32_e32 v85, 0, v85
	v_max_f32_e32 v86, v86, v86
	v_max_f32_e32 v87, v87, v87
	v_max_f32_e32 v76, 0, v76
	v_max_f32_e32 v77, v77, v77
	v_mul_f32_e32 v94, v94, v94
	v_mul_f32_e32 v95, v95, v95
	v_max_f32_e32 v96, 0, v96
	v_max_f32_e32 v97, 0, v97
	v_lshl_add_u64 v[92:93], v[92:93], 0, v[126:127]
	v_mul_f32_e32 v88, v88, v88
	v_mul_f32_e32 v89, v89, v89
	v_max_f32_e32 v90, 0, v90
	v_max_f32_e32 v91, 0, v91
	v_mul_f32_e32 v84, v84, v84
	v_mul_f32_e32 v85, v85, v85
	v_max_f32_e32 v86, 0, v86
	v_max_f32_e32 v87, 0, v87
	v_mul_f32_e32 v76, v76, v76
	v_max_f32_e32 v77, 0, v77
	v_max_f32_e32 v78, v78, v78
	v_max_f32_e32 v79, v79, v79
	v_mul_f32_e32 v96, v96, v96
	v_mul_f32_e32 v97, v97, v97
	v_cvt_pk_bf16_f32 v242, v94, v95
	v_cvt_pk_bf16_f32 v243, v96, v97
	v_mul_f32_e32 v90, v90, v90
	v_mul_f32_e32 v91, v91, v91
	v_cvt_pk_bf16_f32 v244, v88, v89
	v_cvt_pk_bf16_f32 v245, v90, v91
	s_nop 1
	v_permlane16_swap_b32_e32 v242, v244
	v_permlane16_swap_b32_e32 v243, v245
	global_store_dwordx4 v[92:93], v[242:245], off
	v_mul_f32_e32 v86, v86, v86
	v_mul_f32_e32 v87, v87, v87
	v_cvt_pk_bf16_f32 v246, v84, v85
	v_cvt_pk_bf16_f32 v247, v86, v87
	v_mul_f32_e32 v77, v77, v77
	v_max_f32_e32 v78, 0, v78
	v_max_f32_e32 v79, 0, v79
	v_cvt_pk_bf16_f32 v248, v76, v77
	v_mul_f32_e32 v78, v78, v78
	v_mul_f32_e32 v79, v79, v79
	v_cvt_pk_bf16_f32 v249, v78, v79
	s_nop 1
	v_permlane16_swap_b32_e32 v246, v248
	v_permlane16_swap_b32_e32 v247, v249
	global_store_dwordx4 v[92:93], v[246:249], off offset:256
	v_or_b32_e32 v76, 48, v140
	v_ashrrev_i32_e32 v77, 31, v76
	v_max_f32_e32 v78, v80, v80
	v_max_f32_e32 v79, v81, v81
	v_lshlrev_b64 v[76:77], 13, v[76:77]
	v_max_f32_e32 v72, v72, v72
	v_max_f32_e32 v73, v73, v73
	v_max_f32_e32 v68, v68, v68
	v_max_f32_e32 v69, v69, v69
	v_max_f32_e32 v64, v64, v64
	v_max_f32_e32 v78, 0, v78
	v_max_f32_e32 v79, 0, v79
	v_max_f32_e32 v80, v82, v82
	v_max_f32_e32 v81, v83, v83
	v_lshl_add_u64 v[76:77], s[12:13], 0, v[76:77]
	v_max_f32_e32 v72, 0, v72
	v_max_f32_e32 v73, 0, v73
	v_max_f32_e32 v74, v74, v74
	v_max_f32_e32 v75, v75, v75
	v_max_f32_e32 v68, 0, v68
	v_max_f32_e32 v69, 0, v69
	v_max_f32_e32 v70, v70, v70
	v_max_f32_e32 v71, v71, v71
	v_max_f32_e32 v64, 0, v64
	v_max_f32_e32 v65, v65, v65
	v_mul_f32_e32 v78, v78, v78
	v_mul_f32_e32 v79, v79, v79
	v_max_f32_e32 v80, 0, v80
	v_max_f32_e32 v81, 0, v81
	v_lshl_add_u64 v[76:77], v[76:77], 0, v[126:127]
	v_mul_f32_e32 v72, v72, v72
	v_mul_f32_e32 v73, v73, v73
	v_max_f32_e32 v74, 0, v74
	v_max_f32_e32 v75, 0, v75
	v_mul_f32_e32 v68, v68, v68
	v_mul_f32_e32 v69, v69, v69
	v_max_f32_e32 v70, 0, v70
	v_max_f32_e32 v71, 0, v71
	v_mul_f32_e32 v64, v64, v64
	v_max_f32_e32 v65, 0, v65
	v_max_f32_e32 v66, v66, v66
	v_max_f32_e32 v67, v67, v67
	v_max_f32_e32 v60, v60, v60
	v_mul_f32_e32 v80, v80, v80
	v_mul_f32_e32 v81, v81, v81
	v_cvt_pk_bf16_f32 v238, v78, v79
	v_cvt_pk_bf16_f32 v239, v80, v81
	v_mul_f32_e32 v74, v74, v74
	v_mul_f32_e32 v75, v75, v75
	v_cvt_pk_bf16_f32 v240, v72, v73
	v_cvt_pk_bf16_f32 v241, v74, v75
	s_nop 1
	v_permlane16_swap_b32_e32 v238, v240
	v_permlane16_swap_b32_e32 v239, v241
	global_store_dwordx4 v[76:77], v[238:241], off
	v_mul_f32_e32 v70, v70, v70
	v_mul_f32_e32 v71, v71, v71
	v_cvt_pk_bf16_f32 v242, v68, v69
	v_cvt_pk_bf16_f32 v243, v70, v71
	v_mul_f32_e32 v65, v65, v65
	v_max_f32_e32 v66, 0, v66
	v_max_f32_e32 v67, 0, v67
	v_cvt_pk_bf16_f32 v244, v64, v65
	v_max_f32_e32 v60, 0, v60
	v_mul_f32_e32 v66, v66, v66
	v_mul_f32_e32 v67, v67, v67
	v_cvt_pk_bf16_f32 v245, v66, v67
	s_nop 1
	v_permlane16_swap_b32_e32 v242, v244
	v_permlane16_swap_b32_e32 v243, v245
	global_store_dwordx4 v[76:77], v[242:245], off offset:256
	v_mul_f32_e32 v64, v60, v60
	v_max_f32_e32 v60, v61, v61
	v_max_f32_e32 v60, 0, v60
	v_mul_f32_e32 v65, v60, v60
	v_max_f32_e32 v60, v62, v62
	v_max_f32_e32 v60, 0, v60
	v_mul_f32_e32 v66, v60, v60
	v_max_f32_e32 v60, v63, v63
	s_mov_b32 s11, 0x100000
	v_max_f32_e32 v56, v56, v56
	v_max_f32_e32 v57, v57, v57
	v_max_f32_e32 v52, v52, v52
	v_max_f32_e32 v53, v53, v53
	v_max_f32_e32 v44, v44, v44
	v_max_f32_e32 v60, 0, v60
	s_mov_b64 s[26:27], 0x100000
	v_cvt_pk_bf16_f32 v246, v64, v65
	v_add_co_u32_e32 v64, vcc, s11, v124
	v_max_f32_e32 v56, 0, v56
	v_max_f32_e32 v57, 0, v57
	v_max_f32_e32 v58, v58, v58
	v_max_f32_e32 v59, v59, v59
	v_max_f32_e32 v52, 0, v52
	v_max_f32_e32 v53, 0, v53
	v_max_f32_e32 v54, v54, v54
	v_max_f32_e32 v55, v55, v55
	v_max_f32_e32 v44, 0, v44
	v_max_f32_e32 v45, v45, v45
	v_mul_f32_e32 v63, v60, v60
	v_lshl_add_u64 v[60:61], v[124:125], 0, s[26:27]
	v_addc_co_u32_e32 v65, vcc, 0, v125, vcc
	v_mul_f32_e32 v56, v56, v56
	v_mul_f32_e32 v57, v57, v57
	v_max_f32_e32 v58, 0, v58
	v_max_f32_e32 v59, 0, v59
	v_mul_f32_e32 v52, v52, v52
	v_mul_f32_e32 v53, v53, v53
	v_max_f32_e32 v54, 0, v54
	v_max_f32_e32 v55, 0, v55
	v_mul_f32_e32 v44, v44, v44
	v_max_f32_e32 v45, 0, v45
	v_max_f32_e32 v46, v46, v46
	v_max_f32_e32 v47, v47, v47
	v_cvt_pk_bf16_f32 v247, v66, v63
	v_mul_f32_e32 v58, v58, v58
	v_mul_f32_e32 v59, v59, v59
	v_cvt_pk_bf16_f32 v248, v56, v57
	v_cvt_pk_bf16_f32 v249, v58, v59
	s_nop 1
	v_permlane16_swap_b32_e32 v246, v248
	v_permlane16_swap_b32_e32 v247, v249
	global_store_dwordx4 v[60:61], v[246:249], off
	v_mul_f32_e32 v54, v54, v54
	v_mul_f32_e32 v55, v55, v55
	v_cvt_pk_bf16_f32 v238, v52, v53
	v_cvt_pk_bf16_f32 v239, v54, v55
	v_mul_f32_e32 v45, v45, v45
	v_max_f32_e32 v46, 0, v46
	v_max_f32_e32 v47, 0, v47
	v_cvt_pk_bf16_f32 v240, v44, v45
	v_mul_f32_e32 v46, v46, v46
	v_mul_f32_e32 v47, v47, v47
	v_cvt_pk_bf16_f32 v241, v46, v47
	s_nop 1
	v_permlane16_swap_b32_e32 v238, v240
	v_permlane16_swap_b32_e32 v239, v241
	global_store_dwordx4 v[60:61], v[238:241], off offset:256
	v_max_f32_e32 v44, v48, v48
	v_max_f32_e32 v44, 0, v44
	v_mul_f32_e32 v46, v44, v44
	v_max_f32_e32 v44, v49, v49
	v_max_f32_e32 v44, 0, v44
	v_mul_f32_e32 v47, v44, v44
	v_max_f32_e32 v44, v50, v50
	v_max_f32_e32 v44, 0, v44
	v_mul_f32_e32 v48, v44, v44
	v_max_f32_e32 v44, v51, v51
	v_max_f32_e32 v44, 0, v44
	s_mov_b32 s11, 0x120000
	v_max_f32_e32 v40, v40, v40
	v_max_f32_e32 v41, v41, v41
	v_max_f32_e32 v36, v36, v36
	v_max_f32_e32 v37, v37, v37
	v_max_f32_e32 v28, v28, v28
	v_mul_f32_e32 v49, v44, v44
	s_mov_b64 s[26:27], 0x120000
	v_cvt_pk_bf16_f32 v242, v46, v47
	v_cvt_pk_bf16_f32 v243, v48, v49
	v_add_co_u32_e32 v48, vcc, s11, v124
	v_max_f32_e32 v40, 0, v40
	v_max_f32_e32 v41, 0, v41
	v_max_f32_e32 v42, v42, v42
	v_max_f32_e32 v43, v43, v43
	v_max_f32_e32 v36, 0, v36
	v_max_f32_e32 v37, 0, v37
	v_max_f32_e32 v38, v38, v38
	v_max_f32_e32 v39, v39, v39
	v_max_f32_e32 v28, 0, v28
	v_max_f32_e32 v29, v29, v29
	v_lshl_add_u64 v[44:45], v[124:125], 0, s[26:27]
	v_addc_co_u32_e32 v49, vcc, 0, v125, vcc
	v_mul_f32_e32 v40, v40, v40
	v_mul_f32_e32 v41, v41, v41
	v_max_f32_e32 v42, 0, v42
	v_max_f32_e32 v43, 0, v43
	v_mul_f32_e32 v36, v36, v36
	v_mul_f32_e32 v37, v37, v37
	v_max_f32_e32 v38, 0, v38
	v_max_f32_e32 v39, 0, v39
	v_mul_f32_e32 v28, v28, v28
	v_max_f32_e32 v29, 0, v29
	v_max_f32_e32 v30, v30, v30
	v_max_f32_e32 v31, v31, v31
	v_mul_f32_e32 v42, v42, v42
	v_mul_f32_e32 v43, v43, v43
	v_cvt_pk_bf16_f32 v244, v40, v41
	v_cvt_pk_bf16_f32 v245, v42, v43
	s_nop 1
	v_permlane16_swap_b32_e32 v242, v244
	v_permlane16_swap_b32_e32 v243, v245
	global_store_dwordx4 v[44:45], v[242:245], off
	v_mul_f32_e32 v38, v38, v38
	v_mul_f32_e32 v39, v39, v39
	v_cvt_pk_bf16_f32 v246, v36, v37
	v_cvt_pk_bf16_f32 v247, v38, v39
	v_mul_f32_e32 v29, v29, v29
	v_max_f32_e32 v30, 0, v30
	v_max_f32_e32 v31, 0, v31
	v_cvt_pk_bf16_f32 v248, v28, v29
	v_mul_f32_e32 v30, v30, v30
	v_mul_f32_e32 v31, v31, v31
	v_cvt_pk_bf16_f32 v249, v30, v31
	s_nop 1
; #define PG8_WAIT_V(n) asm volatile("s_waitcnt vmcnt(" #n ")" ::: "memory")
; #define PG8_BAR __builtin_amdgcn_s_barrier()
; template <class Epi, class Sched>
; __device__ __forceinline__ void gemm_phase(LAS unsigned char* lds, const Gemm g, const Sched& S, const Epi& E) {
;     ...
;     E(acc, cur, wr, wc, fr, fq);
;     if (!has_next) break;
; #pragma unroll
;     for (int a = 0; a < 2; ++a)
; #pragma unroll
;       for (int b = 0; b < 2; ++b)
; #pragma unroll
;         for (int m = 0; m < 4; ++m)
; #pragma unroll
;           for (int n = 0; n < 2; ++n) acc[a][b][m][n] = (f32x4){0.f, 0.f, 0.f, 0.f};
;     cur = nxt; cA = nA; cB = nB; ++ui;
;   }
;   PG8_WAIT_V(0);
;   if (wr == 0) PG8_BAR;
;   PG8_BAR;
	v_permlane16_swap_b32_e32 v246, v248
	v_permlane16_swap_b32_e32 v247, v249
	global_store_dwordx4 v[44:45], v[246:249], off offset:256
	v_max_f32_e32 v28, v32, v32
	v_max_f32_e32 v28, 0, v28
	v_mul_f32_e32 v30, v28, v28
	v_max_f32_e32 v28, v33, v33
	v_max_f32_e32 v28, 0, v28
	v_mul_f32_e32 v31, v28, v28
	v_max_f32_e32 v28, v34, v34
	v_max_f32_e32 v28, 0, v28
	v_mul_f32_e32 v32, v28, v28
	v_max_f32_e32 v28, v35, v35
	v_max_f32_e32 v28, 0, v28
	s_mov_b32 s11, 0x140000
	v_max_f32_e32 v24, v24, v24
	v_max_f32_e32 v25, v25, v25
	v_max_f32_e32 v20, v20, v20
	v_max_f32_e32 v21, v21, v21
	v_max_f32_e32 v12, v12, v12
	v_mul_f32_e32 v33, v28, v28
	s_mov_b64 s[26:27], 0x140000
	v_cvt_pk_bf16_f32 v238, v30, v31
	v_cvt_pk_bf16_f32 v239, v32, v33
	v_add_co_u32_e32 v32, vcc, s11, v124
	v_max_f32_e32 v24, 0, v24
	v_max_f32_e32 v25, 0, v25
	v_max_f32_e32 v26, v26, v26
	v_max_f32_e32 v27, v27, v27
	v_max_f32_e32 v20, 0, v20
	v_max_f32_e32 v21, 0, v21
	v_max_f32_e32 v22, v22, v22
	v_max_f32_e32 v23, v23, v23
	v_max_f32_e32 v12, 0, v12
	v_max_f32_e32 v13, v13, v13
	v_lshl_add_u64 v[28:29], v[124:125], 0, s[26:27]
	v_addc_co_u32_e32 v33, vcc, 0, v125, vcc
	v_mul_f32_e32 v24, v24, v24
	v_mul_f32_e32 v25, v25, v25
	v_max_f32_e32 v26, 0, v26
	v_max_f32_e32 v27, 0, v27
	v_mul_f32_e32 v20, v20, v20
	v_mul_f32_e32 v21, v21, v21
	v_max_f32_e32 v22, 0, v22
	v_max_f32_e32 v23, 0, v23
	v_mul_f32_e32 v12, v12, v12
	v_max_f32_e32 v13, 0, v13
	v_max_f32_e32 v14, v14, v14
	v_max_f32_e32 v15, v15, v15
	v_mul_f32_e32 v26, v26, v26
	v_mul_f32_e32 v27, v27, v27
	v_cvt_pk_bf16_f32 v240, v24, v25
	v_cvt_pk_bf16_f32 v241, v26, v27
	s_nop 1
	v_permlane16_swap_b32_e32 v238, v240
	v_permlane16_swap_b32_e32 v239, v241
	global_store_dwordx4 v[28:29], v[238:241], off
	v_mul_f32_e32 v22, v22, v22
	v_mul_f32_e32 v23, v23, v23
	v_cvt_pk_bf16_f32 v242, v20, v21
	v_cvt_pk_bf16_f32 v243, v22, v23
	v_mul_f32_e32 v13, v13, v13
	v_max_f32_e32 v14, 0, v14
	v_max_f32_e32 v15, 0, v15
	v_cvt_pk_bf16_f32 v244, v12, v13
	v_mul_f32_e32 v14, v14, v14
	v_mul_f32_e32 v15, v15, v15
	v_cvt_pk_bf16_f32 v245, v14, v15
	s_nop 1
	v_permlane16_swap_b32_e32 v242, v244
	v_permlane16_swap_b32_e32 v243, v245
	global_store_dwordx4 v[28:29], v[242:245], off offset:256
	v_max_f32_e32 v12, v16, v16
	v_max_f32_e32 v12, 0, v12
	v_mul_f32_e32 v14, v12, v12
	v_max_f32_e32 v12, v17, v17
	v_max_f32_e32 v12, 0, v12
	v_mul_f32_e32 v15, v12, v12
	v_max_f32_e32 v12, v18, v18
	v_max_f32_e32 v12, 0, v12
	v_mul_f32_e32 v16, v12, v12
	v_max_f32_e32 v12, v19, v19
	v_max_f32_e32 v12, 0, v12
	s_mov_b32 s11, 0x160000
	v_mul_f32_e32 v17, v12, v12
	v_cvt_pk_bf16_f32 v246, v14, v15
	v_cvt_pk_bf16_f32 v247, v16, v17
	v_add_co_u32_e32 v16, vcc, s11, v124
	v_max_f32_e32 v8, v8, v8
	v_max_f32_e32 v9, v9, v9
	v_max_f32_e32 v4, v4, v4
	v_max_f32_e32 v5, v5, v5
	v_max_f32_e32 v0, v0, v0
	v_max_f32_e32 v1, v1, v1
	s_mov_b64 s[26:27], 0x160000
	v_addc_co_u32_e32 v17, vcc, 0, v125, vcc
	v_max_f32_e32 v8, 0, v8
	v_max_f32_e32 v9, 0, v9
	v_max_f32_e32 v10, v10, v10
	v_max_f32_e32 v11, v11, v11
	v_max_f32_e32 v4, 0, v4
	v_max_f32_e32 v5, 0, v5
	v_max_f32_e32 v6, v6, v6
	v_max_f32_e32 v7, v7, v7
	v_max_f32_e32 v0, 0, v0
	v_max_f32_e32 v1, 0, v1
	v_max_f32_e32 v2, v2, v2
	v_max_f32_e32 v3, v3, v3
	v_lshl_add_u64 v[12:13], v[124:125], 0, s[26:27]
	v_mul_f32_e32 v8, v8, v8
	v_mul_f32_e32 v9, v9, v9
	v_max_f32_e32 v10, 0, v10
	v_max_f32_e32 v11, 0, v11
	v_mul_f32_e32 v4, v4, v4
	v_mul_f32_e32 v5, v5, v5
	v_max_f32_e32 v6, 0, v6
	v_max_f32_e32 v7, 0, v7
	v_mul_f32_e32 v0, v0, v0
	v_mul_f32_e32 v1, v1, v1
	v_max_f32_e32 v2, 0, v2
	v_max_f32_e32 v3, 0, v3
	s_and_b64 vcc, exec, s[8:9]
	s_mov_b32 s20, s10
	s_mov_b32 s22, s14
	s_mov_b64 s[28:29], s[18:19]
	s_mov_b64 s[26:27], s[16:17]
	v_mul_f32_e32 v10, v10, v10
	v_mul_f32_e32 v11, v11, v11
	v_cvt_pk_bf16_f32 v248, v8, v9
	v_cvt_pk_bf16_f32 v249, v10, v11
	s_nop 1
	v_permlane16_swap_b32_e32 v246, v248
	v_permlane16_swap_b32_e32 v247, v249
	global_store_dwordx4 v[12:13], v[246:249], off
	v_mul_f32_e32 v6, v6, v6
	v_mul_f32_e32 v7, v7, v7
	v_cvt_pk_bf16_f32 v238, v4, v5
	v_cvt_pk_bf16_f32 v239, v6, v7
	v_mul_f32_e32 v2, v2, v2
	v_mul_f32_e32 v3, v3, v3
	v_cvt_pk_bf16_f32 v240, v0, v1
	v_cvt_pk_bf16_f32 v241, v2, v3
	s_nop 1
	v_permlane16_swap_b32_e32 v238, v240
	v_permlane16_swap_b32_e32 v239, v241
	global_store_dwordx4 v[12:13], v[238:241], off offset:256
	s_cbranch_vccz .LBB0_2770
	s_waitcnt vmcnt(0)
	s_cmpk_gt_u32 s25, 0xff
	v_readlane_b32 s59, v255, 19
	s_cbranch_scc1 .LBB0_2777
	s_barrier

; #define PG8_STAGE(bufoff, gbase, voff) do { _Pragma("unroll") for (int _i = 0; _i < 2; ++_i) \
;     __builtin_amdgcn_global_load_lds((const unsigned*)((const char*)(gbase) + (voff)[_i]), (LAS unsigned*)(lds + (bufoff) + ldsw + _i * 8192), 16, 0, 0); } while (0)
; #define PG8_LDA(dst, b, h) do { _Pragma("unroll") for (int m = 0; m < 4; ++m) _Pragma("unroll") for (int k = 0; k < 2; ++k) dst[m][k] = *(const LAS bf16x8*)(lds + PG8_SA(b, h) + aoff + m * 2048 + k * 1024); } while (0)
; #define PG8_LDB(dst, b, h) do { _Pragma("unroll") for (int n = 0; n < 2; ++n) _Pragma("unroll") for (int k = 0; k < 2; ++k) dst[n][k] = *(const LAS bf16x8*)(lds + PG8_SB(b, h) + boff + n * 2048 + k * 1024); } while (0)
; #define PG8_BAR __builtin_amdgcn_s_barrier()
; template <class Epi, class Sched>
; __device__ __forceinline__ void gemm_phase(LAS unsigned char* lds, const Gemm g, const Sched& S, const Epi& E) {
;     ...
;     for (int t = 0; t < nt; t += 2) {
;       const bool last = (t == nt - 2);
;       const char* a1 = cA + (size_t)(t + 1) * kstep;
;       const char* a2 = last ? nA : cA + (size_t)(t + 2) * kstep; const char* b2 = last ? nB : cB + (size_t)(t + 2) * kstep;
;       const char* a3 = a2 + kstep; const char* b3 = b2 + kstep;
;       PG8_LDB(B0, 0, 0); PG8_SCHED; PG8_LDA(At, 0, 0); PG8_STAGE(PG8_SA(1, 1), a1 + hstepA, voffA);
;       PG8_WAIT_L(8); PG8_BAR; PG8_WAIT_L(0); PG8_MMA(0, 0, At, B0); PG8_BAR; PG8_SCHED;
;       PG8_LDB(B1, 0, 1); PG8_STAGE(PG8_SB(0, 0), b2, voffB);
;       PG8_BAR; PG8_WAIT_L(0); PG8_MMA(0, 1, At, B1); PG8_BAR;
;       PG8_LDA(At, 0, 1); PG8_STAGE(PG8_SA(0, 0), a2, voffA);
;       PG8_BAR; PG8_WAIT_L(0); PG8_MMA(1, 0, At, B0); PG8_BAR; PG8_SCHED;
;       PG8_STAGE(PG8_SB(0, 1), b2 + hstepB, voffB);
;       PG8_WAIT_V(6); PG8_BAR; PG8_MMA(1, 1, At, B1); PG8_BAR;
;       PG8_LDB(B0, 1, 0); PG8_SCHED; PG8_LDA(At, 1, 0); PG8_STAGE(PG8_SA(0, 1), a2 + hstepA, voffA);
;       PG8_WAIT_L(8); PG8_BAR; PG8_WAIT_L(0); PG8_MMA(0, 0, At, B0); PG8_BAR; PG8_SCHED;
;       PG8_LDB(B1, 1, 1); PG8_STAGE(PG8_SB(1, 0), b3, voffB);
;       PG8_BAR; PG8_WAIT_L(0); PG8_MMA(0, 1, At, B1); PG8_BAR;
;       PG8_LDA(At, 1, 1); PG8_STAGE(PG8_SA(1, 0), a3, voffA);
;       PG8_BAR; PG8_WAIT_L(0); PG8_MMA(1, 0, At, B0); PG8_BAR; PG8_SCHED;
;       PG8_STAGE(PG8_SB(1, 1), b3 + hstepB, voffB);
;       PG8_WAIT_V(6); PG8_BAR; PG8_MMA(1, 1, At, B1); PG8_BAR;
;     }
.LBB0_2839:
	s_add_u32 s26, s22, 0xfff00080
	s_addc_u32 s27, s23, -1
	s_add_i32 s74, 16, 0x10000
	v_add_u32_e32 v158, s74, v145
	ds_read_b128 v[154:157], v158
	ds_read_b128 v[162:165], v158 offset:1024
	ds_read_b128 v[166:169], v158 offset:2048
	ds_read_b128 v[170:173], v158 offset:3072
	s_cmp_eq_u32 s69, 4
	s_cselect_b32 s29, s15, s27
	s_cselect_b32 s28, s59, s26
	s_cselect_b32 s27, s11, s68
	s_cselect_b32 s26, s66, s67
	v_lshl_add_u64 v[158:159], s[22:23], 0, v[150:151]
	s_add_i32 m0, s37, 0xc000
	ds_read_b128 v[174:177], v161
	ds_read_b128 v[178:181], v161 offset:1024
	ds_read_b128 v[182:185], v161 offset:2048
	ds_read_b128 v[198:201], v161 offset:3072
	ds_read_b128 v[214:217], v161 offset:4096
	ds_read_b128 v[218:221], v161 offset:5120
	ds_read_b128 v[222:225], v161 offset:6144
	ds_read_b128 v[226:229], v161 offset:7168
	global_load_lds_dwordx4 v[158:159], off
	v_lshl_add_u64 v[158:159], s[22:23], 0, v[152:153]
	s_add_i32 m0, s37, 0xe000
	s_nop 0
	global_load_lds_dwordx4 v[158:159], off
	s_waitcnt lgkmcnt(8)
	s_barrier
	s_waitcnt lgkmcnt(0)
	s_waitcnt lgkmcnt(0)
	v_mfma_f32_16x16x32_bf16 v[124:127], v[154:157], v[174:177], v[124:127]
	v_mfma_f32_16x16x32_bf16 v[120:123], v[166:169], v[174:177], v[120:123]
	v_mfma_f32_16x16x32_bf16 v[112:115], v[154:157], v[182:185], v[112:115]
	v_mfma_f32_16x16x32_bf16 v[104:107], v[166:169], v[182:185], v[104:107]
	v_mfma_f32_16x16x32_bf16 v[96:99], v[154:157], v[214:217], v[96:99]
	v_mfma_f32_16x16x32_bf16 v[88:91], v[166:169], v[214:217], v[88:91]
	v_mfma_f32_16x16x32_bf16 v[80:83], v[154:157], v[222:225], v[80:83]
	v_mfma_f32_16x16x32_bf16 v[72:75], v[166:169], v[222:225], v[72:75]
	v_mfma_f32_16x16x32_bf16 v[124:127], v[162:165], v[178:181], v[124:127]
	v_mfma_f32_16x16x32_bf16 v[120:123], v[170:173], v[178:181], v[120:123]
	v_mfma_f32_16x16x32_bf16 v[112:115], v[162:165], v[198:201], v[112:115]
	v_mfma_f32_16x16x32_bf16 v[104:107], v[170:173], v[198:201], v[104:107]
	v_mfma_f32_16x16x32_bf16 v[96:99], v[162:165], v[218:221], v[96:99]
	v_mfma_f32_16x16x32_bf16 v[88:91], v[170:173], v[218:221], v[88:91]
	v_mfma_f32_16x16x32_bf16 v[80:83], v[162:165], v[226:229], v[80:83]
	v_mfma_f32_16x16x32_bf16 v[72:75], v[170:173], v[226:229], v[72:75]
	s_barrier
	s_add_i32 s76, 16, 0x14000
	v_add_u32_e32 v158, s76, v145
	s_add_i32 s74, s74, s36
	ds_read_b128 v[230:233], v158
	ds_read_b128 v[234:237], v158 offset:1024
	ds_read_b128 v[238:241], v158 offset:2048
	ds_read_b128 v[242:245], v158 offset:3072
	v_lshl_add_u64 v[158:159], s[26:27], 0, v[130:131]
	s_mov_b32 m0, s74
	v_lshl_add_u64 v[246:247], s[26:27], 0, v[128:129]
	global_load_lds_dwordx4 v[158:159], off
	s_add_i32 m0, s74, 0x2000
	s_nop 0
	global_load_lds_dwordx4 v[246:247], off
	s_barrier
	s_waitcnt lgkmcnt(0)
	s_waitcnt lgkmcnt(0)
	v_mfma_f32_16x16x32_bf16 v[116:119], v[230:233], v[174:177], v[116:119]
	v_mfma_f32_16x16x32_bf16 v[108:111], v[238:241], v[174:177], v[108:111]
	v_mfma_f32_16x16x32_bf16 v[100:103], v[230:233], v[182:185], v[100:103]
	v_mfma_f32_16x16x32_bf16 v[92:95], v[238:241], v[182:185], v[92:95]
	v_mfma_f32_16x16x32_bf16 v[84:87], v[230:233], v[214:217], v[84:87]
	v_mfma_f32_16x16x32_bf16 v[76:79], v[238:241], v[214:217], v[76:79]
	v_mfma_f32_16x16x32_bf16 v[68:71], v[230:233], v[222:225], v[68:71]
	v_mfma_f32_16x16x32_bf16 v[64:67], v[238:241], v[222:225], v[64:67]
	v_mfma_f32_16x16x32_bf16 v[116:119], v[234:237], v[178:181], v[116:119]
	v_mfma_f32_16x16x32_bf16 v[108:111], v[242:245], v[178:181], v[108:111]
	v_mfma_f32_16x16x32_bf16 v[100:103], v[234:237], v[198:201], v[100:103]
	v_mfma_f32_16x16x32_bf16 v[92:95], v[242:245], v[198:201], v[92:95]
	v_mfma_f32_16x16x32_bf16 v[84:87], v[234:237], v[218:221], v[84:87]
	v_mfma_f32_16x16x32_bf16 v[76:79], v[242:245], v[218:221], v[76:79]
	v_mfma_f32_16x16x32_bf16 v[68:71], v[234:237], v[226:229], v[68:71]
	v_mfma_f32_16x16x32_bf16 v[64:67], v[242:245], v[226:229], v[64:67]
	s_mov_b32 m0, s37
	v_lshl_add_u64 v[248:249], s[28:29], 0, v[130:131]
	s_barrier
	ds_read_b128 v[174:177], v161 offset:16384
	ds_read_b128 v[178:181], v161 offset:17408
	ds_read_b128 v[182:185], v161 offset:18432
	ds_read_b128 v[198:201], v161 offset:19456
	ds_read_b128 v[214:217], v161 offset:20480
	ds_read_b128 v[218:221], v161 offset:21504
	ds_read_b128 v[222:225], v161 offset:22528
	ds_read_b128 v[226:229], v161 offset:23552
	global_load_lds_dwordx4 v[248:249], off
	v_lshl_add_u64 v[250:251], s[28:29], 0, v[128:129]
	s_mov_b32 m0, s38
	s_nop 0
	global_load_lds_dwordx4 v[250:251], off
	s_barrier
	s_waitcnt lgkmcnt(0)
	s_waitcnt lgkmcnt(0)
	v_mfma_f32_16x16x32_bf16 v[60:63], v[154:157], v[174:177], v[60:63]
	v_mfma_f32_16x16x32_bf16 v[56:59], v[166:169], v[174:177], v[56:59]
	v_mfma_f32_16x16x32_bf16 v[48:51], v[154:157], v[182:185], v[48:51]
	v_mfma_f32_16x16x32_bf16 v[40:43], v[166:169], v[182:185], v[40:43]
	v_mfma_f32_16x16x32_bf16 v[32:35], v[154:157], v[214:217], v[32:35]
	v_mfma_f32_16x16x32_bf16 v[24:27], v[166:169], v[214:217], v[24:27]
	v_mfma_f32_16x16x32_bf16 v[16:19], v[154:157], v[222:225], v[16:19]
	v_mfma_f32_16x16x32_bf16 v[8:11], v[166:169], v[222:225], v[8:11]
	v_mfma_f32_16x16x32_bf16 v[60:63], v[162:165], v[178:181], v[60:63]
	v_mfma_f32_16x16x32_bf16 v[56:59], v[170:173], v[178:181], v[56:59]
	v_mfma_f32_16x16x32_bf16 v[48:51], v[162:165], v[198:201], v[48:51]
	v_mfma_f32_16x16x32_bf16 v[40:43], v[170:173], v[198:201], v[40:43]
	v_mfma_f32_16x16x32_bf16 v[32:35], v[162:165], v[218:221], v[32:35]
	v_mfma_f32_16x16x32_bf16 v[24:27], v[170:173], v[218:221], v[24:27]
	v_mfma_f32_16x16x32_bf16 v[16:19], v[162:165], v[226:229], v[16:19]
	v_mfma_f32_16x16x32_bf16 v[8:11], v[170:173], v[226:229], v[8:11]
	s_barrier
; #define PG8_STAGE(bufoff, gbase, voff) do { _Pragma("unroll") for (int _i = 0; _i < 2; ++_i) \
;     __builtin_amdgcn_global_load_lds((const unsigned*)((const char*)(gbase) + (voff)[_i]), (LAS unsigned*)(lds + (bufoff) + ldsw + _i * 8192), 16, 0, 0); } while (0)
; #define PG8_LDA(dst, b, h) do { _Pragma("unroll") for (int m = 0; m < 4; ++m) _Pragma("unroll") for (int k = 0; k < 2; ++k) dst[m][k] = *(const LAS bf16x8*)(lds + PG8_SA(b, h) + aoff + m * 2048 + k * 1024); } while (0)
; #define PG8_LDB(dst, b, h) do { _Pragma("unroll") for (int n = 0; n < 2; ++n) _Pragma("unroll") for (int k = 0; k < 2; ++k) dst[n][k] = *(const LAS bf16x8*)(lds + PG8_SB(b, h) + boff + n * 2048 + k * 1024); } while (0)
; #define PG8_BAR __builtin_amdgcn_s_barrier()
; template <class Epi, class Sched>
; __device__ __forceinline__ void gemm_phase(LAS unsigned char* lds, const Gemm g, const Sched& S, const Epi& E) {
;     ...
;     for (int t = 0; t < nt; t += 2) {
;       const bool last = (t == nt - 2);
;       const char* a1 = cA + (size_t)(t + 1) * kstep;
;       const char* a2 = last ? nA : cA + (size_t)(t + 2) * kstep; const char* b2 = last ? nB : cB + (size_t)(t + 2) * kstep;
;       const char* a3 = a2 + kstep; const char* b3 = b2 + kstep;
;       PG8_LDB(B0, 0, 0); PG8_SCHED; PG8_LDA(At, 0, 0); PG8_STAGE(PG8_SA(1, 1), a1 + hstepA, voffA);
;       PG8_WAIT_L(8); PG8_BAR; PG8_WAIT_L(0); PG8_MMA(0, 0, At, B0); PG8_BAR; PG8_SCHED;
;       PG8_LDB(B1, 0, 1); PG8_STAGE(PG8_SB(0, 0), b2, voffB);
;       PG8_BAR; PG8_WAIT_L(0); PG8_MMA(0, 1, At, B1); PG8_BAR;
;       PG8_LDA(At, 0, 1); PG8_STAGE(PG8_SA(0, 0), a2, voffA);
;       PG8_BAR; PG8_WAIT_L(0); PG8_MMA(1, 0, At, B0); PG8_BAR; PG8_SCHED;
;       PG8_STAGE(PG8_SB(0, 1), b2 + hstepB, voffB);
;       PG8_WAIT_V(6); PG8_BAR; PG8_MMA(1, 1, At, B1); PG8_BAR;
;       PG8_LDB(B0, 1, 0); PG8_SCHED; PG8_LDA(At, 1, 0); PG8_STAGE(PG8_SA(0, 1), a2 + hstepA, voffA);
;       PG8_WAIT_L(8); PG8_BAR; PG8_WAIT_L(0); PG8_MMA(0, 0, At, B0); PG8_BAR; PG8_SCHED;
;       PG8_LDB(B1, 1, 1); PG8_STAGE(PG8_SB(1, 0), b3, voffB);
;       PG8_BAR; PG8_WAIT_L(0); PG8_MMA(0, 1, At, B1); PG8_BAR;
;       PG8_LDA(At, 1, 1); PG8_STAGE(PG8_SA(1, 0), a3, voffA);
;       PG8_BAR; PG8_WAIT_L(0); PG8_MMA(1, 0, At, B0); PG8_BAR; PG8_SCHED;
;       PG8_STAGE(PG8_SB(1, 1), b3 + hstepB, voffB);
;       PG8_WAIT_V(6); PG8_BAR; PG8_MMA(1, 1, At, B1); PG8_BAR;
;     }
	s_add_u32 s74, s26, 0x100000
	s_addc_u32 s75, s27, 0
	s_add_i32 s76, s76, s36
	v_lshl_add_u64 v[154:155], s[74:75], 0, v[130:131]
	s_mov_b32 m0, s76
	s_nop 0
	global_load_lds_dwordx4 v[154:155], off
	v_lshl_add_u64 v[154:155], s[74:75], 0, v[128:129]
	s_add_i32 m0, s76, 0x2000
	s_nop 0
	global_load_lds_dwordx4 v[154:155], off
	s_waitcnt vmcnt(6)
	s_barrier
	v_mfma_f32_16x16x32_bf16 v[52:55], v[230:233], v[174:177], v[52:55]
	v_mfma_f32_16x16x32_bf16 v[44:47], v[238:241], v[174:177], v[44:47]
	v_mfma_f32_16x16x32_bf16 v[36:39], v[230:233], v[182:185], v[36:39]
	v_mfma_f32_16x16x32_bf16 v[28:31], v[238:241], v[182:185], v[28:31]
	v_mfma_f32_16x16x32_bf16 v[20:23], v[230:233], v[214:217], v[20:23]
	v_mfma_f32_16x16x32_bf16 v[12:15], v[238:241], v[214:217], v[12:15]
	v_mfma_f32_16x16x32_bf16 v[4:7], v[230:233], v[222:225], v[4:7]
	v_mfma_f32_16x16x32_bf16 v[0:3], v[238:241], v[222:225], v[0:3]
	v_mfma_f32_16x16x32_bf16 v[52:55], v[234:237], v[178:181], v[52:55]
	v_mfma_f32_16x16x32_bf16 v[44:47], v[242:245], v[178:181], v[44:47]
	v_mfma_f32_16x16x32_bf16 v[36:39], v[234:237], v[198:201], v[36:39]
	v_mfma_f32_16x16x32_bf16 v[28:31], v[242:245], v[198:201], v[28:31]
	v_mfma_f32_16x16x32_bf16 v[20:23], v[234:237], v[218:221], v[20:23]
	v_mfma_f32_16x16x32_bf16 v[12:15], v[242:245], v[218:221], v[12:15]
	v_mfma_f32_16x16x32_bf16 v[4:7], v[234:237], v[226:229], v[4:7]
	v_mfma_f32_16x16x32_bf16 v[0:3], v[242:245], v[226:229], v[0:3]
	s_add_i32 s74, 16, 0x18000
	v_add_u32_e32 v170, s74, v145
	s_barrier
	ds_read_b128 v[154:157], v170
	ds_read_b128 v[162:165], v170 offset:1024
	ds_read_b128 v[166:169], v170 offset:2048
	ds_read_b128 v[170:173], v170 offset:3072
	s_add_u32 s28, s28, 0x100000
	s_addc_u32 s29, s29, 0
	s_mov_b32 m0, s39
	v_lshl_add_u64 v[230:231], s[28:29], 0, v[130:131]
	ds_read_b128 v[174:177], v161 offset:32768
	ds_read_b128 v[178:181], v161 offset:33792
	ds_read_b128 v[182:185], v161 offset:34816
	ds_read_b128 v[198:201], v161 offset:35840
	ds_read_b128 v[214:217], v161 offset:36864
	ds_read_b128 v[218:221], v161 offset:37888
	ds_read_b128 v[222:225], v161 offset:38912
	ds_read_b128 v[226:229], v161 offset:39936
	global_load_lds_dwordx4 v[230:231], off
	v_lshl_add_u64 v[230:231], s[28:29], 0, v[128:129]
	s_mov_b32 m0, s44
	s_nop 0
	global_load_lds_dwordx4 v[230:231], off
	s_waitcnt lgkmcnt(8)
	s_barrier
	s_waitcnt lgkmcnt(0)
	s_waitcnt lgkmcnt(0)
	v_mfma_f32_16x16x32_bf16 v[124:127], v[154:157], v[174:177], v[124:127]
	v_mfma_f32_16x16x32_bf16 v[120:123], v[166:169], v[174:177], v[120:123]
	v_mfma_f32_16x16x32_bf16 v[112:115], v[154:157], v[182:185], v[112:115]
	v_mfma_f32_16x16x32_bf16 v[104:107], v[166:169], v[182:185], v[104:107]
	v_mfma_f32_16x16x32_bf16 v[96:99], v[154:157], v[214:217], v[96:99]
	v_mfma_f32_16x16x32_bf16 v[88:91], v[166:169], v[214:217], v[88:91]
	v_mfma_f32_16x16x32_bf16 v[80:83], v[154:157], v[222:225], v[80:83]
	v_mfma_f32_16x16x32_bf16 v[72:75], v[166:169], v[222:225], v[72:75]
	v_mfma_f32_16x16x32_bf16 v[124:127], v[162:165], v[178:181], v[124:127]
	v_mfma_f32_16x16x32_bf16 v[120:123], v[170:173], v[178:181], v[120:123]
	v_mfma_f32_16x16x32_bf16 v[112:115], v[162:165], v[198:201], v[112:115]
	v_mfma_f32_16x16x32_bf16 v[104:107], v[170:173], v[198:201], v[104:107]
	v_mfma_f32_16x16x32_bf16 v[96:99], v[162:165], v[218:221], v[96:99]
	v_mfma_f32_16x16x32_bf16 v[88:91], v[170:173], v[218:221], v[88:91]
	v_mfma_f32_16x16x32_bf16 v[80:83], v[162:165], v[226:229], v[80:83]
	v_mfma_f32_16x16x32_bf16 v[72:75], v[170:173], v[226:229], v[72:75]
	s_barrier
	s_add_i32 s28, 16, 0x1c000
	s_add_i32 s29, s74, s36
	v_add_u32_e32 v189, s28, v145
	v_lshl_add_u64 v[158:159], v[158:159], 0, s[62:63]
	s_mov_b32 m0, s29
	ds_read_b128 v[230:233], v189
	ds_read_b128 v[234:237], v189 offset:1024
	ds_read_b128 v[238:241], v189 offset:2048
	ds_read_b128 v[242:245], v189 offset:3072
	global_load_lds_dwordx4 v[158:159], off
	v_lshl_add_u64 v[158:159], v[246:247], 0, s[62:63]
	s_add_i32 m0, s29, 0x2000
	s_nop 0
	global_load_lds_dwordx4 v[158:159], off
	s_barrier
	s_waitcnt lgkmcnt(0)
	s_waitcnt lgkmcnt(0)
	v_mfma_f32_16x16x32_bf16 v[116:119], v[230:233], v[174:177], v[116:119]
	v_mfma_f32_16x16x32_bf16 v[108:111], v[238:241], v[174:177], v[108:111]
	v_mfma_f32_16x16x32_bf16 v[100:103], v[230:233], v[182:185], v[100:103]
	v_mfma_f32_16x16x32_bf16 v[92:95], v[238:241], v[182:185], v[92:95]
	v_mfma_f32_16x16x32_bf16 v[84:87], v[230:233], v[214:217], v[84:87]
	v_mfma_f32_16x16x32_bf16 v[76:79], v[238:241], v[214:217], v[76:79]
	v_mfma_f32_16x16x32_bf16 v[68:71], v[230:233], v[222:225], v[68:71]
	v_mfma_f32_16x16x32_bf16 v[64:67], v[238:241], v[222:225], v[64:67]
	v_mfma_f32_16x16x32_bf16 v[116:119], v[234:237], v[178:181], v[116:119]
	v_mfma_f32_16x16x32_bf16 v[108:111], v[242:245], v[178:181], v[108:111]
	v_mfma_f32_16x16x32_bf16 v[100:103], v[234:237], v[198:201], v[100:103]
	v_mfma_f32_16x16x32_bf16 v[92:95], v[242:245], v[198:201], v[92:95]
	v_mfma_f32_16x16x32_bf16 v[84:87], v[234:237], v[218:221], v[84:87]
	v_mfma_f32_16x16x32_bf16 v[76:79], v[242:245], v[218:221], v[76:79]
	v_mfma_f32_16x16x32_bf16 v[68:71], v[234:237], v[226:229], v[68:71]
	v_mfma_f32_16x16x32_bf16 v[64:67], v[242:245], v[226:229], v[64:67]
	s_mov_b32 m0, s47
	v_lshl_add_u64 v[158:159], v[248:249], 0, s[62:63]
	s_barrier
	ds_read_b128 v[174:177], v161 offset:49152
	ds_read_b128 v[178:181], v161 offset:50176
	ds_read_b128 v[182:185], v161 offset:51200
	ds_read_b128 v[198:201], v161 offset:52224
	ds_read_b128 v[214:217], v161 offset:53248
	ds_read_b128 v[218:221], v161 offset:54272
	ds_read_b128 v[222:225], v161 offset:55296
	ds_read_b128 v[226:229], v161 offset:56320
	global_load_lds_dwordx4 v[158:159], off
	v_lshl_add_u64 v[158:159], v[250:251], 0, s[62:63]
	s_mov_b32 m0, s48
	s_nop 0
	global_load_lds_dwordx4 v[158:159], off
	s_barrier
; #define PG8_STAGE(bufoff, gbase, voff) do { _Pragma("unroll") for (int _i = 0; _i < 2; ++_i) \
;     __builtin_amdgcn_global_load_lds((const unsigned*)((const char*)(gbase) + (voff)[_i]), (LAS unsigned*)(lds + (bufoff) + ldsw + _i * 8192), 16, 0, 0); } while (0)
; #define PG8_LDA(dst, b, h) do { _Pragma("unroll") for (int m = 0; m < 4; ++m) _Pragma("unroll") for (int k = 0; k < 2; ++k) dst[m][k] = *(const LAS bf16x8*)(lds + PG8_SA(b, h) + aoff + m * 2048 + k * 1024); } while (0)
; #define PG8_LDB(dst, b, h) do { _Pragma("unroll") for (int n = 0; n < 2; ++n) _Pragma("unroll") for (int k = 0; k < 2; ++k) dst[n][k] = *(const LAS bf16x8*)(lds + PG8_SB(b, h) + boff + n * 2048 + k * 1024); } while (0)
; #define PG8_BAR __builtin_amdgcn_s_barrier()
; template <class Epi, class Sched>
; __device__ __forceinline__ void gemm_phase(LAS unsigned char* lds, const Gemm g, const Sched& S, const Epi& E) {
;     ...
;     for (int t = 0; t < nt; t += 2) {
;       const bool last = (t == nt - 2);
;       const char* a1 = cA + (size_t)(t + 1) * kstep;
;       const char* a2 = last ? nA : cA + (size_t)(t + 2) * kstep; const char* b2 = last ? nB : cB + (size_t)(t + 2) * kstep;
;       const char* a3 = a2 + kstep; const char* b3 = b2 + kstep;
;       PG8_LDB(B0, 0, 0); PG8_SCHED; PG8_LDA(At, 0, 0); PG8_STAGE(PG8_SA(1, 1), a1 + hstepA, voffA);
;       PG8_WAIT_L(8); PG8_BAR; PG8_WAIT_L(0); PG8_MMA(0, 0, At, B0); PG8_BAR; PG8_SCHED;
;       PG8_LDB(B1, 0, 1); PG8_STAGE(PG8_SB(0, 0), b2, voffB);
;       PG8_BAR; PG8_WAIT_L(0); PG8_MMA(0, 1, At, B1); PG8_BAR;
;       PG8_LDA(At, 0, 1); PG8_STAGE(PG8_SA(0, 0), a2, voffA);
;       PG8_BAR; PG8_WAIT_L(0); PG8_MMA(1, 0, At, B0); PG8_BAR; PG8_SCHED;
;       PG8_STAGE(PG8_SB(0, 1), b2 + hstepB, voffB);
;       PG8_WAIT_V(6); PG8_BAR; PG8_MMA(1, 1, At, B1); PG8_BAR;
;       PG8_LDB(B0, 1, 0); PG8_SCHED; PG8_LDA(At, 1, 0); PG8_STAGE(PG8_SA(0, 1), a2 + hstepA, voffA);
;       PG8_WAIT_L(8); PG8_BAR; PG8_WAIT_L(0); PG8_MMA(0, 0, At, B0); PG8_BAR; PG8_SCHED;
;       PG8_LDB(B1, 1, 1); PG8_STAGE(PG8_SB(1, 0), b3, voffB);
;       PG8_BAR; PG8_WAIT_L(0); PG8_MMA(0, 1, At, B1); PG8_BAR;
;       PG8_LDA(At, 1, 1); PG8_STAGE(PG8_SA(1, 0), a3, voffA);
;       PG8_BAR; PG8_WAIT_L(0); PG8_MMA(1, 0, At, B0); PG8_BAR; PG8_SCHED;
;       PG8_STAGE(PG8_SB(1, 1), b3 + hstepB, voffB);
;       PG8_WAIT_V(6); PG8_BAR; PG8_MMA(1, 1, At, B1); PG8_BAR;
;     }
	s_waitcnt lgkmcnt(0)
	s_waitcnt lgkmcnt(0)
	v_mfma_f32_16x16x32_bf16 v[60:63], v[154:157], v[174:177], v[60:63]
	v_mfma_f32_16x16x32_bf16 v[56:59], v[166:169], v[174:177], v[56:59]
	v_mfma_f32_16x16x32_bf16 v[48:51], v[154:157], v[182:185], v[48:51]
	v_mfma_f32_16x16x32_bf16 v[40:43], v[166:169], v[182:185], v[40:43]
	v_mfma_f32_16x16x32_bf16 v[32:35], v[154:157], v[214:217], v[32:35]
	v_mfma_f32_16x16x32_bf16 v[24:27], v[166:169], v[214:217], v[24:27]
	v_mfma_f32_16x16x32_bf16 v[16:19], v[154:157], v[222:225], v[16:19]
	v_mfma_f32_16x16x32_bf16 v[8:11], v[166:169], v[222:225], v[8:11]
	v_mfma_f32_16x16x32_bf16 v[60:63], v[162:165], v[178:181], v[60:63]
	v_mfma_f32_16x16x32_bf16 v[56:59], v[170:173], v[178:181], v[56:59]
	v_mfma_f32_16x16x32_bf16 v[48:51], v[162:165], v[198:201], v[48:51]
	v_mfma_f32_16x16x32_bf16 v[40:43], v[170:173], v[198:201], v[40:43]
	v_mfma_f32_16x16x32_bf16 v[32:35], v[162:165], v[218:221], v[32:35]
	v_mfma_f32_16x16x32_bf16 v[24:27], v[170:173], v[218:221], v[24:27]
	v_mfma_f32_16x16x32_bf16 v[16:19], v[162:165], v[226:229], v[16:19]
	v_mfma_f32_16x16x32_bf16 v[8:11], v[170:173], v[226:229], v[8:11]
	s_barrier
	s_add_u32 s26, s26, 0x100080
	s_addc_u32 s27, s27, 0
	s_add_i32 s28, s28, s36
	v_lshl_add_u64 v[154:155], s[26:27], 0, v[130:131]
	s_mov_b32 m0, s28
	s_nop 0
	global_load_lds_dwordx4 v[154:155], off
	v_lshl_add_u64 v[154:155], s[26:27], 0, v[128:129]
	s_add_i32 m0, s28, 0x2000
	s_nop 0
	global_load_lds_dwordx4 v[154:155], off
	s_waitcnt vmcnt(6)
	s_barrier
	v_mfma_f32_16x16x32_bf16 v[52:55], v[230:233], v[174:177], v[52:55]
	v_mfma_f32_16x16x32_bf16 v[44:47], v[238:241], v[174:177], v[44:47]
	v_mfma_f32_16x16x32_bf16 v[36:39], v[230:233], v[182:185], v[36:39]
	v_mfma_f32_16x16x32_bf16 v[28:31], v[238:241], v[182:185], v[28:31]
	v_mfma_f32_16x16x32_bf16 v[20:23], v[230:233], v[214:217], v[20:23]
	v_mfma_f32_16x16x32_bf16 v[12:15], v[238:241], v[214:217], v[12:15]
	v_mfma_f32_16x16x32_bf16 v[4:7], v[230:233], v[222:225], v[4:7]
	v_mfma_f32_16x16x32_bf16 v[0:3], v[238:241], v[222:225], v[0:3]
	v_mfma_f32_16x16x32_bf16 v[52:55], v[234:237], v[178:181], v[52:55]
	v_mfma_f32_16x16x32_bf16 v[44:47], v[242:245], v[178:181], v[44:47]
	v_mfma_f32_16x16x32_bf16 v[36:39], v[234:237], v[198:201], v[36:39]
	v_mfma_f32_16x16x32_bf16 v[28:31], v[242:245], v[198:201], v[28:31]
	v_mfma_f32_16x16x32_bf16 v[20:23], v[234:237], v[218:221], v[20:23]
	v_mfma_f32_16x16x32_bf16 v[12:15], v[242:245], v[218:221], v[12:15]
	v_mfma_f32_16x16x32_bf16 v[4:7], v[234:237], v[226:229], v[4:7]
	v_mfma_f32_16x16x32_bf16 v[0:3], v[242:245], v[226:229], v[0:3]
	s_add_i32 s69, s69, 2
	s_add_u32 s22, s22, 0x100
	s_addc_u32 s23, s23, 0
	s_add_u32 s67, s67, 0x100
	s_addc_u32 s68, s68, 0
	s_cmp_gt_u32 s69, 5
	s_barrier
	s_cbranch_scc0 .LBB0_2839
	v_lshl_or_b32 v166, s58, 8, v160
	v_ashrrev_i32_e32 v167, 31, v166
	v_lshlrev_b64 v[154:155], 2, v[166:167]
	v_lshl_add_u64 v[156:157], s[8:9], 0, v[154:155]
	global_load_dwordx4 v[214:217], v[156:157], off
	global_load_dwordx4 v[218:221], v[156:157], off offset:64
	global_load_dwordx4 v[222:225], v[156:157], off offset:512
	global_load_dwordx4 v[226:229], v[156:157], off offset:576
	s_ashr_i32 s11, s51, 31
	s_lshr_b32 s11, s11, 23
	s_add_i32 s11, s51, s11
	s_ashr_i32 s22, s11, 9
	s_ashr_i32 s23, s22, 31
	s_lshl_b64 s[22:23], s[22:23], 20
	s_add_u32 s22, s45, s22
	s_addc_u32 s23, s46, s23
	v_or_b32_e32 v158, 16, v166
	v_lshl_add_u64 v[168:169], s[22:23], 0, v[132:133]
	v_ashrrev_i32_e32 v159, 31, v158
	v_lshl_add_u64 v[168:169], v[168:169], 0, v[154:155]
	v_lshl_add_u64 v[158:159], v[158:159], 2, s[8:9]
	s_mov_b32 s58, s10
	s_mov_b64 s[26:27], s[20:21]
	s_mov_b32 s51, s14
	s_and_b64 vcc, exec, s[16:17]
	s_waitcnt vmcnt(0)
; #define PG8_WAIT_V(n) asm volatile("s_waitcnt vmcnt(" #n ")" ::: "memory")
; #define PG8_BAR __builtin_amdgcn_s_barrier()
; template <class Epi, class Sched>
; __device__ __forceinline__ void gemm_phase(LAS unsigned char* lds, const Gemm g, const Sched& S, const Epi& E) {
;     ...
;     E(acc, cur, wr, wc, fr, fq);
;     if (!has_next) break;
; #pragma unroll
;     for (int a = 0; a < 2; ++a)
; #pragma unroll
;       for (int b = 0; b < 2; ++b)
; #pragma unroll
;         for (int m = 0; m < 4; ++m)
; #pragma unroll
;           for (int n = 0; n < 2; ++n) acc[a][b][m][n] = (f32x4){0.f, 0.f, 0.f, 0.f};
;     cur = nxt; cA = nA; cB = nB; ++ui;
;   }
;   PG8_WAIT_V(0);
;   if (wr == 0) PG8_BAR;
;   PG8_BAR;
	v_pk_mul_f32 v[126:127], v[126:127], v[216:217]
	v_pk_mul_f32 v[124:125], v[124:125], v[214:215]
	global_store_dwordx4 v[168:169], v[124:127], off
	s_nop 1
	v_pk_mul_f32 v[122:123], v[122:123], v[220:221]
	v_or_b32_e32 v124, 0x80, v166
	v_ashrrev_i32_e32 v125, 31, v124
	v_pk_mul_f32 v[120:121], v[120:121], v[218:219]
	v_lshl_add_u64 v[124:125], v[124:125], 2, s[8:9]
	global_store_dwordx4 v[168:169], v[120:123], off offset:64
	s_nop 1
	v_pk_mul_f32 v[118:119], v[118:119], v[224:225]
	v_or_b32_e32 v120, 0x90, v166
	v_ashrrev_i32_e32 v121, 31, v120
	v_pk_mul_f32 v[116:117], v[116:117], v[222:223]
	v_lshl_add_u64 v[120:121], v[120:121], 2, s[8:9]
	global_store_dwordx4 v[168:169], v[116:119], off offset:512
	s_nop 1
	v_pk_mul_f32 v[110:111], v[110:111], v[228:229]
	v_pk_mul_f32 v[108:109], v[108:109], v[226:227]
	global_store_dwordx4 v[168:169], v[108:111], off offset:576
	s_nop 1
	v_lshl_add_u64 v[116:117], s[22:23], 0, v[134:135]
	v_lshl_add_u64 v[116:117], v[116:117], 0, v[154:155]
	v_pk_mul_f32 v[110:111], v[114:115], v[216:217]
	v_pk_mul_f32 v[108:109], v[112:113], v[214:215]
	global_store_dwordx4 v[116:117], v[108:111], off
	s_nop 1
	v_pk_mul_f32 v[106:107], v[106:107], v[220:221]
	v_pk_mul_f32 v[104:105], v[104:105], v[218:219]
	global_store_dwordx4 v[116:117], v[104:107], off offset:64
	s_nop 1
	v_pk_mul_f32 v[102:103], v[102:103], v[224:225]
	v_pk_mul_f32 v[100:101], v[100:101], v[222:223]
	global_store_dwordx4 v[116:117], v[100:103], off offset:512
	s_nop 1
	v_pk_mul_f32 v[94:95], v[94:95], v[228:229]
	v_pk_mul_f32 v[92:93], v[92:93], v[226:227]
	global_store_dwordx4 v[116:117], v[92:95], off offset:576
	s_nop 1
	v_lshl_add_u64 v[100:101], s[22:23], 0, v[136:137]
	v_lshl_add_u64 v[100:101], v[100:101], 0, v[154:155]
	v_pk_mul_f32 v[94:95], v[98:99], v[216:217]
	v_pk_mul_f32 v[92:93], v[96:97], v[214:215]
	global_store_dwordx4 v[100:101], v[92:95], off
	s_nop 1
	v_pk_mul_f32 v[90:91], v[90:91], v[220:221]
	v_pk_mul_f32 v[88:89], v[88:89], v[218:219]
	global_store_dwordx4 v[100:101], v[88:91], off offset:64
	s_nop 1
	v_pk_mul_f32 v[86:87], v[86:87], v[224:225]
	v_pk_mul_f32 v[84:85], v[84:85], v[222:223]
	global_store_dwordx4 v[100:101], v[84:87], off offset:512
	s_nop 1
	v_pk_mul_f32 v[78:79], v[78:79], v[228:229]
	v_pk_mul_f32 v[76:77], v[76:77], v[226:227]
	global_store_dwordx4 v[100:101], v[76:79], off offset:576
	s_nop 1
	v_lshl_add_u64 v[84:85], s[22:23], 0, v[138:139]
	v_lshl_add_u64 v[84:85], v[84:85], 0, v[154:155]
	v_pk_mul_f32 v[78:79], v[82:83], v[216:217]
	v_pk_mul_f32 v[76:77], v[80:81], v[214:215]
	global_store_dwordx4 v[84:85], v[76:79], off
	s_nop 1
	v_pk_mul_f32 v[74:75], v[74:75], v[220:221]
	v_pk_mul_f32 v[72:73], v[72:73], v[218:219]
	global_store_dwordx4 v[84:85], v[72:75], off offset:64
	s_nop 1
	v_pk_mul_f32 v[70:71], v[70:71], v[224:225]
	v_pk_mul_f32 v[68:69], v[68:69], v[222:223]
	global_store_dwordx4 v[84:85], v[68:71], off offset:512
	s_nop 1
	v_pk_mul_f32 v[66:67], v[66:67], v[228:229]
	v_pk_mul_f32 v[64:65], v[64:65], v[226:227]
	global_store_dwordx4 v[84:85], v[64:67], off offset:576
	s_nop 1
	v_lshl_add_u64 v[68:69], s[22:23], 0, v[140:141]
	v_lshl_add_u64 v[68:69], v[68:69], 0, v[154:155]
	v_pk_mul_f32 v[62:63], v[62:63], v[216:217]
	v_pk_mul_f32 v[60:61], v[60:61], v[214:215]
	global_store_dwordx4 v[68:69], v[60:63], off
	s_nop 1
	v_pk_mul_f32 v[58:59], v[58:59], v[220:221]
	v_pk_mul_f32 v[56:57], v[56:57], v[218:219]
	global_store_dwordx4 v[68:69], v[56:59], off offset:64
	s_nop 1
	v_pk_mul_f32 v[54:55], v[54:55], v[224:225]
	v_pk_mul_f32 v[52:53], v[52:53], v[222:223]
	global_store_dwordx4 v[68:69], v[52:55], off offset:512
	s_nop 1
	v_pk_mul_f32 v[46:47], v[46:47], v[228:229]
	v_pk_mul_f32 v[44:45], v[44:45], v[226:227]
	global_store_dwordx4 v[68:69], v[44:47], off offset:576
	s_nop 1
	v_lshl_add_u64 v[52:53], s[22:23], 0, v[142:143]
	v_lshl_add_u64 v[52:53], v[52:53], 0, v[154:155]
	v_pk_mul_f32 v[46:47], v[50:51], v[216:217]
	v_pk_mul_f32 v[44:45], v[48:49], v[214:215]
	global_store_dwordx4 v[52:53], v[44:47], off
	s_nop 1
	v_pk_mul_f32 v[42:43], v[42:43], v[220:221]
	v_pk_mul_f32 v[40:41], v[40:41], v[218:219]
	global_store_dwordx4 v[52:53], v[40:43], off offset:64
	s_nop 1
	v_pk_mul_f32 v[38:39], v[38:39], v[224:225]
	v_pk_mul_f32 v[36:37], v[36:37], v[222:223]
	global_store_dwordx4 v[52:53], v[36:39], off offset:512
	s_nop 1
	v_pk_mul_f32 v[30:31], v[30:31], v[228:229]
	v_pk_mul_f32 v[28:29], v[28:29], v[226:227]
	global_store_dwordx4 v[52:53], v[28:31], off offset:576
	s_nop 1
	v_lshl_add_u64 v[36:37], s[22:23], 0, v[146:147]
	v_lshl_add_u64 v[36:37], v[36:37], 0, v[154:155]
	v_pk_mul_f32 v[30:31], v[34:35], v[216:217]
	v_pk_mul_f32 v[28:29], v[32:33], v[214:215]
	global_store_dwordx4 v[36:37], v[28:31], off
	s_nop 1
	v_pk_mul_f32 v[26:27], v[26:27], v[220:221]
	v_pk_mul_f32 v[24:25], v[24:25], v[218:219]
	global_store_dwordx4 v[36:37], v[24:27], off offset:64
	s_nop 1
	v_pk_mul_f32 v[22:23], v[22:23], v[224:225]
	v_pk_mul_f32 v[20:21], v[20:21], v[222:223]
	global_store_dwordx4 v[36:37], v[20:23], off offset:512
	s_nop 1
	v_pk_mul_f32 v[14:15], v[14:15], v[228:229]
	v_pk_mul_f32 v[12:13], v[12:13], v[226:227]
	global_store_dwordx4 v[36:37], v[12:15], off offset:576
	s_nop 1
	v_lshl_add_u64 v[20:21], s[22:23], 0, v[148:149]
	v_lshl_add_u64 v[20:21], v[20:21], 0, v[154:155]
	s_mov_b64 s[22:23], s[18:19]
	v_pk_mul_f32 v[14:15], v[18:19], v[216:217]
	v_pk_mul_f32 v[12:13], v[16:17], v[214:215]
	global_store_dwordx4 v[20:21], v[12:15], off
	s_nop 1
	v_pk_mul_f32 v[10:11], v[10:11], v[220:221]
	v_pk_mul_f32 v[8:9], v[8:9], v[218:219]
	global_store_dwordx4 v[20:21], v[8:11], off offset:64
	s_nop 1
	v_pk_mul_f32 v[6:7], v[6:7], v[224:225]
	v_pk_mul_f32 v[4:5], v[4:5], v[222:223]
	global_store_dwordx4 v[20:21], v[4:7], off offset:512
	s_nop 1
	v_pk_mul_f32 v[2:3], v[2:3], v[228:229]
	v_pk_mul_f32 v[0:1], v[0:1], v[226:227]
	global_store_dwordx4 v[20:21], v[0:3], off offset:576
	s_nop 1
	s_cbranch_vccz .LBB0_2836
	s_waitcnt vmcnt(0)
	s_cmpk_gt_u32 s24, 0xff
	s_movk_i32 s48, 0x400
	s_movk_i32 s58, 0x6000
	s_movk_i32 s49, 0xc00
	s_movk_i32 s51, 0x4000
	s_cbranch_scc1 .LBB0_2843
	s_barrier

; #define PG8_STAGE(bufoff, gbase, voff) do { _Pragma("unroll") for (int _i = 0; _i < 2; ++_i) \
;     __builtin_amdgcn_global_load_lds((const unsigned*)((const char*)(gbase) + (voff)[_i]), (LAS unsigned*)(lds + (bufoff) + ldsw + _i * 8192), 16, 0, 0); } while (0)
; #define PG8_LDA(dst, b, h) do { _Pragma("unroll") for (int m = 0; m < 4; ++m) _Pragma("unroll") for (int k = 0; k < 2; ++k) dst[m][k] = *(const LAS bf16x8*)(lds + PG8_SA(b, h) + aoff + m * 2048 + k * 1024); } while (0)
; #define PG8_LDB(dst, b, h) do { _Pragma("unroll") for (int n = 0; n < 2; ++n) _Pragma("unroll") for (int k = 0; k < 2; ++k) dst[n][k] = *(const LAS bf16x8*)(lds + PG8_SB(b, h) + boff + n * 2048 + k * 1024); } while (0)
; #define PG8_MMA(ai, bj, At, Bt) do { __builtin_amdgcn_s_setprio(1); _Pragma("unroll") for (int m = 0; m < 4; ++m) _Pragma("unroll") for (int n = 0; n < 2; ++n) _Pragma("unroll") for (int k = 0; k < 2; ++k) \
;     acc[ai][bj][m][n] = __builtin_amdgcn_mfma_f32_16x16x32_bf16(Bt[n][k], At[m][k], acc[ai][bj][m][n], 0, 0, 0); __builtin_amdgcn_s_setprio(0); } while (0)
; #define PG8_WAIT_V(n) asm volatile("s_waitcnt vmcnt(" #n ")" ::: "memory")
; #define PG8_WAIT_L(n) asm volatile("s_waitcnt lgkmcnt(" #n ")" ::: "memory")
; #define PG8_BAR __builtin_amdgcn_s_barrier()
; #define PG8_SCHED __builtin_amdgcn_sched_barrier(0)
; template <class Epi, class Sched>
; __device__ __forceinline__ void gemm_phase(LAS unsigned char* lds, const Gemm g, const Sched& S, const Epi& E) {
;     ...
;     for (int t = 0; t < nt; t += 2) {
;       const bool last = (t == nt - 2);
;       const char* a1 = cA + (size_t)(t + 1) * kstep;
;       const char* a2 = last ? nA : cA + (size_t)(t + 2) * kstep; const char* b2 = last ? nB : cB + (size_t)(t + 2) * kstep;
;       const char* a3 = a2 + kstep; const char* b3 = b2 + kstep;
;       PG8_LDB(B0, 0, 0); PG8_SCHED; PG8_LDA(At, 0, 0); PG8_STAGE(PG8_SA(1, 1), a1 + hstepA, voffA);
;       PG8_WAIT_L(8); PG8_BAR; PG8_WAIT_L(0); PG8_MMA(0, 0, At, B0); PG8_BAR; PG8_SCHED;
;       PG8_LDB(B1, 0, 1); PG8_STAGE(PG8_SB(0, 0), b2, voffB);
;       PG8_BAR; PG8_WAIT_L(0); PG8_MMA(0, 1, At, B1); PG8_BAR;
;       PG8_LDA(At, 0, 1); PG8_STAGE(PG8_SA(0, 0), a2, voffA);
;       PG8_BAR; PG8_WAIT_L(0); PG8_MMA(1, 0, At, B0); PG8_BAR; PG8_SCHED;
;       PG8_STAGE(PG8_SB(0, 1), b2 + hstepB, voffB);
;       PG8_WAIT_V(6); PG8_BAR; PG8_MMA(1, 1, At, B1); PG8_BAR;
.LBB0_2859:
	s_add_u32 s10, s8, 0xfff00080
	s_addc_u32 s11, s9, -1
	s_add_i32 s78, 16, 0x10000
	v_add_u32_e32 v153, s78, v150
	ds_read_b128 v[136:139], v153
	ds_read_b128 v[140:143], v153 offset:1024
	ds_read_b128 v[146:149], v153 offset:2048
	ds_read_b128 v[154:157], v153 offset:3072
	s_cmp_eq_u32 s77, 60
	s_cselect_b32 s37, s23, s11
	s_cselect_b32 s36, s69, s10
	s_cselect_b32 s11, s21, s76
	s_cselect_b32 s10, s74, s75
	v_lshl_add_u64 v[214:215], s[8:9], 0, v[132:133]
	s_add_i32 m0, s45, 0xc000
	ds_read_b128 v[158:161], v152
	ds_read_b128 v[162:165], v152 offset:1024
	ds_read_b128 v[166:169], v152 offset:2048
	ds_read_b128 v[170:173], v152 offset:3072
	ds_read_b128 v[174:177], v152 offset:4096
	ds_read_b128 v[178:181], v152 offset:5120
	ds_read_b128 v[182:185], v152 offset:6144
	ds_read_b128 v[198:201], v152 offset:7168
	global_load_lds_dwordx4 v[214:215], off
	v_lshl_add_u64 v[214:215], s[8:9], 0, v[134:135]
	s_add_i32 m0, s45, 0xe000
	s_nop 0
	global_load_lds_dwordx4 v[214:215], off
	s_waitcnt lgkmcnt(8)
	s_barrier
	s_waitcnt lgkmcnt(0)
	s_waitcnt lgkmcnt(0)
	v_mfma_f32_16x16x32_bf16 v[124:127], v[136:139], v[158:161], v[124:127]
	v_mfma_f32_16x16x32_bf16 v[120:123], v[146:149], v[158:161], v[120:123]
	v_mfma_f32_16x16x32_bf16 v[108:111], v[136:139], v[166:169], v[108:111]
	v_mfma_f32_16x16x32_bf16 v[104:107], v[146:149], v[166:169], v[104:107]
	v_mfma_f32_16x16x32_bf16 v[92:95], v[136:139], v[174:177], v[92:95]
	v_mfma_f32_16x16x32_bf16 v[88:91], v[146:149], v[174:177], v[88:91]
	v_mfma_f32_16x16x32_bf16 v[76:79], v[136:139], v[182:185], v[76:79]
	v_mfma_f32_16x16x32_bf16 v[72:75], v[146:149], v[182:185], v[72:75]
	v_mfma_f32_16x16x32_bf16 v[124:127], v[140:143], v[162:165], v[124:127]
	v_mfma_f32_16x16x32_bf16 v[120:123], v[154:157], v[162:165], v[120:123]
	v_mfma_f32_16x16x32_bf16 v[108:111], v[140:143], v[170:173], v[108:111]
	v_mfma_f32_16x16x32_bf16 v[104:107], v[154:157], v[170:173], v[104:107]
	v_mfma_f32_16x16x32_bf16 v[92:95], v[140:143], v[178:181], v[92:95]
	v_mfma_f32_16x16x32_bf16 v[88:91], v[154:157], v[178:181], v[88:91]
	v_mfma_f32_16x16x32_bf16 v[76:79], v[140:143], v[198:201], v[76:79]
	v_mfma_f32_16x16x32_bf16 v[72:75], v[154:157], v[198:201], v[72:75]
	s_barrier
	s_add_i32 s82, 16, 0x14000
	s_add_i32 s78, s78, s38
	v_add_u32_e32 v153, s82, v150
	v_lshl_add_u64 v[230:231], s[10:11], 0, v[130:131]
	s_mov_b32 m0, s78
	ds_read_b128 v[214:217], v153
	ds_read_b128 v[218:221], v153 offset:1024
	ds_read_b128 v[222:225], v153 offset:2048
	ds_read_b128 v[226:229], v153 offset:3072
	global_load_lds_dwordx4 v[230:231], off
	v_lshl_add_u64 v[232:233], s[10:11], 0, v[128:129]
	s_add_i32 m0, s78, 0x2000
	s_nop 0
	global_load_lds_dwordx4 v[232:233], off
	s_barrier
	s_waitcnt lgkmcnt(0)
	s_waitcnt lgkmcnt(0)
	v_mfma_f32_16x16x32_bf16 v[116:119], v[214:217], v[158:161], v[116:119]
	v_mfma_f32_16x16x32_bf16 v[112:115], v[222:225], v[158:161], v[112:115]
	v_mfma_f32_16x16x32_bf16 v[100:103], v[214:217], v[166:169], v[100:103]
	v_mfma_f32_16x16x32_bf16 v[96:99], v[222:225], v[166:169], v[96:99]
	v_mfma_f32_16x16x32_bf16 v[84:87], v[214:217], v[174:177], v[84:87]
	v_mfma_f32_16x16x32_bf16 v[80:83], v[222:225], v[174:177], v[80:83]
	v_mfma_f32_16x16x32_bf16 v[68:71], v[214:217], v[182:185], v[68:71]
	v_mfma_f32_16x16x32_bf16 v[64:67], v[222:225], v[182:185], v[64:67]
	v_mfma_f32_16x16x32_bf16 v[116:119], v[218:221], v[162:165], v[116:119]
	v_mfma_f32_16x16x32_bf16 v[112:115], v[226:229], v[162:165], v[112:115]
	v_mfma_f32_16x16x32_bf16 v[100:103], v[218:221], v[170:173], v[100:103]
	v_mfma_f32_16x16x32_bf16 v[96:99], v[226:229], v[170:173], v[96:99]
	v_mfma_f32_16x16x32_bf16 v[84:87], v[218:221], v[178:181], v[84:87]
	v_mfma_f32_16x16x32_bf16 v[80:83], v[226:229], v[178:181], v[80:83]
	v_mfma_f32_16x16x32_bf16 v[68:71], v[218:221], v[198:201], v[68:71]
	v_mfma_f32_16x16x32_bf16 v[64:67], v[226:229], v[198:201], v[64:67]
	s_mov_b32 m0, s45
	v_lshl_add_u64 v[234:235], s[36:37], 0, v[130:131]
	s_barrier
	ds_read_b128 v[158:161], v152 offset:16384
	ds_read_b128 v[162:165], v152 offset:17408
	ds_read_b128 v[166:169], v152 offset:18432
	ds_read_b128 v[170:173], v152 offset:19456
	ds_read_b128 v[174:177], v152 offset:20480
	ds_read_b128 v[178:181], v152 offset:21504
	ds_read_b128 v[182:185], v152 offset:22528
	ds_read_b128 v[198:201], v152 offset:23552
	global_load_lds_dwordx4 v[234:235], off
	v_lshl_add_u64 v[236:237], s[36:37], 0, v[128:129]
	s_mov_b32 m0, s46
	s_nop 0
	global_load_lds_dwordx4 v[236:237], off
	s_barrier
	s_waitcnt lgkmcnt(0)
	s_waitcnt lgkmcnt(0)
	v_mfma_f32_16x16x32_bf16 v[60:63], v[136:139], v[158:161], v[60:63]
	v_mfma_f32_16x16x32_bf16 v[56:59], v[146:149], v[158:161], v[56:59]
	v_mfma_f32_16x16x32_bf16 v[44:47], v[136:139], v[166:169], v[44:47]
	v_mfma_f32_16x16x32_bf16 v[40:43], v[146:149], v[166:169], v[40:43]
	v_mfma_f32_16x16x32_bf16 v[28:31], v[136:139], v[174:177], v[28:31]
	v_mfma_f32_16x16x32_bf16 v[24:27], v[146:149], v[174:177], v[24:27]
	v_mfma_f32_16x16x32_bf16 v[12:15], v[136:139], v[182:185], v[12:15]
	v_mfma_f32_16x16x32_bf16 v[8:11], v[146:149], v[182:185], v[8:11]
	v_mfma_f32_16x16x32_bf16 v[60:63], v[140:143], v[162:165], v[60:63]
	v_mfma_f32_16x16x32_bf16 v[56:59], v[154:157], v[162:165], v[56:59]
	v_mfma_f32_16x16x32_bf16 v[44:47], v[140:143], v[170:173], v[44:47]
	v_mfma_f32_16x16x32_bf16 v[40:43], v[154:157], v[170:173], v[40:43]
	v_mfma_f32_16x16x32_bf16 v[28:31], v[140:143], v[178:181], v[28:31]
	v_mfma_f32_16x16x32_bf16 v[24:27], v[154:157], v[178:181], v[24:27]
	v_mfma_f32_16x16x32_bf16 v[12:15], v[140:143], v[198:201], v[12:15]
	v_mfma_f32_16x16x32_bf16 v[8:11], v[154:157], v[198:201], v[8:11]
	s_barrier
; #define PG8_STAGE(bufoff, gbase, voff) do { _Pragma("unroll") for (int _i = 0; _i < 2; ++_i) \
;     __builtin_amdgcn_global_load_lds((const unsigned*)((const char*)(gbase) + (voff)[_i]), (LAS unsigned*)(lds + (bufoff) + ldsw + _i * 8192), 16, 0, 0); } while (0)
; #define PG8_LDA(dst, b, h) do { _Pragma("unroll") for (int m = 0; m < 4; ++m) _Pragma("unroll") for (int k = 0; k < 2; ++k) dst[m][k] = *(const LAS bf16x8*)(lds + PG8_SA(b, h) + aoff + m * 2048 + k * 1024); } while (0)
; #define PG8_LDB(dst, b, h) do { _Pragma("unroll") for (int n = 0; n < 2; ++n) _Pragma("unroll") for (int k = 0; k < 2; ++k) dst[n][k] = *(const LAS bf16x8*)(lds + PG8_SB(b, h) + boff + n * 2048 + k * 1024); } while (0)
; #define PG8_MMA(ai, bj, At, Bt) do { __builtin_amdgcn_s_setprio(1); _Pragma("unroll") for (int m = 0; m < 4; ++m) _Pragma("unroll") for (int n = 0; n < 2; ++n) _Pragma("unroll") for (int k = 0; k < 2; ++k) \
;     acc[ai][bj][m][n] = __builtin_amdgcn_mfma_f32_16x16x32_bf16(Bt[n][k], At[m][k], acc[ai][bj][m][n], 0, 0, 0); __builtin_amdgcn_s_setprio(0); } while (0)
; #define PG8_WAIT_V(n) asm volatile("s_waitcnt vmcnt(" #n ")" ::: "memory")
; #define PG8_WAIT_L(n) asm volatile("s_waitcnt lgkmcnt(" #n ")" ::: "memory")
; #define PG8_BAR __builtin_amdgcn_s_barrier()
; #define PG8_SCHED __builtin_amdgcn_sched_barrier(0)
; template <class Epi, class Sched>
; __device__ __forceinline__ void gemm_phase(LAS unsigned char* lds, const Gemm g, const Sched& S, const Epi& E) {
;     ...
;       PG8_STAGE(PG8_SB(0, 1), b2 + hstepB, voffB);
;       PG8_WAIT_V(6); PG8_BAR; PG8_MMA(1, 1, At, B1); PG8_BAR;
;       PG8_LDB(B0, 1, 0); PG8_SCHED; PG8_LDA(At, 1, 0); PG8_STAGE(PG8_SA(0, 1), a2 + hstepA, voffA);
;       PG8_WAIT_L(8); PG8_BAR; PG8_WAIT_L(0); PG8_MMA(0, 0, At, B0); PG8_BAR; PG8_SCHED;
;       PG8_LDB(B1, 1, 1); PG8_STAGE(PG8_SB(1, 0), b3, voffB);
;       PG8_BAR; PG8_WAIT_L(0); PG8_MMA(0, 1, At, B1); PG8_BAR;
	s_add_u32 s78, s10, 0x100000
	s_addc_u32 s79, s11, 0
	s_add_i32 s82, s82, s38
	v_lshl_add_u64 v[136:137], s[78:79], 0, v[130:131]
	s_mov_b32 m0, s82
	s_nop 0
	global_load_lds_dwordx4 v[136:137], off
	v_lshl_add_u64 v[136:137], s[78:79], 0, v[128:129]
	s_add_i32 m0, s82, 0x2000
	s_nop 0
	global_load_lds_dwordx4 v[136:137], off
	s_waitcnt vmcnt(6)
	s_barrier
	v_mfma_f32_16x16x32_bf16 v[52:55], v[214:217], v[158:161], v[52:55]
	v_mfma_f32_16x16x32_bf16 v[48:51], v[222:225], v[158:161], v[48:51]
	v_mfma_f32_16x16x32_bf16 v[36:39], v[214:217], v[166:169], v[36:39]
	v_mfma_f32_16x16x32_bf16 v[32:35], v[222:225], v[166:169], v[32:35]
	v_mfma_f32_16x16x32_bf16 v[20:23], v[214:217], v[174:177], v[20:23]
	v_mfma_f32_16x16x32_bf16 v[16:19], v[222:225], v[174:177], v[16:19]
	v_mfma_f32_16x16x32_bf16 v[4:7], v[214:217], v[182:185], v[4:7]
	v_mfma_f32_16x16x32_bf16 v[0:3], v[222:225], v[182:185], v[0:3]
	v_mfma_f32_16x16x32_bf16 v[52:55], v[218:221], v[162:165], v[52:55]
	v_mfma_f32_16x16x32_bf16 v[48:51], v[226:229], v[162:165], v[48:51]
	v_mfma_f32_16x16x32_bf16 v[36:39], v[218:221], v[170:173], v[36:39]
	v_mfma_f32_16x16x32_bf16 v[32:35], v[226:229], v[170:173], v[32:35]
	v_mfma_f32_16x16x32_bf16 v[20:23], v[218:221], v[178:181], v[20:23]
	v_mfma_f32_16x16x32_bf16 v[16:19], v[226:229], v[178:181], v[16:19]
	v_mfma_f32_16x16x32_bf16 v[4:7], v[218:221], v[198:201], v[4:7]
	v_mfma_f32_16x16x32_bf16 v[0:3], v[226:229], v[198:201], v[0:3]
	s_add_i32 s78, 16, 0x18000
	v_add_u32_e32 v153, s78, v150
	s_barrier
	ds_read_b128 v[136:139], v153
	ds_read_b128 v[140:143], v153 offset:1024
	ds_read_b128 v[146:149], v153 offset:2048
	ds_read_b128 v[154:157], v153 offset:3072
	s_add_u32 s36, s36, 0x100000
	s_addc_u32 s37, s37, 0
	s_mov_b32 m0, s47
	v_lshl_add_u64 v[214:215], s[36:37], 0, v[130:131]
	ds_read_b128 v[158:161], v152 offset:32768
	ds_read_b128 v[162:165], v152 offset:33792
	ds_read_b128 v[166:169], v152 offset:34816
	ds_read_b128 v[170:173], v152 offset:35840
	ds_read_b128 v[174:177], v152 offset:36864
	ds_read_b128 v[178:181], v152 offset:37888
	ds_read_b128 v[182:185], v152 offset:38912
	ds_read_b128 v[198:201], v152 offset:39936
	global_load_lds_dwordx4 v[214:215], off
	v_lshl_add_u64 v[214:215], s[36:37], 0, v[128:129]
	s_mov_b32 m0, s48
	s_nop 0
	global_load_lds_dwordx4 v[214:215], off
	s_waitcnt lgkmcnt(8)
	s_barrier
	s_waitcnt lgkmcnt(0)
	s_waitcnt lgkmcnt(0)
	v_mfma_f32_16x16x32_bf16 v[124:127], v[136:139], v[158:161], v[124:127]
	v_mfma_f32_16x16x32_bf16 v[120:123], v[146:149], v[158:161], v[120:123]
	v_mfma_f32_16x16x32_bf16 v[108:111], v[136:139], v[166:169], v[108:111]
	v_mfma_f32_16x16x32_bf16 v[104:107], v[146:149], v[166:169], v[104:107]
	v_mfma_f32_16x16x32_bf16 v[92:95], v[136:139], v[174:177], v[92:95]
	v_mfma_f32_16x16x32_bf16 v[88:91], v[146:149], v[174:177], v[88:91]
	v_mfma_f32_16x16x32_bf16 v[76:79], v[136:139], v[182:185], v[76:79]
	v_mfma_f32_16x16x32_bf16 v[72:75], v[146:149], v[182:185], v[72:75]
	v_mfma_f32_16x16x32_bf16 v[124:127], v[140:143], v[162:165], v[124:127]
	v_mfma_f32_16x16x32_bf16 v[120:123], v[154:157], v[162:165], v[120:123]
	v_mfma_f32_16x16x32_bf16 v[108:111], v[140:143], v[170:173], v[108:111]
	v_mfma_f32_16x16x32_bf16 v[104:107], v[154:157], v[170:173], v[104:107]
	v_mfma_f32_16x16x32_bf16 v[92:95], v[140:143], v[178:181], v[92:95]
	v_mfma_f32_16x16x32_bf16 v[88:91], v[154:157], v[178:181], v[88:91]
	v_mfma_f32_16x16x32_bf16 v[76:79], v[140:143], v[198:201], v[76:79]
	v_mfma_f32_16x16x32_bf16 v[72:75], v[154:157], v[198:201], v[72:75]
	s_barrier
	s_add_i32 s36, 16, 0x1c000
	s_add_i32 s37, s78, s38
	v_add_u32_e32 v153, s36, v150
	v_lshl_add_u64 v[230:231], v[230:231], 0, s[62:63]
	s_mov_b32 m0, s37
	ds_read_b128 v[214:217], v153
	ds_read_b128 v[218:221], v153 offset:1024
	ds_read_b128 v[222:225], v153 offset:2048
	ds_read_b128 v[226:229], v153 offset:3072
	global_load_lds_dwordx4 v[230:231], off
	v_lshl_add_u64 v[230:231], v[232:233], 0, s[62:63]
	s_add_i32 m0, s37, 0x2000
	s_nop 0
	global_load_lds_dwordx4 v[230:231], off
	s_barrier
	s_waitcnt lgkmcnt(0)
	s_waitcnt lgkmcnt(0)
	v_mfma_f32_16x16x32_bf16 v[116:119], v[214:217], v[158:161], v[116:119]
	v_mfma_f32_16x16x32_bf16 v[112:115], v[222:225], v[158:161], v[112:115]
	v_mfma_f32_16x16x32_bf16 v[100:103], v[214:217], v[166:169], v[100:103]
	v_mfma_f32_16x16x32_bf16 v[96:99], v[222:225], v[166:169], v[96:99]
	v_mfma_f32_16x16x32_bf16 v[84:87], v[214:217], v[174:177], v[84:87]
	v_mfma_f32_16x16x32_bf16 v[80:83], v[222:225], v[174:177], v[80:83]
	v_mfma_f32_16x16x32_bf16 v[68:71], v[214:217], v[182:185], v[68:71]
	v_mfma_f32_16x16x32_bf16 v[64:67], v[222:225], v[182:185], v[64:67]
	v_mfma_f32_16x16x32_bf16 v[116:119], v[218:221], v[162:165], v[116:119]
	v_mfma_f32_16x16x32_bf16 v[112:115], v[226:229], v[162:165], v[112:115]
	v_mfma_f32_16x16x32_bf16 v[100:103], v[218:221], v[170:173], v[100:103]
	v_mfma_f32_16x16x32_bf16 v[96:99], v[226:229], v[170:173], v[96:99]
	v_mfma_f32_16x16x32_bf16 v[84:87], v[218:221], v[178:181], v[84:87]
	v_mfma_f32_16x16x32_bf16 v[80:83], v[226:229], v[178:181], v[80:83]
	v_mfma_f32_16x16x32_bf16 v[68:71], v[218:221], v[198:201], v[68:71]
	v_mfma_f32_16x16x32_bf16 v[64:67], v[226:229], v[198:201], v[64:67]
	s_mov_b32 m0, s66
	v_lshl_add_u64 v[230:231], v[234:235], 0, s[62:63]
	s_barrier
; #define PG8_STAGE(bufoff, gbase, voff) do { _Pragma("unroll") for (int _i = 0; _i < 2; ++_i) \
;     __builtin_amdgcn_global_load_lds((const unsigned*)((const char*)(gbase) + (voff)[_i]), (LAS unsigned*)(lds + (bufoff) + ldsw + _i * 8192), 16, 0, 0); } while (0)
; #define PG8_LDA(dst, b, h) do { _Pragma("unroll") for (int m = 0; m < 4; ++m) _Pragma("unroll") for (int k = 0; k < 2; ++k) dst[m][k] = *(const LAS bf16x8*)(lds + PG8_SA(b, h) + aoff + m * 2048 + k * 1024); } while (0)
; #define PG8_MMA(ai, bj, At, Bt) do { __builtin_amdgcn_s_setprio(1); _Pragma("unroll") for (int m = 0; m < 4; ++m) _Pragma("unroll") for (int n = 0; n < 2; ++n) _Pragma("unroll") for (int k = 0; k < 2; ++k) \
;     acc[ai][bj][m][n] = __builtin_amdgcn_mfma_f32_16x16x32_bf16(Bt[n][k], At[m][k], acc[ai][bj][m][n], 0, 0, 0); __builtin_amdgcn_s_setprio(0); } while (0)
; #define PG8_WAIT_V(n) asm volatile("s_waitcnt vmcnt(" #n ")" ::: "memory")
; #define PG8_WAIT_L(n) asm volatile("s_waitcnt lgkmcnt(" #n ")" ::: "memory")
; #define PG8_BAR __builtin_amdgcn_s_barrier()
; #define PG8_SCHED __builtin_amdgcn_sched_barrier(0)
; template <class Epi, class Sched>
; __device__ __forceinline__ void gemm_phase(LAS unsigned char* lds, const Gemm g, const Sched& S, const Epi& E) {
;     ...
;       PG8_LDA(At, 1, 1); PG8_STAGE(PG8_SA(1, 0), a3, voffA);
;       PG8_BAR; PG8_WAIT_L(0); PG8_MMA(1, 0, At, B0); PG8_BAR; PG8_SCHED;
;       PG8_STAGE(PG8_SB(1, 1), b3 + hstepB, voffB);
;       PG8_WAIT_V(6); PG8_BAR; PG8_MMA(1, 1, At, B1); PG8_BAR;
;     }
;     E(acc, cur, wr, wc, fr, fq);
	ds_read_b128 v[158:161], v152 offset:49152
	ds_read_b128 v[162:165], v152 offset:50176
	ds_read_b128 v[166:169], v152 offset:51200
	ds_read_b128 v[170:173], v152 offset:52224
	ds_read_b128 v[174:177], v152 offset:53248
	ds_read_b128 v[178:181], v152 offset:54272
	ds_read_b128 v[182:185], v152 offset:55296
	ds_read_b128 v[198:201], v152 offset:56320
	global_load_lds_dwordx4 v[230:231], off
	v_lshl_add_u64 v[230:231], v[236:237], 0, s[62:63]
	s_mov_b32 m0, s67
	s_nop 0
	global_load_lds_dwordx4 v[230:231], off
	s_barrier
	s_waitcnt lgkmcnt(0)
	s_waitcnt lgkmcnt(0)
	v_mfma_f32_16x16x32_bf16 v[60:63], v[136:139], v[158:161], v[60:63]
	v_mfma_f32_16x16x32_bf16 v[56:59], v[146:149], v[158:161], v[56:59]
	v_mfma_f32_16x16x32_bf16 v[44:47], v[136:139], v[166:169], v[44:47]
	v_mfma_f32_16x16x32_bf16 v[40:43], v[146:149], v[166:169], v[40:43]
	v_mfma_f32_16x16x32_bf16 v[28:31], v[136:139], v[174:177], v[28:31]
	v_mfma_f32_16x16x32_bf16 v[24:27], v[146:149], v[174:177], v[24:27]
	v_mfma_f32_16x16x32_bf16 v[12:15], v[136:139], v[182:185], v[12:15]
	v_mfma_f32_16x16x32_bf16 v[8:11], v[146:149], v[182:185], v[8:11]
	v_mfma_f32_16x16x32_bf16 v[60:63], v[140:143], v[162:165], v[60:63]
	v_mfma_f32_16x16x32_bf16 v[56:59], v[154:157], v[162:165], v[56:59]
	v_mfma_f32_16x16x32_bf16 v[44:47], v[140:143], v[170:173], v[44:47]
	v_mfma_f32_16x16x32_bf16 v[40:43], v[154:157], v[170:173], v[40:43]
	v_mfma_f32_16x16x32_bf16 v[28:31], v[140:143], v[178:181], v[28:31]
	v_mfma_f32_16x16x32_bf16 v[24:27], v[154:157], v[178:181], v[24:27]
	v_mfma_f32_16x16x32_bf16 v[12:15], v[140:143], v[198:201], v[12:15]
	v_mfma_f32_16x16x32_bf16 v[8:11], v[154:157], v[198:201], v[8:11]
	s_barrier
	s_add_u32 s10, s10, 0x100080
	s_addc_u32 s11, s11, 0
	s_add_i32 s36, s36, s38
	v_lshl_add_u64 v[136:137], s[10:11], 0, v[130:131]
	s_mov_b32 m0, s36
	s_nop 0
	global_load_lds_dwordx4 v[136:137], off
	v_lshl_add_u64 v[136:137], s[10:11], 0, v[128:129]
	s_add_i32 m0, s36, 0x2000
	s_nop 0
	global_load_lds_dwordx4 v[136:137], off
	s_waitcnt vmcnt(6)
	s_barrier
	v_mfma_f32_16x16x32_bf16 v[52:55], v[214:217], v[158:161], v[52:55]
	v_mfma_f32_16x16x32_bf16 v[48:51], v[222:225], v[158:161], v[48:51]
	v_mfma_f32_16x16x32_bf16 v[36:39], v[214:217], v[166:169], v[36:39]
	v_mfma_f32_16x16x32_bf16 v[32:35], v[222:225], v[166:169], v[32:35]
	v_mfma_f32_16x16x32_bf16 v[20:23], v[214:217], v[174:177], v[20:23]
	v_mfma_f32_16x16x32_bf16 v[16:19], v[222:225], v[174:177], v[16:19]
	v_mfma_f32_16x16x32_bf16 v[4:7], v[214:217], v[182:185], v[4:7]
	v_mfma_f32_16x16x32_bf16 v[0:3], v[222:225], v[182:185], v[0:3]
	v_mfma_f32_16x16x32_bf16 v[52:55], v[218:221], v[162:165], v[52:55]
	v_mfma_f32_16x16x32_bf16 v[48:51], v[226:229], v[162:165], v[48:51]
	v_mfma_f32_16x16x32_bf16 v[36:39], v[218:221], v[170:173], v[36:39]
	v_mfma_f32_16x16x32_bf16 v[32:35], v[226:229], v[170:173], v[32:35]
	v_mfma_f32_16x16x32_bf16 v[20:23], v[218:221], v[178:181], v[20:23]
	v_mfma_f32_16x16x32_bf16 v[16:19], v[226:229], v[178:181], v[16:19]
	v_mfma_f32_16x16x32_bf16 v[4:7], v[218:221], v[198:201], v[4:7]
	v_mfma_f32_16x16x32_bf16 v[0:3], v[226:229], v[198:201], v[0:3]
	s_add_i32 s77, s77, 2
	s_add_u32 s8, s8, 0x100
	s_addc_u32 s9, s9, 0
	s_add_u32 s75, s75, 0x100
	s_addc_u32 s76, s76, 0
	s_cmp_gt_u32 s77, 61
	s_barrier
	s_cbranch_scc0 .LBB0_2859
	v_lshl_add_u32 v138, s25, 8, v145
	v_mov_b32_e32 v137, s51
	v_mov_b32_e32 v140, s59
	v_cmp_gt_i32_e32 vcc, s73, v138
	v_lshl_or_b32 v136, s24, 8, v151
	v_ashrrev_i32_e32 v139, 31, v138
	v_cndmask_b32_e32 v147, v137, v140, vcc
	v_mov_b32_e32 v137, s49
	v_mov_b32_e32 v140, s58
	v_lshlrev_b64 v[142:143], 12, v[138:139]
	v_cndmask_b32_e32 v146, v137, v140, vcc
	v_ashrrev_i32_e32 v137, 31, v136
	v_lshlrev_b64 v[140:141], 2, v[136:137]
	v_lshl_add_u64 v[142:143], s[14:15], 0, v[142:143]
	v_lshl_add_u64 v[148:149], v[146:147], 0, v[140:141]
	v_lshl_add_u64 v[142:143], v[142:143], 0, v[140:141]
	global_load_dwordx4 v[214:217], v[148:149], off
	global_load_dwordx4 v[218:221], v[148:149], off offset:64
	global_load_dwordx4 v[222:225], v[148:149], off offset:512
	global_load_dwordx4 v[226:229], v[148:149], off offset:576
	global_load_dwordx4 v[230:233], v[142:143], off
	global_load_dwordx4 v[234:237], v[142:143], off offset:64
	global_load_dwordx4 v[238:241], v[142:143], off offset:512
	global_load_dwordx4 v[242:245], v[142:143], off offset:576
	v_mov_b32_e32 v147, v144
	v_cndmask_b32_e64 v153, 0, 1, s[18:19]
	v_add_u32_e32 v146, 0xffffff00, v138
	v_cmp_lt_i32_e64 s[10:11], s81, v138
	v_cmp_ne_u32_e64 s[8:9], 1, v153
	v_lshlrev_b64 v[146:147], 12, v[146:147]
	s_andn2_b64 vcc, exec, s[18:19]
	s_waitcnt vmcnt(3)
	v_pk_fma_f32 v[126:127], v[126:127], v[216:217], v[232:233]
	v_pk_fma_f32 v[124:125], v[124:125], v[214:215], v[230:231]
	s_cbranch_vccnz .LBB0_3019
	s_and_saveexec_b64 s[24:25], s[10:11]
	s_mov_b32 s74, 0x8000
	s_mov_b32 s75, 0x10000
	s_cbranch_execz .LBB0_2863
	v_lshl_add_u64 v[154:155], s[16:17], 0, v[146:147]
	v_lshl_add_u64 v[154:155], v[136:137], 2, v[154:155]
	global_store_dwordx4 v[154:155], v[124:127], off
